# removes the dead s_setprio 0/1 pair between the two MFMA blocks of every GEMM sub-phase (on top of the FFN-in tap staging change)
# speedup vs baseline: 1.0031x; 1.0031x over previous
; #define PG8_STAGE(bufoff, gbase, voff) do { _Pragma("unroll") for (int _i = 0; _i < 2; ++_i) \
;         __builtin_amdgcn_global_load_lds((const unsigned*)((const char*)(gbase) + (voff)[_i]), (LAS unsigned*)(lds + (bufoff) + ldsw + _i * 8192), 16, 0, 0); } while (0)
; #define PG8_LDA(dst, b, h) do { _Pragma("unroll") for (int m = 0; m < 4; ++m) _Pragma("unroll") for (int k = 0; k < 2; ++k) dst[m][k] = *(const LAS bf16x8*)(lds + PG8_SA(b, h) + aoff + m * 2048 + k * 1024); } while (0)
; #define PG8_LDB(dst, b, h) do { _Pragma("unroll") for (int n = 0; n < 2; ++n) _Pragma("unroll") for (int k = 0; k < 2; ++k) dst[n][k] = *(const LAS bf16x8*)(lds + PG8_SB(b, h) + boff + n * 2048 + k * 1024); } while (0)
; #define PG8_MMA(ai, bj, At, Bt_) do { __builtin_amdgcn_s_setprio(1); _Pragma("unroll") for (int m = 0; m < 4; ++m) _Pragma("unroll") for (int n = 0; n < 2; ++n) _Pragma("unroll") for (int k = 0; k < 2; ++k) \
;         acc[ai][bj][m][n] = __builtin_amdgcn_mfma_f32_16x16x32_bf16(Bt_[n][k], At[m][k], acc[ai][bj][m][n], 0, 0, 0); __builtin_amdgcn_s_setprio(0); } while (0)
; #define PG8_WAIT_V(n) asm volatile("s_waitcnt vmcnt(" #n ")" ::: "memory")
; #define PG8_WAIT_L(n) asm volatile("s_waitcnt lgkmcnt(" #n ")" ::: "memory")
; #define PG8_BAR __builtin_amdgcn_s_barrier()
; #define PG8_SCHED __builtin_amdgcn_sched_barrier(0)
; __device__ __forceinline__ void gemm_phase(LAS unsigned char* lds, const bf16_t* A, const bf16_t* Bt, int M, int N, int K, const Epi& E) {
;     ...
;             PG8_LDB(B0, 0, 0); PG8_LDB(B1, 0, 1); PG8_SCHED; PG8_LDA(At, 0, 0); PG8_STAGE(PG8_SA(1, 1), a1 + hstep, voffA);
;             PG8_WAIT_V(8); PG8_WAIT_L(0); PG8_BAR; PG8_MMA(0, 0, At, B0); PG8_MMA(0, 1, At, B1); PG8_BAR; PG8_SCHED;
;             PG8_LDA(At, 0, 1); PG8_STAGE(PG8_SB(0, 0), b2, voffB); PG8_STAGE(PG8_SB(0, 1), b2 + hstep, voffB); PG8_STAGE(PG8_SA(0, 0), a2, voffA);
;             PG8_WAIT_V(8); PG8_WAIT_L(0); PG8_BAR; PG8_MMA(1, 0, At, B0); PG8_MMA(1, 1, At, B1); PG8_BAR; PG8_SCHED;
.LBB0_182:
	s_add_u32 s20, s18, 0xfffc0080
	s_addc_u32 s21, s19, -1
	s_add_i32 s42, 0, 0x10000
	s_cmp_eq_u32 s41, 12
	s_cselect_b32 s23, s11, s21
	s_cselect_b32 s22, s13, s20
	v_add_u32_e32 v142, s42, v145
	s_cselect_b32 s21, s9, s40
	s_cselect_b32 s20, s38, s39
	s_add_i32 s44, 0, 0x14000
	ds_read_b128 v[148:151], v142
	ds_read_b128 v[152:155], v142 offset:1024
	ds_read_b128 v[156:159], v142 offset:2048
	ds_read_b128 v[160:163], v142 offset:3072
	v_add_u32_e32 v142, s44, v145
	ds_read_b128 v[164:167], v142
	ds_read_b128 v[168:171], v142 offset:1024
	ds_read_b128 v[172:175], v142 offset:2048
	ds_read_b128 v[176:179], v142 offset:3072
	v_lshl_add_u64 v[142:143], s[18:19], 0, v[138:139]
	s_add_i32 m0, s27, 0xc000
	ds_read_b128 v[180:183], v147
	ds_read_b128 v[202:205], v147 offset:1024
	ds_read_b128 v[206:209], v147 offset:2048
	ds_read_b128 v[210:213], v147 offset:3072
	ds_read_b128 v[214:217], v147 offset:4096
	ds_read_b128 v[218:221], v147 offset:5120
	ds_read_b128 v[222:225], v147 offset:6144
	ds_read_b128 v[226:229], v147 offset:7168
	global_load_lds_dwordx4 v[142:143], off
	v_lshl_add_u64 v[142:143], s[18:19], 0, v[140:141]
	s_add_i32 m0, s27, 0xe000
	s_nop 0
	global_load_lds_dwordx4 v[142:143], off
	s_waitcnt vmcnt(8)
	s_waitcnt lgkmcnt(0)
	s_barrier
	s_setprio 1
	s_waitcnt lgkmcnt(0)
	v_mfma_f32_16x16x32_bf16 v[126:129], v[148:151], v[180:183], v[126:129]
	v_mfma_f32_16x16x32_bf16 v[122:125], v[156:159], v[180:183], v[122:125]
	v_mfma_f32_16x16x32_bf16 v[118:121], v[148:151], v[206:209], v[118:121]
	v_mfma_f32_16x16x32_bf16 v[114:117], v[156:159], v[206:209], v[114:117]
	v_mfma_f32_16x16x32_bf16 v[102:105], v[148:151], v[214:217], v[102:105]
	v_mfma_f32_16x16x32_bf16 v[98:101], v[156:159], v[214:217], v[98:101]
	v_mfma_f32_16x16x32_bf16 v[86:89], v[148:151], v[222:225], v[86:89]
	v_mfma_f32_16x16x32_bf16 v[82:85], v[156:159], v[222:225], v[82:85]
	v_mfma_f32_16x16x32_bf16 v[126:129], v[152:155], v[202:205], v[126:129]
	v_mfma_f32_16x16x32_bf16 v[122:125], v[160:163], v[202:205], v[122:125]
	v_mfma_f32_16x16x32_bf16 v[118:121], v[152:155], v[210:213], v[118:121]
	v_mfma_f32_16x16x32_bf16 v[114:117], v[160:163], v[210:213], v[114:117]
	v_mfma_f32_16x16x32_bf16 v[102:105], v[152:155], v[218:221], v[102:105]
	v_mfma_f32_16x16x32_bf16 v[98:101], v[160:163], v[218:221], v[98:101]
	v_mfma_f32_16x16x32_bf16 v[86:89], v[152:155], v[226:229], v[86:89]
	v_mfma_f32_16x16x32_bf16 v[82:85], v[160:163], v[226:229], v[82:85]
	v_mfma_f32_16x16x32_bf16 v[110:113], v[164:167], v[180:183], v[110:113]
	v_mfma_f32_16x16x32_bf16 v[106:109], v[172:175], v[180:183], v[106:109]
	v_mfma_f32_16x16x32_bf16 v[94:97], v[164:167], v[206:209], v[94:97]
	v_mfma_f32_16x16x32_bf16 v[90:93], v[172:175], v[206:209], v[90:93]
	v_mfma_f32_16x16x32_bf16 v[78:81], v[164:167], v[214:217], v[78:81]
	v_mfma_f32_16x16x32_bf16 v[74:77], v[172:175], v[214:217], v[74:77]
	v_mfma_f32_16x16x32_bf16 v[70:73], v[164:167], v[222:225], v[70:73]
	v_mfma_f32_16x16x32_bf16 v[66:69], v[172:175], v[222:225], v[66:69]
	v_mfma_f32_16x16x32_bf16 v[110:113], v[168:171], v[202:205], v[110:113]
	v_mfma_f32_16x16x32_bf16 v[106:109], v[176:179], v[202:205], v[106:109]
	v_mfma_f32_16x16x32_bf16 v[94:97], v[168:171], v[210:213], v[94:97]
	v_mfma_f32_16x16x32_bf16 v[90:93], v[176:179], v[210:213], v[90:93]
	v_mfma_f32_16x16x32_bf16 v[78:81], v[168:171], v[218:221], v[78:81]
	v_mfma_f32_16x16x32_bf16 v[74:77], v[176:179], v[218:221], v[74:77]
	v_mfma_f32_16x16x32_bf16 v[70:73], v[168:171], v[226:229], v[70:73]
	v_mfma_f32_16x16x32_bf16 v[66:69], v[176:179], v[226:229], v[66:69]
	s_setprio 0
	s_barrier
	s_add_i32 s42, s42, s26
	v_lshl_add_u64 v[142:143], s[20:21], 0, v[0:1]
	s_mov_b32 m0, s42
	ds_read_b128 v[180:183], v147 offset:16384
	ds_read_b128 v[202:205], v147 offset:17408
	ds_read_b128 v[206:209], v147 offset:18432
	ds_read_b128 v[210:213], v147 offset:19456
	ds_read_b128 v[214:217], v147 offset:20480
	ds_read_b128 v[218:221], v147 offset:21504
	ds_read_b128 v[222:225], v147 offset:22528
	ds_read_b128 v[226:229], v147 offset:23552
	global_load_lds_dwordx4 v[142:143], off
	s_add_i32 m0, s42, 0x2000
	s_add_u32 s42, s20, 0x40000
	v_lshl_add_u64 v[184:185], s[20:21], 0, v[134:135]
	s_addc_u32 s43, s21, 0
	s_add_i32 s44, s44, s26
	global_load_lds_dwordx4 v[184:185], off
	v_lshl_add_u64 v[230:231], s[42:43], 0, v[0:1]
	s_mov_b32 m0, s44
	v_lshl_add_u64 v[232:233], s[22:23], 0, v[132:133]
	global_load_lds_dwordx4 v[230:231], off
	v_lshl_add_u64 v[230:231], s[42:43], 0, v[134:135]
	s_add_i32 m0, s44, 0x2000
	s_nop 0
	global_load_lds_dwordx4 v[230:231], off
	v_lshl_add_u64 v[230:231], s[22:23], 0, v[130:131]
	s_mov_b32 m0, s27
	s_nop 0
	global_load_lds_dwordx4 v[230:231], off
	s_mov_b32 m0, s28
	s_nop 0
	global_load_lds_dwordx4 v[232:233], off
	s_waitcnt vmcnt(8)
	s_waitcnt lgkmcnt(0)
	s_barrier
; #define PG8_STAGE(bufoff, gbase, voff) do { _Pragma("unroll") for (int _i = 0; _i < 2; ++_i) \
;         __builtin_amdgcn_global_load_lds((const unsigned*)((const char*)(gbase) + (voff)[_i]), (LAS unsigned*)(lds + (bufoff) + ldsw + _i * 8192), 16, 0, 0); } while (0)
; #define PG8_LDA(dst, b, h) do { _Pragma("unroll") for (int m = 0; m < 4; ++m) _Pragma("unroll") for (int k = 0; k < 2; ++k) dst[m][k] = *(const LAS bf16x8*)(lds + PG8_SA(b, h) + aoff + m * 2048 + k * 1024); } while (0)
; #define PG8_LDB(dst, b, h) do { _Pragma("unroll") for (int n = 0; n < 2; ++n) _Pragma("unroll") for (int k = 0; k < 2; ++k) dst[n][k] = *(const LAS bf16x8*)(lds + PG8_SB(b, h) + boff + n * 2048 + k * 1024); } while (0)
; #define PG8_MMA(ai, bj, At, Bt_) do { __builtin_amdgcn_s_setprio(1); _Pragma("unroll") for (int m = 0; m < 4; ++m) _Pragma("unroll") for (int n = 0; n < 2; ++n) _Pragma("unroll") for (int k = 0; k < 2; ++k) \
;         acc[ai][bj][m][n] = __builtin_amdgcn_mfma_f32_16x16x32_bf16(Bt_[n][k], At[m][k], acc[ai][bj][m][n], 0, 0, 0); __builtin_amdgcn_s_setprio(0); } while (0)
; #define PG8_WAIT_V(n) asm volatile("s_waitcnt vmcnt(" #n ")" ::: "memory")
; #define PG8_WAIT_L(n) asm volatile("s_waitcnt lgkmcnt(" #n ")" ::: "memory")
; #define PG8_BAR __builtin_amdgcn_s_barrier()
; #define PG8_SCHED __builtin_amdgcn_sched_barrier(0)
; __device__ __forceinline__ void gemm_phase(LAS unsigned char* lds, const bf16_t* A, const bf16_t* Bt, int M, int N, int K, const Epi& E) {
;     ...
;             PG8_WAIT_V(8); PG8_WAIT_L(0); PG8_BAR; PG8_MMA(1, 0, At, B0); PG8_MMA(1, 1, At, B1); PG8_BAR; PG8_SCHED;
;             PG8_LDB(B0, 1, 0); PG8_LDB(B1, 1, 1); PG8_SCHED; PG8_LDA(At, 1, 0); PG8_STAGE(PG8_SA(0, 1), a2 + hstep, voffA);
;             PG8_WAIT_V(8); PG8_WAIT_L(0); PG8_BAR; PG8_MMA(0, 0, At, B0); PG8_MMA(0, 1, At, B1); PG8_BAR; PG8_SCHED;
	s_setprio 1
	s_waitcnt lgkmcnt(0)
	v_mfma_f32_16x16x32_bf16 v[62:65], v[148:151], v[180:183], v[62:65]
	v_mfma_f32_16x16x32_bf16 v[58:61], v[156:159], v[180:183], v[58:61]
	v_mfma_f32_16x16x32_bf16 v[54:57], v[148:151], v[206:209], v[54:57]
	v_mfma_f32_16x16x32_bf16 v[50:53], v[156:159], v[206:209], v[50:53]
	v_mfma_f32_16x16x32_bf16 v[38:41], v[148:151], v[214:217], v[38:41]
	v_mfma_f32_16x16x32_bf16 v[34:37], v[156:159], v[214:217], v[34:37]
	v_mfma_f32_16x16x32_bf16 v[22:25], v[148:151], v[222:225], v[22:25]
	v_mfma_f32_16x16x32_bf16 v[18:21], v[156:159], v[222:225], v[18:21]
	v_mfma_f32_16x16x32_bf16 v[62:65], v[152:155], v[202:205], v[62:65]
	v_mfma_f32_16x16x32_bf16 v[58:61], v[160:163], v[202:205], v[58:61]
	v_mfma_f32_16x16x32_bf16 v[54:57], v[152:155], v[210:213], v[54:57]
	v_mfma_f32_16x16x32_bf16 v[50:53], v[160:163], v[210:213], v[50:53]
	v_mfma_f32_16x16x32_bf16 v[38:41], v[152:155], v[218:221], v[38:41]
	v_mfma_f32_16x16x32_bf16 v[34:37], v[160:163], v[218:221], v[34:37]
	v_mfma_f32_16x16x32_bf16 v[22:25], v[152:155], v[226:229], v[22:25]
	v_mfma_f32_16x16x32_bf16 v[18:21], v[160:163], v[226:229], v[18:21]
	v_mfma_f32_16x16x32_bf16 v[46:49], v[164:167], v[180:183], v[46:49]
	v_mfma_f32_16x16x32_bf16 v[42:45], v[172:175], v[180:183], v[42:45]
	v_mfma_f32_16x16x32_bf16 v[30:33], v[164:167], v[206:209], v[30:33]
	v_mfma_f32_16x16x32_bf16 v[26:29], v[172:175], v[206:209], v[26:29]
	v_mfma_f32_16x16x32_bf16 v[14:17], v[164:167], v[214:217], v[14:17]
	v_mfma_f32_16x16x32_bf16 v[10:13], v[172:175], v[214:217], v[10:13]
	v_mfma_f32_16x16x32_bf16 v[6:9], v[164:167], v[222:225], v[6:9]
	v_mfma_f32_16x16x32_bf16 v[2:5], v[172:175], v[222:225], v[2:5]
	v_mfma_f32_16x16x32_bf16 v[46:49], v[168:171], v[202:205], v[46:49]
	v_mfma_f32_16x16x32_bf16 v[42:45], v[176:179], v[202:205], v[42:45]
	v_mfma_f32_16x16x32_bf16 v[30:33], v[168:171], v[210:213], v[30:33]
	v_mfma_f32_16x16x32_bf16 v[26:29], v[176:179], v[210:213], v[26:29]
	v_mfma_f32_16x16x32_bf16 v[14:17], v[168:171], v[218:221], v[14:17]
	v_mfma_f32_16x16x32_bf16 v[10:13], v[176:179], v[218:221], v[10:13]
	v_mfma_f32_16x16x32_bf16 v[6:9], v[168:171], v[226:229], v[6:9]
	v_mfma_f32_16x16x32_bf16 v[2:5], v[176:179], v[226:229], v[2:5]
	s_setprio 0
	s_barrier
	s_add_i32 s42, 0, 0x18000
	s_add_i32 s43, 0, 0x1c000
	v_add_u32_e32 v160, s42, v145
	v_add_u32_e32 v176, s43, v145
	ds_read_b128 v[148:151], v160
	ds_read_b128 v[152:155], v160 offset:1024
	ds_read_b128 v[156:159], v160 offset:2048
	ds_read_b128 v[160:163], v160 offset:3072
	ds_read_b128 v[164:167], v176
	ds_read_b128 v[168:171], v176 offset:1024
	ds_read_b128 v[172:175], v176 offset:2048
	ds_read_b128 v[176:179], v176 offset:3072
	s_add_u32 s22, s22, 0x40000
	s_addc_u32 s23, s23, 0
	s_mov_b32 m0, s29
	v_lshl_add_u64 v[240:241], s[22:23], 0, v[130:131]
	ds_read_b128 v[180:183], v147 offset:32768
	ds_read_b128 v[202:205], v147 offset:33792
	ds_read_b128 v[206:209], v147 offset:34816
	ds_read_b128 v[210:213], v147 offset:35840
	ds_read_b128 v[214:217], v147 offset:36864
	ds_read_b128 v[218:221], v147 offset:37888
	ds_read_b128 v[222:225], v147 offset:38912
	ds_read_b128 v[226:229], v147 offset:39936
	global_load_lds_dwordx4 v[240:241], off
	v_lshl_add_u64 v[240:241], s[22:23], 0, v[132:133]
	s_mov_b32 m0, s33
	s_nop 0
	global_load_lds_dwordx4 v[240:241], off
	s_waitcnt vmcnt(8)
	s_waitcnt lgkmcnt(0)
	s_barrier
	s_setprio 1
	s_waitcnt lgkmcnt(0)
	v_mfma_f32_16x16x32_bf16 v[126:129], v[148:151], v[180:183], v[126:129]
	v_mfma_f32_16x16x32_bf16 v[122:125], v[156:159], v[180:183], v[122:125]
	v_mfma_f32_16x16x32_bf16 v[118:121], v[148:151], v[206:209], v[118:121]
	v_mfma_f32_16x16x32_bf16 v[114:117], v[156:159], v[206:209], v[114:117]
	v_mfma_f32_16x16x32_bf16 v[102:105], v[148:151], v[214:217], v[102:105]
	v_mfma_f32_16x16x32_bf16 v[98:101], v[156:159], v[214:217], v[98:101]
	v_mfma_f32_16x16x32_bf16 v[86:89], v[148:151], v[222:225], v[86:89]
	v_mfma_f32_16x16x32_bf16 v[82:85], v[156:159], v[222:225], v[82:85]
	v_mfma_f32_16x16x32_bf16 v[126:129], v[152:155], v[202:205], v[126:129]
	v_mfma_f32_16x16x32_bf16 v[122:125], v[160:163], v[202:205], v[122:125]
	v_mfma_f32_16x16x32_bf16 v[118:121], v[152:155], v[210:213], v[118:121]
	v_mfma_f32_16x16x32_bf16 v[114:117], v[160:163], v[210:213], v[114:117]
	v_mfma_f32_16x16x32_bf16 v[102:105], v[152:155], v[218:221], v[102:105]
	v_mfma_f32_16x16x32_bf16 v[98:101], v[160:163], v[218:221], v[98:101]
	v_mfma_f32_16x16x32_bf16 v[86:89], v[152:155], v[226:229], v[86:89]
	v_mfma_f32_16x16x32_bf16 v[82:85], v[160:163], v[226:229], v[82:85]
	v_mfma_f32_16x16x32_bf16 v[110:113], v[164:167], v[180:183], v[110:113]
	v_mfma_f32_16x16x32_bf16 v[106:109], v[172:175], v[180:183], v[106:109]
	v_mfma_f32_16x16x32_bf16 v[94:97], v[164:167], v[206:209], v[94:97]
	v_mfma_f32_16x16x32_bf16 v[90:93], v[172:175], v[206:209], v[90:93]
	v_mfma_f32_16x16x32_bf16 v[78:81], v[164:167], v[214:217], v[78:81]
	v_mfma_f32_16x16x32_bf16 v[74:77], v[172:175], v[214:217], v[74:77]
	v_mfma_f32_16x16x32_bf16 v[70:73], v[164:167], v[222:225], v[70:73]
	v_mfma_f32_16x16x32_bf16 v[66:69], v[172:175], v[222:225], v[66:69]
	v_mfma_f32_16x16x32_bf16 v[110:113], v[168:171], v[202:205], v[110:113]
	v_mfma_f32_16x16x32_bf16 v[106:109], v[176:179], v[202:205], v[106:109]
	v_mfma_f32_16x16x32_bf16 v[94:97], v[168:171], v[210:213], v[94:97]
	v_mfma_f32_16x16x32_bf16 v[90:93], v[176:179], v[210:213], v[90:93]
	v_mfma_f32_16x16x32_bf16 v[78:81], v[168:171], v[218:221], v[78:81]
	v_mfma_f32_16x16x32_bf16 v[74:77], v[176:179], v[218:221], v[74:77]
	v_mfma_f32_16x16x32_bf16 v[70:73], v[168:171], v[226:229], v[70:73]
	v_mfma_f32_16x16x32_bf16 v[66:69], v[176:179], v[226:229], v[66:69]
	s_setprio 0
	s_barrier
; #define PG8_STAGE(bufoff, gbase, voff) do { _Pragma("unroll") for (int _i = 0; _i < 2; ++_i) \
;         __builtin_amdgcn_global_load_lds((const unsigned*)((const char*)(gbase) + (voff)[_i]), (LAS unsigned*)(lds + (bufoff) + ldsw + _i * 8192), 16, 0, 0); } while (0)
; #define PG8_LDA(dst, b, h) do { _Pragma("unroll") for (int m = 0; m < 4; ++m) _Pragma("unroll") for (int k = 0; k < 2; ++k) dst[m][k] = *(const LAS bf16x8*)(lds + PG8_SA(b, h) + aoff + m * 2048 + k * 1024); } while (0)
; #define PG8_MMA(ai, bj, At, Bt_) do { __builtin_amdgcn_s_setprio(1); _Pragma("unroll") for (int m = 0; m < 4; ++m) _Pragma("unroll") for (int n = 0; n < 2; ++n) _Pragma("unroll") for (int k = 0; k < 2; ++k) \
;         acc[ai][bj][m][n] = __builtin_amdgcn_mfma_f32_16x16x32_bf16(Bt_[n][k], At[m][k], acc[ai][bj][m][n], 0, 0, 0); __builtin_amdgcn_s_setprio(0); } while (0)
; #define PG8_WAIT_V(n) asm volatile("s_waitcnt vmcnt(" #n ")" ::: "memory")
; #define PG8_WAIT_L(n) asm volatile("s_waitcnt lgkmcnt(" #n ")" ::: "memory")
; #define PG8_BAR __builtin_amdgcn_s_barrier()
; #define PG8_SCHED __builtin_amdgcn_sched_barrier(0)
; __device__ __forceinline__ void gemm_phase(LAS unsigned char* lds, const bf16_t* A, const bf16_t* Bt, int M, int N, int K, const Epi& E) {
;     ...
;             PG8_LDA(At, 1, 1); PG8_STAGE(PG8_SB(1, 0), b3, voffB); PG8_STAGE(PG8_SB(1, 1), b3 + hstep, voffB); PG8_STAGE(PG8_SA(1, 0), a3, voffA);
;             PG8_WAIT_V(8); PG8_WAIT_L(0); PG8_BAR; PG8_MMA(1, 0, At, B0); PG8_MMA(1, 1, At, B1); PG8_BAR; PG8_SCHED;
;         }
;         if (wr == 0) PG8_BAR;
	s_add_i32 s22, s42, s26
	v_lshl_add_u64 v[142:143], v[142:143], 0, s[46:47]
	s_mov_b32 m0, s22
	ds_read_b128 v[180:183], v147 offset:49152
	ds_read_b128 v[202:205], v147 offset:50176
	ds_read_b128 v[206:209], v147 offset:51200
	ds_read_b128 v[210:213], v147 offset:52224
	ds_read_b128 v[214:217], v147 offset:53248
	ds_read_b128 v[218:221], v147 offset:54272
	ds_read_b128 v[222:225], v147 offset:55296
	ds_read_b128 v[226:229], v147 offset:56320
	global_load_lds_dwordx4 v[142:143], off
	s_add_i32 m0, s22, 0x2000
	s_add_u32 s20, s20, 0x40080
	v_lshl_add_u64 v[142:143], v[184:185], 0, s[46:47]
	s_addc_u32 s21, s21, 0
	s_add_i32 s22, s43, s26
	global_load_lds_dwordx4 v[142:143], off
	v_lshl_add_u64 v[142:143], s[20:21], 0, v[0:1]
	s_mov_b32 m0, s22
	s_nop 0
	global_load_lds_dwordx4 v[142:143], off
	v_lshl_add_u64 v[142:143], s[20:21], 0, v[134:135]
	s_add_i32 m0, s22, 0x2000
	s_nop 0
	global_load_lds_dwordx4 v[142:143], off
	v_lshl_add_u64 v[142:143], v[230:231], 0, s[46:47]
	s_mov_b32 m0, s34
	s_nop 0
	global_load_lds_dwordx4 v[142:143], off
	v_lshl_add_u64 v[142:143], v[232:233], 0, s[46:47]
	s_mov_b32 m0, s35
	s_nop 0
	global_load_lds_dwordx4 v[142:143], off
	s_waitcnt vmcnt(8)
	s_waitcnt lgkmcnt(0)
	s_barrier
	s_setprio 1
	s_waitcnt lgkmcnt(0)
	v_mfma_f32_16x16x32_bf16 v[62:65], v[148:151], v[180:183], v[62:65]
	v_mfma_f32_16x16x32_bf16 v[58:61], v[156:159], v[180:183], v[58:61]
	v_mfma_f32_16x16x32_bf16 v[54:57], v[148:151], v[206:209], v[54:57]
	v_mfma_f32_16x16x32_bf16 v[50:53], v[156:159], v[206:209], v[50:53]
	v_mfma_f32_16x16x32_bf16 v[38:41], v[148:151], v[214:217], v[38:41]
	v_mfma_f32_16x16x32_bf16 v[34:37], v[156:159], v[214:217], v[34:37]
	v_mfma_f32_16x16x32_bf16 v[22:25], v[148:151], v[222:225], v[22:25]
	v_mfma_f32_16x16x32_bf16 v[18:21], v[156:159], v[222:225], v[18:21]
	v_mfma_f32_16x16x32_bf16 v[62:65], v[152:155], v[202:205], v[62:65]
	v_mfma_f32_16x16x32_bf16 v[58:61], v[160:163], v[202:205], v[58:61]
	v_mfma_f32_16x16x32_bf16 v[54:57], v[152:155], v[210:213], v[54:57]
	v_mfma_f32_16x16x32_bf16 v[50:53], v[160:163], v[210:213], v[50:53]
	v_mfma_f32_16x16x32_bf16 v[38:41], v[152:155], v[218:221], v[38:41]
	v_mfma_f32_16x16x32_bf16 v[34:37], v[160:163], v[218:221], v[34:37]
	v_mfma_f32_16x16x32_bf16 v[22:25], v[152:155], v[226:229], v[22:25]
	v_mfma_f32_16x16x32_bf16 v[18:21], v[160:163], v[226:229], v[18:21]
	v_mfma_f32_16x16x32_bf16 v[46:49], v[164:167], v[180:183], v[46:49]
	v_mfma_f32_16x16x32_bf16 v[42:45], v[172:175], v[180:183], v[42:45]
	v_mfma_f32_16x16x32_bf16 v[30:33], v[164:167], v[206:209], v[30:33]
	v_mfma_f32_16x16x32_bf16 v[26:29], v[172:175], v[206:209], v[26:29]
	v_mfma_f32_16x16x32_bf16 v[14:17], v[164:167], v[214:217], v[14:17]
	v_mfma_f32_16x16x32_bf16 v[10:13], v[172:175], v[214:217], v[10:13]
	v_mfma_f32_16x16x32_bf16 v[6:9], v[164:167], v[222:225], v[6:9]
	v_mfma_f32_16x16x32_bf16 v[2:5], v[172:175], v[222:225], v[2:5]
	v_mfma_f32_16x16x32_bf16 v[46:49], v[168:171], v[202:205], v[46:49]
	v_mfma_f32_16x16x32_bf16 v[42:45], v[176:179], v[202:205], v[42:45]
	v_mfma_f32_16x16x32_bf16 v[30:33], v[168:171], v[210:213], v[30:33]
	v_mfma_f32_16x16x32_bf16 v[26:29], v[176:179], v[210:213], v[26:29]
	v_mfma_f32_16x16x32_bf16 v[14:17], v[168:171], v[218:221], v[14:17]
	v_mfma_f32_16x16x32_bf16 v[10:13], v[176:179], v[218:221], v[10:13]
	v_mfma_f32_16x16x32_bf16 v[6:9], v[168:171], v[226:229], v[6:9]
	v_mfma_f32_16x16x32_bf16 v[2:5], v[176:179], v[226:229], v[2:5]
	s_setprio 0
	s_barrier
	s_add_i32 s41, s41, 2
	s_add_u32 s18, s18, 0x100
	s_addc_u32 s19, s19, 0
	s_add_u32 s39, s39, 0x100
	s_addc_u32 s40, s40, 0
	s_cmp_gt_u32 s41, 13
	s_cbranch_scc0 .LBB0_182
	s_and_b64 vcc, exec, s[4:5]
	s_cbranch_vccz .LBB0_185
	s_barrier

; #define PG8_STAGE(bufoff, gbase, voff) do { _Pragma("unroll") for (int _i = 0; _i < 2; ++_i) \
;         __builtin_amdgcn_global_load_lds((const unsigned*)((const char*)(gbase) + (voff)[_i]), (LAS unsigned*)(lds + (bufoff) + ldsw + _i * 8192), 16, 0, 0); } while (0)
; #define PG8_LDA(dst, b, h) do { _Pragma("unroll") for (int m = 0; m < 4; ++m) _Pragma("unroll") for (int k = 0; k < 2; ++k) dst[m][k] = *(const LAS bf16x8*)(lds + PG8_SA(b, h) + aoff + m * 2048 + k * 1024); } while (0)
; #define PG8_LDB(dst, b, h) do { _Pragma("unroll") for (int n = 0; n < 2; ++n) _Pragma("unroll") for (int k = 0; k < 2; ++k) dst[n][k] = *(const LAS bf16x8*)(lds + PG8_SB(b, h) + boff + n * 2048 + k * 1024); } while (0)
; #define PG8_MMA(ai, bj, At, Bt_) do { __builtin_amdgcn_s_setprio(1); _Pragma("unroll") for (int m = 0; m < 4; ++m) _Pragma("unroll") for (int n = 0; n < 2; ++n) _Pragma("unroll") for (int k = 0; k < 2; ++k) \
;         acc[ai][bj][m][n] = __builtin_amdgcn_mfma_f32_16x16x32_bf16(Bt_[n][k], At[m][k], acc[ai][bj][m][n], 0, 0, 0); __builtin_amdgcn_s_setprio(0); } while (0)
; #define PG8_WAIT_V(n) asm volatile("s_waitcnt vmcnt(" #n ")" ::: "memory")
; #define PG8_WAIT_L(n) asm volatile("s_waitcnt lgkmcnt(" #n ")" ::: "memory")
; #define PG8_BAR __builtin_amdgcn_s_barrier()
; #define PG8_SCHED __builtin_amdgcn_sched_barrier(0)
; __device__ __forceinline__ void gemm_phase(LAS unsigned char* lds, const bf16_t* A, const bf16_t* Bt, int M, int N, int K, const Epi& E) {
;     ...
;             PG8_LDB(B0, 0, 0); PG8_LDB(B1, 0, 1); PG8_SCHED; PG8_LDA(At, 0, 0); PG8_STAGE(PG8_SA(1, 1), a1 + hstep, voffA);
;             PG8_WAIT_V(8); PG8_WAIT_L(0); PG8_BAR; PG8_MMA(0, 0, At, B0); PG8_MMA(0, 1, At, B1); PG8_BAR; PG8_SCHED;
;             PG8_LDA(At, 0, 1); PG8_STAGE(PG8_SB(0, 0), b2, voffB); PG8_STAGE(PG8_SB(0, 1), b2 + hstep, voffB); PG8_STAGE(PG8_SA(0, 0), a2, voffA);
;             PG8_WAIT_V(8); PG8_WAIT_L(0); PG8_BAR; PG8_MMA(1, 0, At, B0); PG8_MMA(1, 1, At, B1); PG8_BAR; PG8_SCHED;
.LBB0_352:
	s_add_u32 s14, s12, 0x100
	s_addc_u32 s15, s13, 0
	s_add_i32 s40, 0, 0x10000
	s_cmp_eq_u32 s39, 2
	s_cselect_b32 s19, s3, s15
	s_cselect_b32 s18, s2, s14
	v_add_u32_e32 v142, s40, v145
	s_cselect_b32 s17, s11, s38
	s_cselect_b32 s16, s10, s37
	s_add_i32 s41, 0, 0x14000
	ds_read_b128 v[148:151], v142
	ds_read_b128 v[152:155], v142 offset:1024
	ds_read_b128 v[156:159], v142 offset:2048
	ds_read_b128 v[160:163], v142 offset:3072
	v_add_u32_e32 v142, s41, v145
	ds_read_b128 v[164:167], v142
	ds_read_b128 v[168:171], v142 offset:1024
	ds_read_b128 v[172:175], v142 offset:2048
	ds_read_b128 v[176:179], v142 offset:3072
	v_lshl_add_u64 v[142:143], s[12:13], 0, v[138:139]
	s_add_i32 m0, s23, 0xc000
	ds_read_b128 v[180:183], v147
	ds_read_b128 v[202:205], v147 offset:1024
	ds_read_b128 v[206:209], v147 offset:2048
	ds_read_b128 v[210:213], v147 offset:3072
	ds_read_b128 v[214:217], v147 offset:4096
	ds_read_b128 v[218:221], v147 offset:5120
	ds_read_b128 v[222:225], v147 offset:6144
	ds_read_b128 v[226:229], v147 offset:7168
	global_load_lds_dwordx4 v[142:143], off
	v_lshl_add_u64 v[142:143], s[12:13], 0, v[140:141]
	s_add_i32 m0, s23, 0xe000
	s_nop 0
	global_load_lds_dwordx4 v[142:143], off
	s_waitcnt vmcnt(8)
	s_waitcnt lgkmcnt(0)
	s_barrier
	s_setprio 1
	s_waitcnt lgkmcnt(0)
	v_mfma_f32_16x16x32_bf16 v[126:129], v[148:151], v[180:183], v[126:129]
	v_mfma_f32_16x16x32_bf16 v[122:125], v[156:159], v[180:183], v[122:125]
	v_mfma_f32_16x16x32_bf16 v[118:121], v[148:151], v[206:209], v[118:121]
	v_mfma_f32_16x16x32_bf16 v[114:117], v[156:159], v[206:209], v[114:117]
	v_mfma_f32_16x16x32_bf16 v[102:105], v[148:151], v[214:217], v[102:105]
	v_mfma_f32_16x16x32_bf16 v[98:101], v[156:159], v[214:217], v[98:101]
	v_mfma_f32_16x16x32_bf16 v[86:89], v[148:151], v[222:225], v[86:89]
	v_mfma_f32_16x16x32_bf16 v[82:85], v[156:159], v[222:225], v[82:85]
	v_mfma_f32_16x16x32_bf16 v[126:129], v[152:155], v[202:205], v[126:129]
	v_mfma_f32_16x16x32_bf16 v[122:125], v[160:163], v[202:205], v[122:125]
	v_mfma_f32_16x16x32_bf16 v[118:121], v[152:155], v[210:213], v[118:121]
	v_mfma_f32_16x16x32_bf16 v[114:117], v[160:163], v[210:213], v[114:117]
	v_mfma_f32_16x16x32_bf16 v[102:105], v[152:155], v[218:221], v[102:105]
	v_mfma_f32_16x16x32_bf16 v[98:101], v[160:163], v[218:221], v[98:101]
	v_mfma_f32_16x16x32_bf16 v[86:89], v[152:155], v[226:229], v[86:89]
	v_mfma_f32_16x16x32_bf16 v[82:85], v[160:163], v[226:229], v[82:85]
	v_mfma_f32_16x16x32_bf16 v[110:113], v[164:167], v[180:183], v[110:113]
	v_mfma_f32_16x16x32_bf16 v[106:109], v[172:175], v[180:183], v[106:109]
	v_mfma_f32_16x16x32_bf16 v[94:97], v[164:167], v[206:209], v[94:97]
	v_mfma_f32_16x16x32_bf16 v[90:93], v[172:175], v[206:209], v[90:93]
	v_mfma_f32_16x16x32_bf16 v[78:81], v[164:167], v[214:217], v[78:81]
	v_mfma_f32_16x16x32_bf16 v[74:77], v[172:175], v[214:217], v[74:77]
	v_mfma_f32_16x16x32_bf16 v[70:73], v[164:167], v[222:225], v[70:73]
	v_mfma_f32_16x16x32_bf16 v[66:69], v[172:175], v[222:225], v[66:69]
	v_mfma_f32_16x16x32_bf16 v[110:113], v[168:171], v[202:205], v[110:113]
	v_mfma_f32_16x16x32_bf16 v[106:109], v[176:179], v[202:205], v[106:109]
	v_mfma_f32_16x16x32_bf16 v[94:97], v[168:171], v[210:213], v[94:97]
	v_mfma_f32_16x16x32_bf16 v[90:93], v[176:179], v[210:213], v[90:93]
	v_mfma_f32_16x16x32_bf16 v[78:81], v[168:171], v[218:221], v[78:81]
	v_mfma_f32_16x16x32_bf16 v[74:77], v[176:179], v[218:221], v[74:77]
	v_mfma_f32_16x16x32_bf16 v[70:73], v[168:171], v[226:229], v[70:73]
	v_mfma_f32_16x16x32_bf16 v[66:69], v[176:179], v[226:229], v[66:69]
	s_setprio 0
	s_barrier
	s_add_i32 s12, s40, s22
	v_lshl_add_u64 v[142:143], s[16:17], 0, v[0:1]
	s_mov_b32 m0, s12
	ds_read_b128 v[180:183], v147 offset:16384
	ds_read_b128 v[202:205], v147 offset:17408
	ds_read_b128 v[206:209], v147 offset:18432
	ds_read_b128 v[210:213], v147 offset:19456
	ds_read_b128 v[214:217], v147 offset:20480
	ds_read_b128 v[218:221], v147 offset:21504
	ds_read_b128 v[222:225], v147 offset:22528
	ds_read_b128 v[226:229], v147 offset:23552
	global_load_lds_dwordx4 v[142:143], off
	s_add_i32 m0, s12, 0x2000
	s_add_u32 s12, s16, 0x18000
	v_lshl_add_u64 v[184:185], s[16:17], 0, v[134:135]
	s_addc_u32 s13, s17, 0
	s_add_i32 s40, s41, s22
	global_load_lds_dwordx4 v[184:185], off
	v_lshl_add_u64 v[230:231], s[12:13], 0, v[0:1]
	s_mov_b32 m0, s40
	v_lshl_add_u64 v[232:233], s[18:19], 0, v[132:133]
	global_load_lds_dwordx4 v[230:231], off
	v_lshl_add_u64 v[230:231], s[12:13], 0, v[134:135]
	s_add_i32 m0, s40, 0x2000
	s_nop 0
	global_load_lds_dwordx4 v[230:231], off
	v_lshl_add_u64 v[230:231], s[18:19], 0, v[130:131]
	s_mov_b32 m0, s23
	s_nop 0
	global_load_lds_dwordx4 v[230:231], off
	s_mov_b32 m0, s24
	s_nop 0
	global_load_lds_dwordx4 v[232:233], off
	s_waitcnt vmcnt(8)
	s_waitcnt lgkmcnt(0)
	s_barrier
; #define PG8_STAGE(bufoff, gbase, voff) do { _Pragma("unroll") for (int _i = 0; _i < 2; ++_i) \
;         __builtin_amdgcn_global_load_lds((const unsigned*)((const char*)(gbase) + (voff)[_i]), (LAS unsigned*)(lds + (bufoff) + ldsw + _i * 8192), 16, 0, 0); } while (0)
; #define PG8_LDA(dst, b, h) do { _Pragma("unroll") for (int m = 0; m < 4; ++m) _Pragma("unroll") for (int k = 0; k < 2; ++k) dst[m][k] = *(const LAS bf16x8*)(lds + PG8_SA(b, h) + aoff + m * 2048 + k * 1024); } while (0)
; #define PG8_LDB(dst, b, h) do { _Pragma("unroll") for (int n = 0; n < 2; ++n) _Pragma("unroll") for (int k = 0; k < 2; ++k) dst[n][k] = *(const LAS bf16x8*)(lds + PG8_SB(b, h) + boff + n * 2048 + k * 1024); } while (0)
; #define PG8_MMA(ai, bj, At, Bt_) do { __builtin_amdgcn_s_setprio(1); _Pragma("unroll") for (int m = 0; m < 4; ++m) _Pragma("unroll") for (int n = 0; n < 2; ++n) _Pragma("unroll") for (int k = 0; k < 2; ++k) \
;         acc[ai][bj][m][n] = __builtin_amdgcn_mfma_f32_16x16x32_bf16(Bt_[n][k], At[m][k], acc[ai][bj][m][n], 0, 0, 0); __builtin_amdgcn_s_setprio(0); } while (0)
; #define PG8_WAIT_V(n) asm volatile("s_waitcnt vmcnt(" #n ")" ::: "memory")
; #define PG8_WAIT_L(n) asm volatile("s_waitcnt lgkmcnt(" #n ")" ::: "memory")
; #define PG8_BAR __builtin_amdgcn_s_barrier()
; #define PG8_SCHED __builtin_amdgcn_sched_barrier(0)
; __device__ __forceinline__ void gemm_phase(LAS unsigned char* lds, const bf16_t* A, const bf16_t* Bt, int M, int N, int K, const Epi& E) {
;     ...
;             PG8_WAIT_V(8); PG8_WAIT_L(0); PG8_BAR; PG8_MMA(1, 0, At, B0); PG8_MMA(1, 1, At, B1); PG8_BAR; PG8_SCHED;
;             PG8_LDB(B0, 1, 0); PG8_LDB(B1, 1, 1); PG8_SCHED; PG8_LDA(At, 1, 0); PG8_STAGE(PG8_SA(0, 1), a2 + hstep, voffA);
;             PG8_WAIT_V(8); PG8_WAIT_L(0); PG8_BAR; PG8_MMA(0, 0, At, B0); PG8_MMA(0, 1, At, B1); PG8_BAR; PG8_SCHED;
	s_setprio 1
	s_waitcnt lgkmcnt(0)
	v_mfma_f32_16x16x32_bf16 v[62:65], v[148:151], v[180:183], v[62:65]
	v_mfma_f32_16x16x32_bf16 v[58:61], v[156:159], v[180:183], v[58:61]
	v_mfma_f32_16x16x32_bf16 v[54:57], v[148:151], v[206:209], v[54:57]
	v_mfma_f32_16x16x32_bf16 v[50:53], v[156:159], v[206:209], v[50:53]
	v_mfma_f32_16x16x32_bf16 v[38:41], v[148:151], v[214:217], v[38:41]
	v_mfma_f32_16x16x32_bf16 v[34:37], v[156:159], v[214:217], v[34:37]
	v_mfma_f32_16x16x32_bf16 v[22:25], v[148:151], v[222:225], v[22:25]
	v_mfma_f32_16x16x32_bf16 v[18:21], v[156:159], v[222:225], v[18:21]
	v_mfma_f32_16x16x32_bf16 v[62:65], v[152:155], v[202:205], v[62:65]
	v_mfma_f32_16x16x32_bf16 v[58:61], v[160:163], v[202:205], v[58:61]
	v_mfma_f32_16x16x32_bf16 v[54:57], v[152:155], v[210:213], v[54:57]
	v_mfma_f32_16x16x32_bf16 v[50:53], v[160:163], v[210:213], v[50:53]
	v_mfma_f32_16x16x32_bf16 v[38:41], v[152:155], v[218:221], v[38:41]
	v_mfma_f32_16x16x32_bf16 v[34:37], v[160:163], v[218:221], v[34:37]
	v_mfma_f32_16x16x32_bf16 v[22:25], v[152:155], v[226:229], v[22:25]
	v_mfma_f32_16x16x32_bf16 v[18:21], v[160:163], v[226:229], v[18:21]
	v_mfma_f32_16x16x32_bf16 v[46:49], v[164:167], v[180:183], v[46:49]
	v_mfma_f32_16x16x32_bf16 v[42:45], v[172:175], v[180:183], v[42:45]
	v_mfma_f32_16x16x32_bf16 v[30:33], v[164:167], v[206:209], v[30:33]
	v_mfma_f32_16x16x32_bf16 v[26:29], v[172:175], v[206:209], v[26:29]
	v_mfma_f32_16x16x32_bf16 v[14:17], v[164:167], v[214:217], v[14:17]
	v_mfma_f32_16x16x32_bf16 v[10:13], v[172:175], v[214:217], v[10:13]
	v_mfma_f32_16x16x32_bf16 v[6:9], v[164:167], v[222:225], v[6:9]
	v_mfma_f32_16x16x32_bf16 v[2:5], v[172:175], v[222:225], v[2:5]
	v_mfma_f32_16x16x32_bf16 v[46:49], v[168:171], v[202:205], v[46:49]
	v_mfma_f32_16x16x32_bf16 v[42:45], v[176:179], v[202:205], v[42:45]
	v_mfma_f32_16x16x32_bf16 v[30:33], v[168:171], v[210:213], v[30:33]
	v_mfma_f32_16x16x32_bf16 v[26:29], v[176:179], v[210:213], v[26:29]
	v_mfma_f32_16x16x32_bf16 v[14:17], v[168:171], v[218:221], v[14:17]
	v_mfma_f32_16x16x32_bf16 v[10:13], v[176:179], v[218:221], v[10:13]
	v_mfma_f32_16x16x32_bf16 v[6:9], v[168:171], v[226:229], v[6:9]
	v_mfma_f32_16x16x32_bf16 v[2:5], v[176:179], v[226:229], v[2:5]
	s_setprio 0
	s_barrier
	s_add_i32 s40, 0, 0x18000
	s_add_i32 s41, 0, 0x1c000
	v_add_u32_e32 v160, s40, v145
	v_add_u32_e32 v176, s41, v145
	ds_read_b128 v[148:151], v160
	ds_read_b128 v[152:155], v160 offset:1024
	ds_read_b128 v[156:159], v160 offset:2048
	ds_read_b128 v[160:163], v160 offset:3072
	ds_read_b128 v[164:167], v176
	ds_read_b128 v[168:171], v176 offset:1024
	ds_read_b128 v[172:175], v176 offset:2048
	ds_read_b128 v[176:179], v176 offset:3072
	s_add_u32 s12, s18, 0x18000
	s_addc_u32 s13, s19, 0
	s_mov_b32 m0, s25
	v_lshl_add_u64 v[240:241], s[12:13], 0, v[130:131]
	ds_read_b128 v[180:183], v147 offset:32768
	ds_read_b128 v[202:205], v147 offset:33792
	ds_read_b128 v[206:209], v147 offset:34816
	ds_read_b128 v[210:213], v147 offset:35840
	ds_read_b128 v[214:217], v147 offset:36864
	ds_read_b128 v[218:221], v147 offset:37888
	ds_read_b128 v[222:225], v147 offset:38912
	ds_read_b128 v[226:229], v147 offset:39936
	global_load_lds_dwordx4 v[240:241], off
	v_lshl_add_u64 v[240:241], s[12:13], 0, v[132:133]
	s_mov_b32 m0, s26
	s_nop 0
	global_load_lds_dwordx4 v[240:241], off
	s_waitcnt vmcnt(8)
	s_waitcnt lgkmcnt(0)
	s_barrier
	s_setprio 1
	s_waitcnt lgkmcnt(0)
	v_mfma_f32_16x16x32_bf16 v[126:129], v[148:151], v[180:183], v[126:129]
	v_mfma_f32_16x16x32_bf16 v[122:125], v[156:159], v[180:183], v[122:125]
	v_mfma_f32_16x16x32_bf16 v[118:121], v[148:151], v[206:209], v[118:121]
	v_mfma_f32_16x16x32_bf16 v[114:117], v[156:159], v[206:209], v[114:117]
	v_mfma_f32_16x16x32_bf16 v[102:105], v[148:151], v[214:217], v[102:105]
	v_mfma_f32_16x16x32_bf16 v[98:101], v[156:159], v[214:217], v[98:101]
	v_mfma_f32_16x16x32_bf16 v[86:89], v[148:151], v[222:225], v[86:89]
	v_mfma_f32_16x16x32_bf16 v[82:85], v[156:159], v[222:225], v[82:85]
	v_mfma_f32_16x16x32_bf16 v[126:129], v[152:155], v[202:205], v[126:129]
	v_mfma_f32_16x16x32_bf16 v[122:125], v[160:163], v[202:205], v[122:125]
	v_mfma_f32_16x16x32_bf16 v[118:121], v[152:155], v[210:213], v[118:121]
	v_mfma_f32_16x16x32_bf16 v[114:117], v[160:163], v[210:213], v[114:117]
	v_mfma_f32_16x16x32_bf16 v[102:105], v[152:155], v[218:221], v[102:105]
	v_mfma_f32_16x16x32_bf16 v[98:101], v[160:163], v[218:221], v[98:101]
	v_mfma_f32_16x16x32_bf16 v[86:89], v[152:155], v[226:229], v[86:89]
	v_mfma_f32_16x16x32_bf16 v[82:85], v[160:163], v[226:229], v[82:85]
	v_mfma_f32_16x16x32_bf16 v[110:113], v[164:167], v[180:183], v[110:113]
	v_mfma_f32_16x16x32_bf16 v[106:109], v[172:175], v[180:183], v[106:109]
	v_mfma_f32_16x16x32_bf16 v[94:97], v[164:167], v[206:209], v[94:97]
	v_mfma_f32_16x16x32_bf16 v[90:93], v[172:175], v[206:209], v[90:93]
	v_mfma_f32_16x16x32_bf16 v[78:81], v[164:167], v[214:217], v[78:81]
	v_mfma_f32_16x16x32_bf16 v[74:77], v[172:175], v[214:217], v[74:77]
	v_mfma_f32_16x16x32_bf16 v[70:73], v[164:167], v[222:225], v[70:73]
	v_mfma_f32_16x16x32_bf16 v[66:69], v[172:175], v[222:225], v[66:69]
	v_mfma_f32_16x16x32_bf16 v[110:113], v[168:171], v[202:205], v[110:113]
	v_mfma_f32_16x16x32_bf16 v[106:109], v[176:179], v[202:205], v[106:109]
	v_mfma_f32_16x16x32_bf16 v[94:97], v[168:171], v[210:213], v[94:97]
	v_mfma_f32_16x16x32_bf16 v[90:93], v[176:179], v[210:213], v[90:93]
	v_mfma_f32_16x16x32_bf16 v[78:81], v[168:171], v[218:221], v[78:81]
	v_mfma_f32_16x16x32_bf16 v[74:77], v[176:179], v[218:221], v[74:77]
	v_mfma_f32_16x16x32_bf16 v[70:73], v[168:171], v[226:229], v[70:73]
	v_mfma_f32_16x16x32_bf16 v[66:69], v[176:179], v[226:229], v[66:69]
	s_setprio 0
	s_barrier
; #define PG8_STAGE(bufoff, gbase, voff) do { _Pragma("unroll") for (int _i = 0; _i < 2; ++_i) \
;         __builtin_amdgcn_global_load_lds((const unsigned*)((const char*)(gbase) + (voff)[_i]), (LAS unsigned*)(lds + (bufoff) + ldsw + _i * 8192), 16, 0, 0); } while (0)
; #define PG8_LDA(dst, b, h) do { _Pragma("unroll") for (int m = 0; m < 4; ++m) _Pragma("unroll") for (int k = 0; k < 2; ++k) dst[m][k] = *(const LAS bf16x8*)(lds + PG8_SA(b, h) + aoff + m * 2048 + k * 1024); } while (0)
; #define PG8_MMA(ai, bj, At, Bt_) do { __builtin_amdgcn_s_setprio(1); _Pragma("unroll") for (int m = 0; m < 4; ++m) _Pragma("unroll") for (int n = 0; n < 2; ++n) _Pragma("unroll") for (int k = 0; k < 2; ++k) \
;         acc[ai][bj][m][n] = __builtin_amdgcn_mfma_f32_16x16x32_bf16(Bt_[n][k], At[m][k], acc[ai][bj][m][n], 0, 0, 0); __builtin_amdgcn_s_setprio(0); } while (0)
; #define PG8_WAIT_V(n) asm volatile("s_waitcnt vmcnt(" #n ")" ::: "memory")
; #define PG8_WAIT_L(n) asm volatile("s_waitcnt lgkmcnt(" #n ")" ::: "memory")
; #define PG8_BAR __builtin_amdgcn_s_barrier()
; #define PG8_SCHED __builtin_amdgcn_sched_barrier(0)
; __device__ __forceinline__ void gemm_phase(LAS unsigned char* lds, const bf16_t* A, const bf16_t* Bt, int M, int N, int K, const Epi& E) {
;     ...
;             PG8_LDA(At, 1, 1); PG8_STAGE(PG8_SB(1, 0), b3, voffB); PG8_STAGE(PG8_SB(1, 1), b3 + hstep, voffB); PG8_STAGE(PG8_SA(1, 0), a3, voffA);
;             PG8_WAIT_V(8); PG8_WAIT_L(0); PG8_BAR; PG8_MMA(1, 0, At, B0); PG8_MMA(1, 1, At, B1); PG8_BAR; PG8_SCHED;
;         }
;         if (wr == 0) PG8_BAR;
	s_add_i32 s12, s40, s22
	v_lshl_add_u64 v[142:143], v[142:143], 0, s[42:43]
	s_mov_b32 m0, s12
	ds_read_b128 v[180:183], v147 offset:49152
	ds_read_b128 v[202:205], v147 offset:50176
	ds_read_b128 v[206:209], v147 offset:51200
	ds_read_b128 v[210:213], v147 offset:52224
	ds_read_b128 v[214:217], v147 offset:53248
	ds_read_b128 v[218:221], v147 offset:54272
	ds_read_b128 v[222:225], v147 offset:55296
	ds_read_b128 v[226:229], v147 offset:56320
	global_load_lds_dwordx4 v[142:143], off
	s_add_i32 m0, s12, 0x2000
	s_add_u32 s12, s16, 0x18080
	v_lshl_add_u64 v[142:143], v[184:185], 0, s[42:43]
	s_addc_u32 s13, s17, 0
	s_add_i32 s16, s41, s22
	global_load_lds_dwordx4 v[142:143], off
	v_lshl_add_u64 v[142:143], s[12:13], 0, v[0:1]
	s_mov_b32 m0, s16
	s_nop 0
	global_load_lds_dwordx4 v[142:143], off
	v_lshl_add_u64 v[142:143], s[12:13], 0, v[134:135]
	s_add_i32 m0, s16, 0x2000
	s_nop 0
	global_load_lds_dwordx4 v[142:143], off
	v_lshl_add_u64 v[142:143], v[230:231], 0, s[42:43]
	s_mov_b32 m0, s27
	s_nop 0
	global_load_lds_dwordx4 v[142:143], off
	v_lshl_add_u64 v[142:143], v[232:233], 0, s[42:43]
	s_mov_b32 m0, s28
	s_nop 0
	global_load_lds_dwordx4 v[142:143], off
	s_waitcnt vmcnt(8)
	s_waitcnt lgkmcnt(0)
	s_barrier
	s_setprio 1
	s_waitcnt lgkmcnt(0)
	v_mfma_f32_16x16x32_bf16 v[62:65], v[148:151], v[180:183], v[62:65]
	v_mfma_f32_16x16x32_bf16 v[58:61], v[156:159], v[180:183], v[58:61]
	v_mfma_f32_16x16x32_bf16 v[54:57], v[148:151], v[206:209], v[54:57]
	v_mfma_f32_16x16x32_bf16 v[50:53], v[156:159], v[206:209], v[50:53]
	v_mfma_f32_16x16x32_bf16 v[38:41], v[148:151], v[214:217], v[38:41]
	v_mfma_f32_16x16x32_bf16 v[34:37], v[156:159], v[214:217], v[34:37]
	v_mfma_f32_16x16x32_bf16 v[22:25], v[148:151], v[222:225], v[22:25]
	v_mfma_f32_16x16x32_bf16 v[18:21], v[156:159], v[222:225], v[18:21]
	v_mfma_f32_16x16x32_bf16 v[62:65], v[152:155], v[202:205], v[62:65]
	v_mfma_f32_16x16x32_bf16 v[58:61], v[160:163], v[202:205], v[58:61]
	v_mfma_f32_16x16x32_bf16 v[54:57], v[152:155], v[210:213], v[54:57]
	v_mfma_f32_16x16x32_bf16 v[50:53], v[160:163], v[210:213], v[50:53]
	v_mfma_f32_16x16x32_bf16 v[38:41], v[152:155], v[218:221], v[38:41]
	v_mfma_f32_16x16x32_bf16 v[34:37], v[160:163], v[218:221], v[34:37]
	v_mfma_f32_16x16x32_bf16 v[22:25], v[152:155], v[226:229], v[22:25]
	v_mfma_f32_16x16x32_bf16 v[18:21], v[160:163], v[226:229], v[18:21]
	v_mfma_f32_16x16x32_bf16 v[46:49], v[164:167], v[180:183], v[46:49]
	v_mfma_f32_16x16x32_bf16 v[42:45], v[172:175], v[180:183], v[42:45]
	v_mfma_f32_16x16x32_bf16 v[30:33], v[164:167], v[206:209], v[30:33]
	v_mfma_f32_16x16x32_bf16 v[26:29], v[172:175], v[206:209], v[26:29]
	v_mfma_f32_16x16x32_bf16 v[14:17], v[164:167], v[214:217], v[14:17]
	v_mfma_f32_16x16x32_bf16 v[10:13], v[172:175], v[214:217], v[10:13]
	v_mfma_f32_16x16x32_bf16 v[6:9], v[164:167], v[222:225], v[6:9]
	v_mfma_f32_16x16x32_bf16 v[2:5], v[172:175], v[222:225], v[2:5]
	v_mfma_f32_16x16x32_bf16 v[46:49], v[168:171], v[202:205], v[46:49]
	v_mfma_f32_16x16x32_bf16 v[42:45], v[176:179], v[202:205], v[42:45]
	v_mfma_f32_16x16x32_bf16 v[30:33], v[168:171], v[210:213], v[30:33]
	v_mfma_f32_16x16x32_bf16 v[26:29], v[176:179], v[210:213], v[26:29]
	v_mfma_f32_16x16x32_bf16 v[14:17], v[168:171], v[218:221], v[14:17]
	v_mfma_f32_16x16x32_bf16 v[10:13], v[176:179], v[218:221], v[10:13]
	v_mfma_f32_16x16x32_bf16 v[6:9], v[168:171], v[226:229], v[6:9]
	v_mfma_f32_16x16x32_bf16 v[2:5], v[176:179], v[226:229], v[2:5]
	s_setprio 0
	s_barrier
	s_add_i32 s39, s39, 2
	s_add_u32 s37, s37, 0x100
	s_addc_u32 s38, s38, 0
	s_cmp_gt_u32 s39, 3
	s_mov_b64 s[12:13], s[14:15]
	s_cbranch_scc0 .LBB0_352
	s_and_b64 vcc, exec, s[6:7]
	s_cbranch_vccz .LBB0_355
	s_barrier

; #define PG8_STAGE(bufoff, gbase, voff) do { _Pragma("unroll") for (int _i = 0; _i < 2; ++_i) \
;         __builtin_amdgcn_global_load_lds((const unsigned*)((const char*)(gbase) + (voff)[_i]), (LAS unsigned*)(lds + (bufoff) + ldsw + _i * 8192), 16, 0, 0); } while (0)
; #define PG8_LDA(dst, b, h) do { _Pragma("unroll") for (int m = 0; m < 4; ++m) _Pragma("unroll") for (int k = 0; k < 2; ++k) dst[m][k] = *(const LAS bf16x8*)(lds + PG8_SA(b, h) + aoff + m * 2048 + k * 1024); } while (0)
; #define PG8_LDB(dst, b, h) do { _Pragma("unroll") for (int n = 0; n < 2; ++n) _Pragma("unroll") for (int k = 0; k < 2; ++k) dst[n][k] = *(const LAS bf16x8*)(lds + PG8_SB(b, h) + boff + n * 2048 + k * 1024); } while (0)
; #define PG8_MMA(ai, bj, At, Bt_) do { __builtin_amdgcn_s_setprio(1); _Pragma("unroll") for (int m = 0; m < 4; ++m) _Pragma("unroll") for (int n = 0; n < 2; ++n) _Pragma("unroll") for (int k = 0; k < 2; ++k) \
;         acc[ai][bj][m][n] = __builtin_amdgcn_mfma_f32_16x16x32_bf16(Bt_[n][k], At[m][k], acc[ai][bj][m][n], 0, 0, 0); __builtin_amdgcn_s_setprio(0); } while (0)
; #define PG8_WAIT_V(n) asm volatile("s_waitcnt vmcnt(" #n ")" ::: "memory")
; #define PG8_WAIT_L(n) asm volatile("s_waitcnt lgkmcnt(" #n ")" ::: "memory")
; #define PG8_BAR __builtin_amdgcn_s_barrier()
; #define PG8_SCHED __builtin_amdgcn_sched_barrier(0)
; __device__ __forceinline__ void gemm_phase(LAS unsigned char* lds, const bf16_t* A, const bf16_t* Bt, int M, int N, int K, const Epi& E) {
;     ...
;         for (int t = 0; t < nt; t += 2) {
;             const bool last = (t == nt - 2);
;             const char* a1 = cA + (size_t)(t + 1) * kstep;
;             const char* a2 = last ? nA : cA + (size_t)(t + 2) * kstep; const char* b2 = last ? nB : cB + (size_t)(t + 2) * kstep;
;             const char* a3 = a2 + kstep; const char* b3 = b2 + kstep;
;             PG8_LDB(B0, 0, 0); PG8_LDB(B1, 0, 1); PG8_SCHED; PG8_LDA(At, 0, 0); PG8_STAGE(PG8_SA(1, 1), a1 + hstep, voffA);
;             PG8_WAIT_V(8); PG8_WAIT_L(0); PG8_BAR; PG8_MMA(0, 0, At, B0); PG8_MMA(0, 1, At, B1); PG8_BAR; PG8_SCHED;
;             PG8_LDA(At, 0, 1); PG8_STAGE(PG8_SB(0, 0), b2, voffB); PG8_STAGE(PG8_SB(0, 1), b2 + hstep, voffB); PG8_STAGE(PG8_SA(0, 0), a2, voffA);
;             PG8_WAIT_V(8); PG8_WAIT_L(0); PG8_BAR; PG8_MMA(1, 0, At, B0); PG8_MMA(1, 1, At, B1); PG8_BAR; PG8_SCHED;
.LBB0_374:
	s_add_u32 s27, s20, s26
	s_addc_u32 s36, s21, 0
	s_add_u32 s34, s27, 0x100
	s_addc_u32 s35, s36, 0
	s_and_b64 s[28:29], s[24:25], exec
	s_cselect_b32 s29, s11, s35
	s_cselect_b32 s28, s17, s34
	s_add_u32 s26, s18, s26
	s_addc_u32 s34, s19, 0
	s_add_u32 s26, s26, 0x100
	s_addc_u32 s34, s34, 0
	s_add_i32 s59, 0, 0x10000
	s_and_b64 s[24:25], s[24:25], exec
	s_cselect_b32 s35, s9, s34
	s_cselect_b32 s34, s50, s26
	s_add_i32 s25, 0, 0x14000
	s_add_u32 s38, s27, 0x10080
	s_addc_u32 s39, s36, 0
	s_add_i32 s58, s59, s40
	s_add_i32 m0, s42, 0xc000
	s_add_i32 s62, s42, 0xe000
	s_add_i32 s55, s58, 0x2000
	v_add_u32_e32 v138, s59, v141
	s_add_u32 s36, s34, 0x10000
	ds_read_b128 v[144:147], v138
	ds_read_b128 v[148:151], v138 offset:1024
	ds_read_b128 v[152:155], v138 offset:2048
	ds_read_b128 v[156:159], v138 offset:3072
	v_add_u32_e32 v138, s25, v141
	s_addc_u32 s37, s35, 0
	s_add_i32 s57, s25, s40
	ds_read_b128 v[160:163], v138
	ds_read_b128 v[164:167], v138 offset:1024
	ds_read_b128 v[168:171], v138 offset:2048
	ds_read_b128 v[172:175], v138 offset:3072
	s_add_i32 s56, s57, 0x2000
	s_add_i32 s54, 0, 0x18000
	s_add_i32 s53, 0, 0x1c000
	s_add_u32 s26, s28, 0x10000
	s_addc_u32 s27, s29, 0
	s_add_i32 s52, s54, s40
	s_add_i32 s51, s52, 0x2000
	s_add_u32 s24, s34, 0x10080
	s_addc_u32 s25, s35, 0
	s_add_i32 s61, s53, s40
	s_add_i32 s59, s61, 0x2000
	v_lshl_add_u64 v[138:139], s[38:39], 0, v[134:135]
	ds_read_b128 v[176:179], v143
	ds_read_b128 v[180:183], v143 offset:1024
	ds_read_b128 v[202:205], v143 offset:2048
	ds_read_b128 v[206:209], v143 offset:3072
	ds_read_b128 v[210:213], v143 offset:4096
	ds_read_b128 v[214:217], v143 offset:5120
	ds_read_b128 v[218:221], v143 offset:6144
	ds_read_b128 v[222:225], v143 offset:7168
	global_load_lds_dwordx4 v[138:139], off
	v_lshl_add_u64 v[138:139], s[38:39], 0, v[132:133]
	s_mov_b32 m0, s62
	s_nop 0
	global_load_lds_dwordx4 v[138:139], off
	s_waitcnt vmcnt(8)
	s_waitcnt lgkmcnt(0)
	s_barrier
	s_setprio 1
	s_waitcnt lgkmcnt(0)
	v_mfma_f32_16x16x32_bf16 v[126:129], v[144:147], v[176:179], v[126:129]
	v_mfma_f32_16x16x32_bf16 v[122:125], v[152:155], v[176:179], v[122:125]
	v_mfma_f32_16x16x32_bf16 v[118:121], v[144:147], v[202:205], v[118:121]
	v_mfma_f32_16x16x32_bf16 v[114:117], v[152:155], v[202:205], v[114:117]
	v_mfma_f32_16x16x32_bf16 v[102:105], v[144:147], v[210:213], v[102:105]
	v_mfma_f32_16x16x32_bf16 v[98:101], v[152:155], v[210:213], v[98:101]
	v_mfma_f32_16x16x32_bf16 v[86:89], v[144:147], v[218:221], v[86:89]
	v_mfma_f32_16x16x32_bf16 v[82:85], v[152:155], v[218:221], v[82:85]
	v_mfma_f32_16x16x32_bf16 v[126:129], v[148:151], v[180:183], v[126:129]
	v_mfma_f32_16x16x32_bf16 v[122:125], v[156:159], v[180:183], v[122:125]
	v_mfma_f32_16x16x32_bf16 v[118:121], v[148:151], v[206:209], v[118:121]
	v_mfma_f32_16x16x32_bf16 v[114:117], v[156:159], v[206:209], v[114:117]
	v_mfma_f32_16x16x32_bf16 v[102:105], v[148:151], v[214:217], v[102:105]
	v_mfma_f32_16x16x32_bf16 v[98:101], v[156:159], v[214:217], v[98:101]
	v_mfma_f32_16x16x32_bf16 v[86:89], v[148:151], v[222:225], v[86:89]
	v_mfma_f32_16x16x32_bf16 v[82:85], v[156:159], v[222:225], v[82:85]
	v_mfma_f32_16x16x32_bf16 v[110:113], v[160:163], v[176:179], v[110:113]
	v_mfma_f32_16x16x32_bf16 v[106:109], v[168:171], v[176:179], v[106:109]
	v_mfma_f32_16x16x32_bf16 v[94:97], v[160:163], v[202:205], v[94:97]
	v_mfma_f32_16x16x32_bf16 v[90:93], v[168:171], v[202:205], v[90:93]
	v_mfma_f32_16x16x32_bf16 v[78:81], v[160:163], v[210:213], v[78:81]
	v_mfma_f32_16x16x32_bf16 v[74:77], v[168:171], v[210:213], v[74:77]
	v_mfma_f32_16x16x32_bf16 v[70:73], v[160:163], v[218:221], v[70:73]
	v_mfma_f32_16x16x32_bf16 v[66:69], v[168:171], v[218:221], v[66:69]
	v_mfma_f32_16x16x32_bf16 v[110:113], v[164:167], v[180:183], v[110:113]
	v_mfma_f32_16x16x32_bf16 v[106:109], v[172:175], v[180:183], v[106:109]
	v_mfma_f32_16x16x32_bf16 v[94:97], v[164:167], v[206:209], v[94:97]
	v_mfma_f32_16x16x32_bf16 v[90:93], v[172:175], v[206:209], v[90:93]
	v_mfma_f32_16x16x32_bf16 v[78:81], v[164:167], v[214:217], v[78:81]
	v_mfma_f32_16x16x32_bf16 v[74:77], v[172:175], v[214:217], v[74:77]
	v_mfma_f32_16x16x32_bf16 v[70:73], v[164:167], v[222:225], v[70:73]
	v_mfma_f32_16x16x32_bf16 v[66:69], v[172:175], v[222:225], v[66:69]
	s_setprio 0
	s_barrier
	s_mov_b32 m0, s58
	v_lshl_add_u64 v[138:139], s[34:35], 0, v[0:1]
	ds_read_b128 v[176:179], v143 offset:16384
	ds_read_b128 v[180:183], v143 offset:17408
	ds_read_b128 v[202:205], v143 offset:18432
	ds_read_b128 v[206:209], v143 offset:19456
	ds_read_b128 v[210:213], v143 offset:20480
	ds_read_b128 v[214:217], v143 offset:21504
	ds_read_b128 v[218:221], v143 offset:22528
	ds_read_b128 v[222:225], v143 offset:23552
	global_load_lds_dwordx4 v[138:139], off
	v_lshl_add_u64 v[184:185], s[34:35], 0, v[130:131]
	s_mov_b32 m0, s55
	v_lshl_add_u64 v[226:227], s[36:37], 0, v[0:1]
	global_load_lds_dwordx4 v[184:185], off
	s_mov_b32 m0, s57
	v_lshl_add_u64 v[228:229], s[28:29], 0, v[132:133]
	global_load_lds_dwordx4 v[226:227], off
	v_lshl_add_u64 v[226:227], s[36:37], 0, v[130:131]
	s_mov_b32 m0, s56
	s_nop 0
	global_load_lds_dwordx4 v[226:227], off
	v_lshl_add_u64 v[226:227], s[28:29], 0, v[134:135]
	s_mov_b32 m0, s42
	s_nop 0
	global_load_lds_dwordx4 v[226:227], off
	s_mov_b32 m0, s43
	s_nop 0
	global_load_lds_dwordx4 v[228:229], off
	s_waitcnt vmcnt(8)
	s_waitcnt lgkmcnt(0)
	s_barrier
; #define PG8_STAGE(bufoff, gbase, voff) do { _Pragma("unroll") for (int _i = 0; _i < 2; ++_i) \
;         __builtin_amdgcn_global_load_lds((const unsigned*)((const char*)(gbase) + (voff)[_i]), (LAS unsigned*)(lds + (bufoff) + ldsw + _i * 8192), 16, 0, 0); } while (0)
; #define PG8_LDA(dst, b, h) do { _Pragma("unroll") for (int m = 0; m < 4; ++m) _Pragma("unroll") for (int k = 0; k < 2; ++k) dst[m][k] = *(const LAS bf16x8*)(lds + PG8_SA(b, h) + aoff + m * 2048 + k * 1024); } while (0)
; #define PG8_LDB(dst, b, h) do { _Pragma("unroll") for (int n = 0; n < 2; ++n) _Pragma("unroll") for (int k = 0; k < 2; ++k) dst[n][k] = *(const LAS bf16x8*)(lds + PG8_SB(b, h) + boff + n * 2048 + k * 1024); } while (0)
; #define PG8_MMA(ai, bj, At, Bt_) do { __builtin_amdgcn_s_setprio(1); _Pragma("unroll") for (int m = 0; m < 4; ++m) _Pragma("unroll") for (int n = 0; n < 2; ++n) _Pragma("unroll") for (int k = 0; k < 2; ++k) \
;         acc[ai][bj][m][n] = __builtin_amdgcn_mfma_f32_16x16x32_bf16(Bt_[n][k], At[m][k], acc[ai][bj][m][n], 0, 0, 0); __builtin_amdgcn_s_setprio(0); } while (0)
; #define PG8_WAIT_V(n) asm volatile("s_waitcnt vmcnt(" #n ")" ::: "memory")
; #define PG8_WAIT_L(n) asm volatile("s_waitcnt lgkmcnt(" #n ")" ::: "memory")
; #define PG8_BAR __builtin_amdgcn_s_barrier()
; #define PG8_SCHED __builtin_amdgcn_sched_barrier(0)
; __device__ __forceinline__ void gemm_phase(LAS unsigned char* lds, const bf16_t* A, const bf16_t* Bt, int M, int N, int K, const Epi& E) {
;     ...
;             PG8_WAIT_V(8); PG8_WAIT_L(0); PG8_BAR; PG8_MMA(1, 0, At, B0); PG8_MMA(1, 1, At, B1); PG8_BAR; PG8_SCHED;
;             PG8_LDB(B0, 1, 0); PG8_LDB(B1, 1, 1); PG8_SCHED; PG8_LDA(At, 1, 0); PG8_STAGE(PG8_SA(0, 1), a2 + hstep, voffA);
;             PG8_WAIT_V(8); PG8_WAIT_L(0); PG8_BAR; PG8_MMA(0, 0, At, B0); PG8_MMA(0, 1, At, B1); PG8_BAR; PG8_SCHED;
	s_setprio 1
	s_waitcnt lgkmcnt(0)
	v_mfma_f32_16x16x32_bf16 v[62:65], v[144:147], v[176:179], v[62:65]
	v_mfma_f32_16x16x32_bf16 v[58:61], v[152:155], v[176:179], v[58:61]
	v_mfma_f32_16x16x32_bf16 v[54:57], v[144:147], v[202:205], v[54:57]
	v_mfma_f32_16x16x32_bf16 v[50:53], v[152:155], v[202:205], v[50:53]
	v_mfma_f32_16x16x32_bf16 v[38:41], v[144:147], v[210:213], v[38:41]
	v_mfma_f32_16x16x32_bf16 v[34:37], v[152:155], v[210:213], v[34:37]
	v_mfma_f32_16x16x32_bf16 v[22:25], v[144:147], v[218:221], v[22:25]
	v_mfma_f32_16x16x32_bf16 v[18:21], v[152:155], v[218:221], v[18:21]
	v_mfma_f32_16x16x32_bf16 v[62:65], v[148:151], v[180:183], v[62:65]
	v_mfma_f32_16x16x32_bf16 v[58:61], v[156:159], v[180:183], v[58:61]
	v_mfma_f32_16x16x32_bf16 v[54:57], v[148:151], v[206:209], v[54:57]
	v_mfma_f32_16x16x32_bf16 v[50:53], v[156:159], v[206:209], v[50:53]
	v_mfma_f32_16x16x32_bf16 v[38:41], v[148:151], v[214:217], v[38:41]
	v_mfma_f32_16x16x32_bf16 v[34:37], v[156:159], v[214:217], v[34:37]
	v_mfma_f32_16x16x32_bf16 v[22:25], v[148:151], v[222:225], v[22:25]
	v_mfma_f32_16x16x32_bf16 v[18:21], v[156:159], v[222:225], v[18:21]
	v_mfma_f32_16x16x32_bf16 v[46:49], v[160:163], v[176:179], v[46:49]
	v_mfma_f32_16x16x32_bf16 v[42:45], v[168:171], v[176:179], v[42:45]
	v_mfma_f32_16x16x32_bf16 v[30:33], v[160:163], v[202:205], v[30:33]
	v_mfma_f32_16x16x32_bf16 v[26:29], v[168:171], v[202:205], v[26:29]
	v_mfma_f32_16x16x32_bf16 v[14:17], v[160:163], v[210:213], v[14:17]
	v_mfma_f32_16x16x32_bf16 v[10:13], v[168:171], v[210:213], v[10:13]
	v_mfma_f32_16x16x32_bf16 v[6:9], v[160:163], v[218:221], v[6:9]
	v_mfma_f32_16x16x32_bf16 v[2:5], v[168:171], v[218:221], v[2:5]
	v_mfma_f32_16x16x32_bf16 v[46:49], v[164:167], v[180:183], v[46:49]
	v_mfma_f32_16x16x32_bf16 v[42:45], v[172:175], v[180:183], v[42:45]
	v_mfma_f32_16x16x32_bf16 v[30:33], v[164:167], v[206:209], v[30:33]
	v_mfma_f32_16x16x32_bf16 v[26:29], v[172:175], v[206:209], v[26:29]
	v_mfma_f32_16x16x32_bf16 v[14:17], v[164:167], v[214:217], v[14:17]
	v_mfma_f32_16x16x32_bf16 v[10:13], v[172:175], v[214:217], v[10:13]
	v_mfma_f32_16x16x32_bf16 v[6:9], v[164:167], v[222:225], v[6:9]
	v_mfma_f32_16x16x32_bf16 v[2:5], v[172:175], v[222:225], v[2:5]
	s_setprio 0
	s_barrier
	v_add_u32_e32 v156, s54, v141
	v_add_u32_e32 v172, s53, v141
	ds_read_b128 v[144:147], v156
	ds_read_b128 v[148:151], v156 offset:1024
	ds_read_b128 v[152:155], v156 offset:2048
	ds_read_b128 v[156:159], v156 offset:3072
	ds_read_b128 v[160:163], v172
	ds_read_b128 v[164:167], v172 offset:1024
	ds_read_b128 v[168:171], v172 offset:2048
	ds_read_b128 v[172:175], v172 offset:3072
	s_mov_b32 m0, s44
	v_lshl_add_u64 v[230:231], s[26:27], 0, v[134:135]
	ds_read_b128 v[176:179], v143 offset:32768
	ds_read_b128 v[180:183], v143 offset:33792
	ds_read_b128 v[202:205], v143 offset:34816
	ds_read_b128 v[206:209], v143 offset:35840
	ds_read_b128 v[210:213], v143 offset:36864
	ds_read_b128 v[214:217], v143 offset:37888
	ds_read_b128 v[218:221], v143 offset:38912
	ds_read_b128 v[222:225], v143 offset:39936
	global_load_lds_dwordx4 v[230:231], off
	v_lshl_add_u64 v[230:231], s[26:27], 0, v[132:133]
	s_mov_b32 m0, s45
	s_nop 0
	global_load_lds_dwordx4 v[230:231], off
	s_waitcnt vmcnt(8)
	s_waitcnt lgkmcnt(0)
	s_barrier
	s_setprio 1
	s_waitcnt lgkmcnt(0)
	v_mfma_f32_16x16x32_bf16 v[126:129], v[144:147], v[176:179], v[126:129]
	v_mfma_f32_16x16x32_bf16 v[122:125], v[152:155], v[176:179], v[122:125]
	v_mfma_f32_16x16x32_bf16 v[118:121], v[144:147], v[202:205], v[118:121]
	v_mfma_f32_16x16x32_bf16 v[114:117], v[152:155], v[202:205], v[114:117]
	v_mfma_f32_16x16x32_bf16 v[102:105], v[144:147], v[210:213], v[102:105]
	v_mfma_f32_16x16x32_bf16 v[98:101], v[152:155], v[210:213], v[98:101]
	v_mfma_f32_16x16x32_bf16 v[86:89], v[144:147], v[218:221], v[86:89]
	v_mfma_f32_16x16x32_bf16 v[82:85], v[152:155], v[218:221], v[82:85]
	v_mfma_f32_16x16x32_bf16 v[126:129], v[148:151], v[180:183], v[126:129]
	v_mfma_f32_16x16x32_bf16 v[122:125], v[156:159], v[180:183], v[122:125]
	v_mfma_f32_16x16x32_bf16 v[118:121], v[148:151], v[206:209], v[118:121]
	v_mfma_f32_16x16x32_bf16 v[114:117], v[156:159], v[206:209], v[114:117]
	v_mfma_f32_16x16x32_bf16 v[102:105], v[148:151], v[214:217], v[102:105]
	v_mfma_f32_16x16x32_bf16 v[98:101], v[156:159], v[214:217], v[98:101]
	v_mfma_f32_16x16x32_bf16 v[86:89], v[148:151], v[222:225], v[86:89]
	v_mfma_f32_16x16x32_bf16 v[82:85], v[156:159], v[222:225], v[82:85]
	v_mfma_f32_16x16x32_bf16 v[110:113], v[160:163], v[176:179], v[110:113]
	v_mfma_f32_16x16x32_bf16 v[106:109], v[168:171], v[176:179], v[106:109]
	v_mfma_f32_16x16x32_bf16 v[94:97], v[160:163], v[202:205], v[94:97]
	v_mfma_f32_16x16x32_bf16 v[90:93], v[168:171], v[202:205], v[90:93]
	v_mfma_f32_16x16x32_bf16 v[78:81], v[160:163], v[210:213], v[78:81]
	v_mfma_f32_16x16x32_bf16 v[74:77], v[168:171], v[210:213], v[74:77]
	v_mfma_f32_16x16x32_bf16 v[70:73], v[160:163], v[218:221], v[70:73]
	v_mfma_f32_16x16x32_bf16 v[66:69], v[168:171], v[218:221], v[66:69]
	v_mfma_f32_16x16x32_bf16 v[110:113], v[164:167], v[180:183], v[110:113]
	v_mfma_f32_16x16x32_bf16 v[106:109], v[172:175], v[180:183], v[106:109]
	v_mfma_f32_16x16x32_bf16 v[94:97], v[164:167], v[206:209], v[94:97]
	v_mfma_f32_16x16x32_bf16 v[90:93], v[172:175], v[206:209], v[90:93]
	v_mfma_f32_16x16x32_bf16 v[78:81], v[164:167], v[214:217], v[78:81]
	v_mfma_f32_16x16x32_bf16 v[74:77], v[172:175], v[214:217], v[74:77]
	v_mfma_f32_16x16x32_bf16 v[70:73], v[164:167], v[222:225], v[70:73]
	v_mfma_f32_16x16x32_bf16 v[66:69], v[172:175], v[222:225], v[66:69]
	s_setprio 0
	s_barrier
; #define PG8_STAGE(bufoff, gbase, voff) do { _Pragma("unroll") for (int _i = 0; _i < 2; ++_i) \
;         __builtin_amdgcn_global_load_lds((const unsigned*)((const char*)(gbase) + (voff)[_i]), (LAS unsigned*)(lds + (bufoff) + ldsw + _i * 8192), 16, 0, 0); } while (0)
; #define PG8_LDA(dst, b, h) do { _Pragma("unroll") for (int m = 0; m < 4; ++m) _Pragma("unroll") for (int k = 0; k < 2; ++k) dst[m][k] = *(const LAS bf16x8*)(lds + PG8_SA(b, h) + aoff + m * 2048 + k * 1024); } while (0)
; #define PG8_MMA(ai, bj, At, Bt_) do { __builtin_amdgcn_s_setprio(1); _Pragma("unroll") for (int m = 0; m < 4; ++m) _Pragma("unroll") for (int n = 0; n < 2; ++n) _Pragma("unroll") for (int k = 0; k < 2; ++k) \
;         acc[ai][bj][m][n] = __builtin_amdgcn_mfma_f32_16x16x32_bf16(Bt_[n][k], At[m][k], acc[ai][bj][m][n], 0, 0, 0); __builtin_amdgcn_s_setprio(0); } while (0)
; #define PG8_WAIT_V(n) asm volatile("s_waitcnt vmcnt(" #n ")" ::: "memory")
; #define PG8_WAIT_L(n) asm volatile("s_waitcnt lgkmcnt(" #n ")" ::: "memory")
; #define PG8_BAR __builtin_amdgcn_s_barrier()
; #define PG8_SCHED __builtin_amdgcn_sched_barrier(0)
; __device__ __forceinline__ void gemm_phase(LAS unsigned char* lds, const bf16_t* A, const bf16_t* Bt, int M, int N, int K, const Epi& E) {
;     ...
;             PG8_LDA(At, 1, 1); PG8_STAGE(PG8_SB(1, 0), b3, voffB); PG8_STAGE(PG8_SB(1, 1), b3 + hstep, voffB); PG8_STAGE(PG8_SA(1, 0), a3, voffA);
;             PG8_WAIT_V(8); PG8_WAIT_L(0); PG8_BAR; PG8_MMA(1, 0, At, B0); PG8_MMA(1, 1, At, B1); PG8_BAR; PG8_SCHED;
;         }
;         if (wr == 0) PG8_BAR;
	s_mov_b32 m0, s52
	v_lshl_add_u64 v[138:139], v[138:139], 0, s[64:65]
	ds_read_b128 v[176:179], v143 offset:49152
	ds_read_b128 v[180:183], v143 offset:50176
	ds_read_b128 v[202:205], v143 offset:51200
	ds_read_b128 v[206:209], v143 offset:52224
	ds_read_b128 v[210:213], v143 offset:53248
	ds_read_b128 v[214:217], v143 offset:54272
	ds_read_b128 v[218:221], v143 offset:55296
	ds_read_b128 v[222:225], v143 offset:56320
	global_load_lds_dwordx4 v[138:139], off
	v_lshl_add_u64 v[138:139], v[184:185], 0, s[64:65]
	s_mov_b32 m0, s51
	s_nop 0
	global_load_lds_dwordx4 v[138:139], off
	v_lshl_add_u64 v[138:139], s[24:25], 0, v[0:1]
	s_mov_b32 m0, s61
	s_nop 0
	global_load_lds_dwordx4 v[138:139], off
	v_lshl_add_u64 v[138:139], s[24:25], 0, v[130:131]
	s_mov_b32 m0, s59
	s_nop 0
	global_load_lds_dwordx4 v[138:139], off
	v_lshl_add_u64 v[138:139], v[226:227], 0, s[64:65]
	s_mov_b32 m0, s46
	s_nop 0
	global_load_lds_dwordx4 v[138:139], off
	v_lshl_add_u64 v[138:139], v[228:229], 0, s[64:65]
	s_mov_b32 m0, s47
	s_nop 0
	global_load_lds_dwordx4 v[138:139], off
	s_waitcnt vmcnt(8)
	s_waitcnt lgkmcnt(0)
	s_barrier
	s_setprio 1
	s_waitcnt lgkmcnt(0)
	v_mfma_f32_16x16x32_bf16 v[62:65], v[144:147], v[176:179], v[62:65]
	v_mfma_f32_16x16x32_bf16 v[58:61], v[152:155], v[176:179], v[58:61]
	v_mfma_f32_16x16x32_bf16 v[54:57], v[144:147], v[202:205], v[54:57]
	v_mfma_f32_16x16x32_bf16 v[50:53], v[152:155], v[202:205], v[50:53]
	v_mfma_f32_16x16x32_bf16 v[38:41], v[144:147], v[210:213], v[38:41]
	v_mfma_f32_16x16x32_bf16 v[34:37], v[152:155], v[210:213], v[34:37]
	v_mfma_f32_16x16x32_bf16 v[22:25], v[144:147], v[218:221], v[22:25]
	v_mfma_f32_16x16x32_bf16 v[18:21], v[152:155], v[218:221], v[18:21]
	v_mfma_f32_16x16x32_bf16 v[62:65], v[148:151], v[180:183], v[62:65]
	v_mfma_f32_16x16x32_bf16 v[58:61], v[156:159], v[180:183], v[58:61]
	v_mfma_f32_16x16x32_bf16 v[54:57], v[148:151], v[206:209], v[54:57]
	v_mfma_f32_16x16x32_bf16 v[50:53], v[156:159], v[206:209], v[50:53]
	v_mfma_f32_16x16x32_bf16 v[38:41], v[148:151], v[214:217], v[38:41]
	v_mfma_f32_16x16x32_bf16 v[34:37], v[156:159], v[214:217], v[34:37]
	v_mfma_f32_16x16x32_bf16 v[22:25], v[148:151], v[222:225], v[22:25]
	v_mfma_f32_16x16x32_bf16 v[18:21], v[156:159], v[222:225], v[18:21]
	v_mfma_f32_16x16x32_bf16 v[46:49], v[160:163], v[176:179], v[46:49]
	v_mfma_f32_16x16x32_bf16 v[42:45], v[168:171], v[176:179], v[42:45]
	v_mfma_f32_16x16x32_bf16 v[30:33], v[160:163], v[202:205], v[30:33]
	v_mfma_f32_16x16x32_bf16 v[26:29], v[168:171], v[202:205], v[26:29]
	v_mfma_f32_16x16x32_bf16 v[14:17], v[160:163], v[210:213], v[14:17]
	v_mfma_f32_16x16x32_bf16 v[10:13], v[168:171], v[210:213], v[10:13]
	v_mfma_f32_16x16x32_bf16 v[6:9], v[160:163], v[218:221], v[6:9]
	v_mfma_f32_16x16x32_bf16 v[2:5], v[168:171], v[218:221], v[2:5]
	v_mfma_f32_16x16x32_bf16 v[46:49], v[164:167], v[180:183], v[46:49]
	v_mfma_f32_16x16x32_bf16 v[42:45], v[172:175], v[180:183], v[42:45]
	v_mfma_f32_16x16x32_bf16 v[30:33], v[164:167], v[206:209], v[30:33]
	v_mfma_f32_16x16x32_bf16 v[26:29], v[172:175], v[206:209], v[26:29]
	v_mfma_f32_16x16x32_bf16 v[14:17], v[164:167], v[214:217], v[14:17]
	v_mfma_f32_16x16x32_bf16 v[10:13], v[172:175], v[214:217], v[10:13]
	v_mfma_f32_16x16x32_bf16 v[6:9], v[164:167], v[222:225], v[6:9]
	v_mfma_f32_16x16x32_bf16 v[2:5], v[172:175], v[222:225], v[2:5]
	s_setprio 0
	s_barrier
	s_movk_i32 s26, 0x100
	s_andn2_b64 vcc, exec, s[22:23]
	s_mov_b64 s[24:25], -1
	s_mov_b64 s[22:23], 0
	s_cbranch_vccz .LBB0_374
	s_and_b64 vcc, exec, s[4:5]
	s_cbranch_vccz .LBB0_377
	s_barrier

; #define PG8_STAGE(bufoff, gbase, voff) do { _Pragma("unroll") for (int _i = 0; _i < 2; ++_i) \
;         __builtin_amdgcn_global_load_lds((const unsigned*)((const char*)(gbase) + (voff)[_i]), (LAS unsigned*)(lds + (bufoff) + ldsw + _i * 8192), 16, 0, 0); } while (0)
; #define PG8_LDA(dst, b, h) do { _Pragma("unroll") for (int m = 0; m < 4; ++m) _Pragma("unroll") for (int k = 0; k < 2; ++k) dst[m][k] = *(const LAS bf16x8*)(lds + PG8_SA(b, h) + aoff + m * 2048 + k * 1024); } while (0)
; #define PG8_LDB(dst, b, h) do { _Pragma("unroll") for (int n = 0; n < 2; ++n) _Pragma("unroll") for (int k = 0; k < 2; ++k) dst[n][k] = *(const LAS bf16x8*)(lds + PG8_SB(b, h) + boff + n * 2048 + k * 1024); } while (0)
; #define PG8_MMA(ai, bj, At, Bt_) do { __builtin_amdgcn_s_setprio(1); _Pragma("unroll") for (int m = 0; m < 4; ++m) _Pragma("unroll") for (int n = 0; n < 2; ++n) _Pragma("unroll") for (int k = 0; k < 2; ++k) \
;         acc[ai][bj][m][n] = __builtin_amdgcn_mfma_f32_16x16x32_bf16(Bt_[n][k], At[m][k], acc[ai][bj][m][n], 0, 0, 0); __builtin_amdgcn_s_setprio(0); } while (0)
; #define PG8_WAIT_V(n) asm volatile("s_waitcnt vmcnt(" #n ")" ::: "memory")
; #define PG8_WAIT_L(n) asm volatile("s_waitcnt lgkmcnt(" #n ")" ::: "memory")
; #define PG8_BAR __builtin_amdgcn_s_barrier()
; #define PG8_SCHED __builtin_amdgcn_sched_barrier(0)
; __device__ __forceinline__ void gemm_phase(LAS unsigned char* lds, const bf16_t* A, const bf16_t* Bt, int M, int N, int K, const Epi& E) {
;     ...
;             PG8_LDB(B0, 0, 0); PG8_LDB(B1, 0, 1); PG8_SCHED; PG8_LDA(At, 0, 0); PG8_STAGE(PG8_SA(1, 1), a1 + hstep, voffA);
;             PG8_WAIT_V(8); PG8_WAIT_L(0); PG8_BAR; PG8_MMA(0, 0, At, B0); PG8_MMA(0, 1, At, B1); PG8_BAR; PG8_SCHED;
;             PG8_LDA(At, 0, 1); PG8_STAGE(PG8_SB(0, 0), b2, voffB); PG8_STAGE(PG8_SB(0, 1), b2 + hstep, voffB); PG8_STAGE(PG8_SA(0, 0), a2, voffA);
;             PG8_WAIT_V(8); PG8_WAIT_L(0); PG8_BAR; PG8_MMA(1, 0, At, B0); PG8_MMA(1, 1, At, B1); PG8_BAR; PG8_SCHED;
.LBB0_572:
	s_add_u32 s20, s18, 0xfffc0080
	s_addc_u32 s21, s19, -1
	s_add_i32 s43, 0, 0x10000
	s_cmp_eq_u32 s42, 12
	s_cselect_b32 s23, s1, s21
	s_cselect_b32 s22, s3, s20
	s_cselect_b32 s21, s11, s41
	s_cselect_b32 s20, s13, s40
	s_add_i32 s46, 0, 0x14000
	s_waitcnt vmcnt(0)
	v_add_u32_e32 v118, s43, v249
	v_add_u32_e32 v158, s46, v249
	ds_read_b128 v[102:105], v118
	ds_read_b128 v[110:113], v118 offset:1024
	ds_read_b128 v[114:117], v118 offset:2048
	ds_read_b128 v[118:121], v118 offset:3072
	ds_read_b128 v[146:149], v158
	ds_read_b128 v[150:153], v158 offset:1024
	ds_read_b128 v[154:157], v158 offset:2048
	ds_read_b128 v[158:161], v158 offset:3072
	v_lshl_add_u64 v[220:221], s[18:19], 0, v[208:209]
	s_add_i32 m0, s27, 0xc000
	ds_read_b128 v[162:165], v240
	ds_read_b128 v[166:169], v240 offset:1024
	ds_read_b128 v[170:173], v240 offset:2048
	ds_read_b128 v[174:177], v240 offset:3072
	ds_read_b128 v[178:181], v240 offset:4096
	ds_read_b128 v[182:185], v240 offset:5120
	ds_read_b128 v[212:215], v240 offset:6144
	ds_read_b128 v[216:219], v240 offset:7168
	global_load_lds_dwordx4 v[220:221], off
	v_lshl_add_u64 v[220:221], s[18:19], 0, v[210:211]
	s_add_i32 m0, s27, 0xe000
	s_nop 0
	global_load_lds_dwordx4 v[220:221], off
	s_waitcnt vmcnt(8)
	s_waitcnt lgkmcnt(0)
	s_barrier
	s_setprio 1
	s_waitcnt lgkmcnt(0)
	v_mfma_f32_16x16x32_bf16 v[142:145], v[102:105], v[162:165], v[142:145]
	v_mfma_f32_16x16x32_bf16 v[138:141], v[114:117], v[162:165], v[138:141]
	v_mfma_f32_16x16x32_bf16 v[126:129], v[102:105], v[170:173], v[126:129]
	v_mfma_f32_16x16x32_bf16 v[122:125], v[114:117], v[170:173], v[122:125]
	v_mfma_f32_16x16x32_bf16 v[94:97], v[102:105], v[178:181], v[94:97]
	v_mfma_f32_16x16x32_bf16 v[90:93], v[114:117], v[178:181], v[90:93]
	v_mfma_f32_16x16x32_bf16 v[78:81], v[102:105], v[212:215], v[78:81]
	v_mfma_f32_16x16x32_bf16 v[74:77], v[114:117], v[212:215], v[74:77]
	v_mfma_f32_16x16x32_bf16 v[142:145], v[110:113], v[166:169], v[142:145]
	v_mfma_f32_16x16x32_bf16 v[138:141], v[118:121], v[166:169], v[138:141]
	v_mfma_f32_16x16x32_bf16 v[126:129], v[110:113], v[174:177], v[126:129]
	v_mfma_f32_16x16x32_bf16 v[122:125], v[118:121], v[174:177], v[122:125]
	v_mfma_f32_16x16x32_bf16 v[94:97], v[110:113], v[182:185], v[94:97]
	v_mfma_f32_16x16x32_bf16 v[90:93], v[118:121], v[182:185], v[90:93]
	v_mfma_f32_16x16x32_bf16 v[78:81], v[110:113], v[216:219], v[78:81]
	v_mfma_f32_16x16x32_bf16 v[74:77], v[118:121], v[216:219], v[74:77]
	v_mfma_f32_16x16x32_bf16 v[134:137], v[146:149], v[162:165], v[134:137]
	v_mfma_f32_16x16x32_bf16 v[130:133], v[154:157], v[162:165], v[130:133]
	v_mfma_f32_16x16x32_bf16 v[106:109], v[146:149], v[170:173], v[106:109]
	v_mfma_f32_16x16x32_bf16 v[98:101], v[154:157], v[170:173], v[98:101]
	v_mfma_f32_16x16x32_bf16 v[86:89], v[146:149], v[178:181], v[86:89]
	v_mfma_f32_16x16x32_bf16 v[82:85], v[154:157], v[178:181], v[82:85]
	v_mfma_f32_16x16x32_bf16 v[70:73], v[146:149], v[212:215], v[70:73]
	v_mfma_f32_16x16x32_bf16 v[66:69], v[154:157], v[212:215], v[66:69]
	v_mfma_f32_16x16x32_bf16 v[134:137], v[150:153], v[166:169], v[134:137]
	v_mfma_f32_16x16x32_bf16 v[130:133], v[158:161], v[166:169], v[130:133]
	v_mfma_f32_16x16x32_bf16 v[106:109], v[150:153], v[174:177], v[106:109]
	v_mfma_f32_16x16x32_bf16 v[98:101], v[158:161], v[174:177], v[98:101]
	v_mfma_f32_16x16x32_bf16 v[86:89], v[150:153], v[182:185], v[86:89]
	v_mfma_f32_16x16x32_bf16 v[82:85], v[158:161], v[182:185], v[82:85]
	v_mfma_f32_16x16x32_bf16 v[70:73], v[150:153], v[216:219], v[70:73]
	v_mfma_f32_16x16x32_bf16 v[66:69], v[158:161], v[216:219], v[66:69]
	s_setprio 0
	s_barrier
	s_add_i32 s43, s43, s26
	v_lshl_add_u64 v[220:221], s[20:21], 0, v[0:1]
	s_mov_b32 m0, s43
	ds_read_b128 v[162:165], v240 offset:16384
	ds_read_b128 v[166:169], v240 offset:17408
	ds_read_b128 v[170:173], v240 offset:18432
	ds_read_b128 v[174:177], v240 offset:19456
	ds_read_b128 v[178:181], v240 offset:20480
	ds_read_b128 v[182:185], v240 offset:21504
	ds_read_b128 v[212:215], v240 offset:22528
	ds_read_b128 v[216:219], v240 offset:23552
	global_load_lds_dwordx4 v[220:221], off
	s_add_i32 m0, s43, 0x2000
	s_add_u32 s44, s20, 0x40000
	v_lshl_add_u64 v[222:223], s[20:21], 0, v[206:207]
	s_addc_u32 s45, s21, 0
	s_add_i32 s43, s46, s26
	global_load_lds_dwordx4 v[222:223], off
	v_lshl_add_u64 v[224:225], s[44:45], 0, v[0:1]
	s_mov_b32 m0, s43
	v_lshl_add_u64 v[226:227], s[22:23], 0, v[204:205]
	global_load_lds_dwordx4 v[224:225], off
	v_lshl_add_u64 v[224:225], s[44:45], 0, v[206:207]
	s_add_i32 m0, s43, 0x2000
	s_nop 0
	global_load_lds_dwordx4 v[224:225], off
	v_lshl_add_u64 v[224:225], s[22:23], 0, v[202:203]
	s_mov_b32 m0, s27
	s_nop 0
	global_load_lds_dwordx4 v[224:225], off
	s_mov_b32 m0, s28
	s_nop 0
	global_load_lds_dwordx4 v[226:227], off
	s_waitcnt vmcnt(8)
	s_waitcnt lgkmcnt(0)
	s_barrier
; #define PG8_STAGE(bufoff, gbase, voff) do { _Pragma("unroll") for (int _i = 0; _i < 2; ++_i) \
;         __builtin_amdgcn_global_load_lds((const unsigned*)((const char*)(gbase) + (voff)[_i]), (LAS unsigned*)(lds + (bufoff) + ldsw + _i * 8192), 16, 0, 0); } while (0)
; #define PG8_LDA(dst, b, h) do { _Pragma("unroll") for (int m = 0; m < 4; ++m) _Pragma("unroll") for (int k = 0; k < 2; ++k) dst[m][k] = *(const LAS bf16x8*)(lds + PG8_SA(b, h) + aoff + m * 2048 + k * 1024); } while (0)
; #define PG8_LDB(dst, b, h) do { _Pragma("unroll") for (int n = 0; n < 2; ++n) _Pragma("unroll") for (int k = 0; k < 2; ++k) dst[n][k] = *(const LAS bf16x8*)(lds + PG8_SB(b, h) + boff + n * 2048 + k * 1024); } while (0)
; #define PG8_MMA(ai, bj, At, Bt_) do { __builtin_amdgcn_s_setprio(1); _Pragma("unroll") for (int m = 0; m < 4; ++m) _Pragma("unroll") for (int n = 0; n < 2; ++n) _Pragma("unroll") for (int k = 0; k < 2; ++k) \
;         acc[ai][bj][m][n] = __builtin_amdgcn_mfma_f32_16x16x32_bf16(Bt_[n][k], At[m][k], acc[ai][bj][m][n], 0, 0, 0); __builtin_amdgcn_s_setprio(0); } while (0)
; #define PG8_WAIT_V(n) asm volatile("s_waitcnt vmcnt(" #n ")" ::: "memory")
; #define PG8_WAIT_L(n) asm volatile("s_waitcnt lgkmcnt(" #n ")" ::: "memory")
; #define PG8_BAR __builtin_amdgcn_s_barrier()
; #define PG8_SCHED __builtin_amdgcn_sched_barrier(0)
; __device__ __forceinline__ void gemm_phase(LAS unsigned char* lds, const bf16_t* A, const bf16_t* Bt, int M, int N, int K, const Epi& E) {
;     ...
;             PG8_WAIT_V(8); PG8_WAIT_L(0); PG8_BAR; PG8_MMA(1, 0, At, B0); PG8_MMA(1, 1, At, B1); PG8_BAR; PG8_SCHED;
;             PG8_LDB(B0, 1, 0); PG8_LDB(B1, 1, 1); PG8_SCHED; PG8_LDA(At, 1, 0); PG8_STAGE(PG8_SA(0, 1), a2 + hstep, voffA);
;             PG8_WAIT_V(8); PG8_WAIT_L(0); PG8_BAR; PG8_MMA(0, 0, At, B0); PG8_MMA(0, 1, At, B1); PG8_BAR; PG8_SCHED;
	s_setprio 1
	s_waitcnt lgkmcnt(0)
	v_mfma_f32_16x16x32_bf16 v[62:65], v[102:105], v[162:165], v[62:65]
	v_mfma_f32_16x16x32_bf16 v[58:61], v[114:117], v[162:165], v[58:61]
	v_mfma_f32_16x16x32_bf16 v[46:49], v[102:105], v[170:173], v[46:49]
	v_mfma_f32_16x16x32_bf16 v[42:45], v[114:117], v[170:173], v[42:45]
	v_mfma_f32_16x16x32_bf16 v[30:33], v[102:105], v[178:181], v[30:33]
	v_mfma_f32_16x16x32_bf16 v[26:29], v[114:117], v[178:181], v[26:29]
	v_mfma_f32_16x16x32_bf16 v[14:17], v[102:105], v[212:215], v[14:17]
	v_mfma_f32_16x16x32_bf16 v[10:13], v[114:117], v[212:215], v[10:13]
	v_mfma_f32_16x16x32_bf16 v[62:65], v[110:113], v[166:169], v[62:65]
	v_mfma_f32_16x16x32_bf16 v[58:61], v[118:121], v[166:169], v[58:61]
	v_mfma_f32_16x16x32_bf16 v[46:49], v[110:113], v[174:177], v[46:49]
	v_mfma_f32_16x16x32_bf16 v[42:45], v[118:121], v[174:177], v[42:45]
	v_mfma_f32_16x16x32_bf16 v[30:33], v[110:113], v[182:185], v[30:33]
	v_mfma_f32_16x16x32_bf16 v[26:29], v[118:121], v[182:185], v[26:29]
	v_mfma_f32_16x16x32_bf16 v[14:17], v[110:113], v[216:219], v[14:17]
	v_mfma_f32_16x16x32_bf16 v[10:13], v[118:121], v[216:219], v[10:13]
	v_mfma_f32_16x16x32_bf16 v[54:57], v[146:149], v[162:165], v[54:57]
	v_mfma_f32_16x16x32_bf16 v[50:53], v[154:157], v[162:165], v[50:53]
	v_mfma_f32_16x16x32_bf16 v[38:41], v[146:149], v[170:173], v[38:41]
	v_mfma_f32_16x16x32_bf16 v[34:37], v[154:157], v[170:173], v[34:37]
	v_mfma_f32_16x16x32_bf16 v[22:25], v[146:149], v[178:181], v[22:25]
	v_mfma_f32_16x16x32_bf16 v[18:21], v[154:157], v[178:181], v[18:21]
	v_mfma_f32_16x16x32_bf16 v[6:9], v[146:149], v[212:215], v[6:9]
	v_mfma_f32_16x16x32_bf16 v[2:5], v[154:157], v[212:215], v[2:5]
	v_mfma_f32_16x16x32_bf16 v[54:57], v[150:153], v[166:169], v[54:57]
	v_mfma_f32_16x16x32_bf16 v[50:53], v[158:161], v[166:169], v[50:53]
	v_mfma_f32_16x16x32_bf16 v[38:41], v[150:153], v[174:177], v[38:41]
	v_mfma_f32_16x16x32_bf16 v[34:37], v[158:161], v[174:177], v[34:37]
	v_mfma_f32_16x16x32_bf16 v[22:25], v[150:153], v[182:185], v[22:25]
	v_mfma_f32_16x16x32_bf16 v[18:21], v[158:161], v[182:185], v[18:21]
	v_mfma_f32_16x16x32_bf16 v[6:9], v[150:153], v[216:219], v[6:9]
	v_mfma_f32_16x16x32_bf16 v[2:5], v[158:161], v[216:219], v[2:5]
	s_setprio 0
	s_barrier
	s_add_i32 s43, 0, 0x18000
	s_add_i32 s44, 0, 0x1c000
	v_add_u32_e32 v118, s43, v249
	v_add_u32_e32 v158, s44, v249
	ds_read_b128 v[102:105], v118
	ds_read_b128 v[110:113], v118 offset:1024
	ds_read_b128 v[114:117], v118 offset:2048
	ds_read_b128 v[118:121], v118 offset:3072
	ds_read_b128 v[146:149], v158
	ds_read_b128 v[150:153], v158 offset:1024
	ds_read_b128 v[154:157], v158 offset:2048
	ds_read_b128 v[158:161], v158 offset:3072
	s_add_u32 s22, s22, 0x40000
	s_addc_u32 s23, s23, 0
	s_mov_b32 m0, s29
	v_lshl_add_u64 v[228:229], s[22:23], 0, v[202:203]
	ds_read_b128 v[162:165], v240 offset:32768
	ds_read_b128 v[166:169], v240 offset:33792
	ds_read_b128 v[170:173], v240 offset:34816
	ds_read_b128 v[174:177], v240 offset:35840
	ds_read_b128 v[178:181], v240 offset:36864
	ds_read_b128 v[182:185], v240 offset:37888
	ds_read_b128 v[212:215], v240 offset:38912
	ds_read_b128 v[216:219], v240 offset:39936
	global_load_lds_dwordx4 v[228:229], off
	v_lshl_add_u64 v[228:229], s[22:23], 0, v[204:205]
	s_mov_b32 m0, s33
	s_nop 0
	global_load_lds_dwordx4 v[228:229], off
	s_waitcnt vmcnt(8)
	s_waitcnt lgkmcnt(0)
	s_barrier
	s_setprio 1
	s_waitcnt lgkmcnt(0)
	v_mfma_f32_16x16x32_bf16 v[142:145], v[102:105], v[162:165], v[142:145]
	v_mfma_f32_16x16x32_bf16 v[138:141], v[114:117], v[162:165], v[138:141]
	v_mfma_f32_16x16x32_bf16 v[126:129], v[102:105], v[170:173], v[126:129]
	v_mfma_f32_16x16x32_bf16 v[122:125], v[114:117], v[170:173], v[122:125]
	v_mfma_f32_16x16x32_bf16 v[94:97], v[102:105], v[178:181], v[94:97]
	v_mfma_f32_16x16x32_bf16 v[90:93], v[114:117], v[178:181], v[90:93]
	v_mfma_f32_16x16x32_bf16 v[78:81], v[102:105], v[212:215], v[78:81]
	v_mfma_f32_16x16x32_bf16 v[74:77], v[114:117], v[212:215], v[74:77]
	v_mfma_f32_16x16x32_bf16 v[142:145], v[110:113], v[166:169], v[142:145]
	v_mfma_f32_16x16x32_bf16 v[138:141], v[118:121], v[166:169], v[138:141]
	v_mfma_f32_16x16x32_bf16 v[126:129], v[110:113], v[174:177], v[126:129]
	v_mfma_f32_16x16x32_bf16 v[122:125], v[118:121], v[174:177], v[122:125]
	v_mfma_f32_16x16x32_bf16 v[94:97], v[110:113], v[182:185], v[94:97]
	v_mfma_f32_16x16x32_bf16 v[90:93], v[118:121], v[182:185], v[90:93]
	v_mfma_f32_16x16x32_bf16 v[78:81], v[110:113], v[216:219], v[78:81]
	v_mfma_f32_16x16x32_bf16 v[74:77], v[118:121], v[216:219], v[74:77]
	v_mfma_f32_16x16x32_bf16 v[134:137], v[146:149], v[162:165], v[134:137]
	v_mfma_f32_16x16x32_bf16 v[130:133], v[154:157], v[162:165], v[130:133]
	v_mfma_f32_16x16x32_bf16 v[106:109], v[146:149], v[170:173], v[106:109]
	v_mfma_f32_16x16x32_bf16 v[98:101], v[154:157], v[170:173], v[98:101]
	v_mfma_f32_16x16x32_bf16 v[86:89], v[146:149], v[178:181], v[86:89]
	v_mfma_f32_16x16x32_bf16 v[82:85], v[154:157], v[178:181], v[82:85]
	v_mfma_f32_16x16x32_bf16 v[70:73], v[146:149], v[212:215], v[70:73]
	v_mfma_f32_16x16x32_bf16 v[66:69], v[154:157], v[212:215], v[66:69]
	v_mfma_f32_16x16x32_bf16 v[134:137], v[150:153], v[166:169], v[134:137]
	v_mfma_f32_16x16x32_bf16 v[130:133], v[158:161], v[166:169], v[130:133]
	v_mfma_f32_16x16x32_bf16 v[106:109], v[150:153], v[174:177], v[106:109]
	v_mfma_f32_16x16x32_bf16 v[98:101], v[158:161], v[174:177], v[98:101]
	v_mfma_f32_16x16x32_bf16 v[86:89], v[150:153], v[182:185], v[86:89]
	v_mfma_f32_16x16x32_bf16 v[82:85], v[158:161], v[182:185], v[82:85]
	v_mfma_f32_16x16x32_bf16 v[70:73], v[150:153], v[216:219], v[70:73]
	v_mfma_f32_16x16x32_bf16 v[66:69], v[158:161], v[216:219], v[66:69]
	s_setprio 0
	s_barrier
; #define PG8_STAGE(bufoff, gbase, voff) do { _Pragma("unroll") for (int _i = 0; _i < 2; ++_i) \
;         __builtin_amdgcn_global_load_lds((const unsigned*)((const char*)(gbase) + (voff)[_i]), (LAS unsigned*)(lds + (bufoff) + ldsw + _i * 8192), 16, 0, 0); } while (0)
; #define PG8_LDA(dst, b, h) do { _Pragma("unroll") for (int m = 0; m < 4; ++m) _Pragma("unroll") for (int k = 0; k < 2; ++k) dst[m][k] = *(const LAS bf16x8*)(lds + PG8_SA(b, h) + aoff + m * 2048 + k * 1024); } while (0)
; #define PG8_MMA(ai, bj, At, Bt_) do { __builtin_amdgcn_s_setprio(1); _Pragma("unroll") for (int m = 0; m < 4; ++m) _Pragma("unroll") for (int n = 0; n < 2; ++n) _Pragma("unroll") for (int k = 0; k < 2; ++k) \
;         acc[ai][bj][m][n] = __builtin_amdgcn_mfma_f32_16x16x32_bf16(Bt_[n][k], At[m][k], acc[ai][bj][m][n], 0, 0, 0); __builtin_amdgcn_s_setprio(0); } while (0)
; #define PG8_WAIT_V(n) asm volatile("s_waitcnt vmcnt(" #n ")" ::: "memory")
; #define PG8_WAIT_L(n) asm volatile("s_waitcnt lgkmcnt(" #n ")" ::: "memory")
; #define PG8_BAR __builtin_amdgcn_s_barrier()
; #define PG8_SCHED __builtin_amdgcn_sched_barrier(0)
; __device__ __forceinline__ void gemm_phase(LAS unsigned char* lds, const bf16_t* A, const bf16_t* Bt, int M, int N, int K, const Epi& E) {
;     ...
;             PG8_LDA(At, 1, 1); PG8_STAGE(PG8_SB(1, 0), b3, voffB); PG8_STAGE(PG8_SB(1, 1), b3 + hstep, voffB); PG8_STAGE(PG8_SA(1, 0), a3, voffA);
;             PG8_WAIT_V(8); PG8_WAIT_L(0); PG8_BAR; PG8_MMA(1, 0, At, B0); PG8_MMA(1, 1, At, B1); PG8_BAR; PG8_SCHED;
;         }
;         if (wr == 0) PG8_BAR;
	s_add_i32 s22, s43, s26
	v_lshl_add_u64 v[220:221], v[220:221], 0, s[48:49]
	s_mov_b32 m0, s22
	ds_read_b128 v[162:165], v240 offset:49152
	ds_read_b128 v[166:169], v240 offset:50176
	ds_read_b128 v[170:173], v240 offset:51200
	ds_read_b128 v[174:177], v240 offset:52224
	ds_read_b128 v[178:181], v240 offset:53248
	ds_read_b128 v[182:185], v240 offset:54272
	ds_read_b128 v[212:215], v240 offset:55296
	ds_read_b128 v[216:219], v240 offset:56320
	global_load_lds_dwordx4 v[220:221], off
	s_add_i32 m0, s22, 0x2000
	s_add_u32 s20, s20, 0x40080
	v_lshl_add_u64 v[220:221], v[222:223], 0, s[48:49]
	s_addc_u32 s21, s21, 0
	s_add_i32 s22, s44, s26
	global_load_lds_dwordx4 v[220:221], off
	v_lshl_add_u64 v[220:221], s[20:21], 0, v[0:1]
	s_mov_b32 m0, s22
	s_nop 0
	global_load_lds_dwordx4 v[220:221], off
	v_lshl_add_u64 v[220:221], s[20:21], 0, v[206:207]
	s_add_i32 m0, s22, 0x2000
	s_nop 0
	global_load_lds_dwordx4 v[220:221], off
	v_lshl_add_u64 v[220:221], v[224:225], 0, s[48:49]
	s_mov_b32 m0, s35
	s_nop 0
	global_load_lds_dwordx4 v[220:221], off
	v_lshl_add_u64 v[220:221], v[226:227], 0, s[48:49]
	s_mov_b32 m0, s38
	s_nop 0
	global_load_lds_dwordx4 v[220:221], off
	s_waitcnt vmcnt(8)
	s_waitcnt lgkmcnt(0)
	s_barrier
	s_setprio 1
	s_waitcnt lgkmcnt(0)
	v_mfma_f32_16x16x32_bf16 v[62:65], v[102:105], v[162:165], v[62:65]
	v_mfma_f32_16x16x32_bf16 v[58:61], v[114:117], v[162:165], v[58:61]
	v_mfma_f32_16x16x32_bf16 v[46:49], v[102:105], v[170:173], v[46:49]
	v_mfma_f32_16x16x32_bf16 v[42:45], v[114:117], v[170:173], v[42:45]
	v_mfma_f32_16x16x32_bf16 v[30:33], v[102:105], v[178:181], v[30:33]
	v_mfma_f32_16x16x32_bf16 v[26:29], v[114:117], v[178:181], v[26:29]
	v_mfma_f32_16x16x32_bf16 v[14:17], v[102:105], v[212:215], v[14:17]
	v_mfma_f32_16x16x32_bf16 v[10:13], v[114:117], v[212:215], v[10:13]
	v_mfma_f32_16x16x32_bf16 v[62:65], v[110:113], v[166:169], v[62:65]
	v_mfma_f32_16x16x32_bf16 v[58:61], v[118:121], v[166:169], v[58:61]
	v_mfma_f32_16x16x32_bf16 v[46:49], v[110:113], v[174:177], v[46:49]
	v_mfma_f32_16x16x32_bf16 v[42:45], v[118:121], v[174:177], v[42:45]
	v_mfma_f32_16x16x32_bf16 v[30:33], v[110:113], v[182:185], v[30:33]
	v_mfma_f32_16x16x32_bf16 v[26:29], v[118:121], v[182:185], v[26:29]
	v_mfma_f32_16x16x32_bf16 v[14:17], v[110:113], v[216:219], v[14:17]
	v_mfma_f32_16x16x32_bf16 v[10:13], v[118:121], v[216:219], v[10:13]
	v_mfma_f32_16x16x32_bf16 v[54:57], v[146:149], v[162:165], v[54:57]
	v_mfma_f32_16x16x32_bf16 v[50:53], v[154:157], v[162:165], v[50:53]
	v_mfma_f32_16x16x32_bf16 v[38:41], v[146:149], v[170:173], v[38:41]
	v_mfma_f32_16x16x32_bf16 v[34:37], v[154:157], v[170:173], v[34:37]
	v_mfma_f32_16x16x32_bf16 v[22:25], v[146:149], v[178:181], v[22:25]
	v_mfma_f32_16x16x32_bf16 v[18:21], v[154:157], v[178:181], v[18:21]
	v_mfma_f32_16x16x32_bf16 v[6:9], v[146:149], v[212:215], v[6:9]
	v_mfma_f32_16x16x32_bf16 v[2:5], v[154:157], v[212:215], v[2:5]
	v_mfma_f32_16x16x32_bf16 v[54:57], v[150:153], v[166:169], v[54:57]
	v_mfma_f32_16x16x32_bf16 v[50:53], v[158:161], v[166:169], v[50:53]
	v_mfma_f32_16x16x32_bf16 v[38:41], v[150:153], v[174:177], v[38:41]
	v_mfma_f32_16x16x32_bf16 v[34:37], v[158:161], v[174:177], v[34:37]
	v_mfma_f32_16x16x32_bf16 v[22:25], v[150:153], v[182:185], v[22:25]
	v_mfma_f32_16x16x32_bf16 v[18:21], v[158:161], v[182:185], v[18:21]
	v_mfma_f32_16x16x32_bf16 v[6:9], v[150:153], v[216:219], v[6:9]
	v_mfma_f32_16x16x32_bf16 v[2:5], v[158:161], v[216:219], v[2:5]
	s_setprio 0
	s_barrier
	s_add_i32 s42, s42, 2
	s_add_u32 s18, s18, 0x100
	s_addc_u32 s19, s19, 0
	s_add_u32 s40, s40, 0x100
	s_addc_u32 s41, s41, 0
	s_cmp_gt_u32 s42, 13
	s_cbranch_scc0 .LBB0_572
	s_and_b64 vcc, exec, s[6:7]
	s_cbranch_vccz .LBB0_575
	s_barrier

; #define PG8_STAGE(bufoff, gbase, voff) do { _Pragma("unroll") for (int _i = 0; _i < 2; ++_i) \
;         __builtin_amdgcn_global_load_lds((const unsigned*)((const char*)(gbase) + (voff)[_i]), (LAS unsigned*)(lds + (bufoff) + ldsw + _i * 8192), 16, 0, 0); } while (0)
; #define PG8_LDA(dst, b, h) do { _Pragma("unroll") for (int m = 0; m < 4; ++m) _Pragma("unroll") for (int k = 0; k < 2; ++k) dst[m][k] = *(const LAS bf16x8*)(lds + PG8_SA(b, h) + aoff + m * 2048 + k * 1024); } while (0)
; #define PG8_LDB(dst, b, h) do { _Pragma("unroll") for (int n = 0; n < 2; ++n) _Pragma("unroll") for (int k = 0; k < 2; ++k) dst[n][k] = *(const LAS bf16x8*)(lds + PG8_SB(b, h) + boff + n * 2048 + k * 1024); } while (0)
; #define PG8_MMA(ai, bj, At, Bt_) do { __builtin_amdgcn_s_setprio(1); _Pragma("unroll") for (int m = 0; m < 4; ++m) _Pragma("unroll") for (int n = 0; n < 2; ++n) _Pragma("unroll") for (int k = 0; k < 2; ++k) \
;         acc[ai][bj][m][n] = __builtin_amdgcn_mfma_f32_16x16x32_bf16(Bt_[n][k], At[m][k], acc[ai][bj][m][n], 0, 0, 0); __builtin_amdgcn_s_setprio(0); } while (0)
; #define PG8_WAIT_V(n) asm volatile("s_waitcnt vmcnt(" #n ")" ::: "memory")
; #define PG8_WAIT_L(n) asm volatile("s_waitcnt lgkmcnt(" #n ")" ::: "memory")
; #define PG8_BAR __builtin_amdgcn_s_barrier()
; #define PG8_SCHED __builtin_amdgcn_sched_barrier(0)
; __device__ __forceinline__ void gemm_phase(LAS unsigned char* lds, const bf16_t* A, const bf16_t* Bt, int M, int N, int K, const Epi& E) {
;     ...
;             PG8_LDB(B0, 0, 0); PG8_LDB(B1, 0, 1); PG8_SCHED; PG8_LDA(At, 0, 0); PG8_STAGE(PG8_SA(1, 1), a1 + hstep, voffA);
;             PG8_WAIT_V(8); PG8_WAIT_L(0); PG8_BAR; PG8_MMA(0, 0, At, B0); PG8_MMA(0, 1, At, B1); PG8_BAR; PG8_SCHED;
;             PG8_LDA(At, 0, 1); PG8_STAGE(PG8_SB(0, 0), b2, voffB); PG8_STAGE(PG8_SB(0, 1), b2 + hstep, voffB); PG8_STAGE(PG8_SA(0, 0), a2, voffA);
;             PG8_WAIT_V(8); PG8_WAIT_L(0); PG8_BAR; PG8_MMA(1, 0, At, B0); PG8_MMA(1, 1, At, B1); PG8_BAR; PG8_SCHED;
.LBB0_735:
	s_add_u32 s20, s18, 0xfffc0080
	s_addc_u32 s21, s19, -1
	s_add_i32 s40, 0, 0x10000
	s_cmp_eq_u32 s39, 12
	s_cselect_b32 s23, s11, s21
	s_cselect_b32 s22, s13, s20
	v_add_u32_e32 v142, s40, v145
	s_cselect_b32 s21, s9, s38
	s_cselect_b32 s20, s36, s37
	s_add_i32 s42, 0, 0x14000
	ds_read_b128 v[148:151], v142
	ds_read_b128 v[152:155], v142 offset:1024
	ds_read_b128 v[156:159], v142 offset:2048
	ds_read_b128 v[160:163], v142 offset:3072
	v_add_u32_e32 v142, s42, v145
	ds_read_b128 v[164:167], v142
	ds_read_b128 v[168:171], v142 offset:1024
	ds_read_b128 v[172:175], v142 offset:2048
	ds_read_b128 v[176:179], v142 offset:3072
	v_lshl_add_u64 v[142:143], s[18:19], 0, v[138:139]
	s_add_i32 m0, s27, 0xc000
	ds_read_b128 v[180:183], v147
	ds_read_b128 v[202:205], v147 offset:1024
	ds_read_b128 v[206:209], v147 offset:2048
	ds_read_b128 v[210:213], v147 offset:3072
	ds_read_b128 v[214:217], v147 offset:4096
	ds_read_b128 v[218:221], v147 offset:5120
	ds_read_b128 v[222:225], v147 offset:6144
	ds_read_b128 v[226:229], v147 offset:7168
	global_load_lds_dwordx4 v[142:143], off
	v_lshl_add_u64 v[142:143], s[18:19], 0, v[140:141]
	s_add_i32 m0, s27, 0xe000
	s_nop 0
	global_load_lds_dwordx4 v[142:143], off
	s_waitcnt vmcnt(8)
	s_waitcnt lgkmcnt(0)
	s_barrier
	s_setprio 1
	s_waitcnt lgkmcnt(0)
	v_mfma_f32_16x16x32_bf16 v[126:129], v[148:151], v[180:183], v[126:129]
	v_mfma_f32_16x16x32_bf16 v[122:125], v[156:159], v[180:183], v[122:125]
	v_mfma_f32_16x16x32_bf16 v[118:121], v[148:151], v[206:209], v[118:121]
	v_mfma_f32_16x16x32_bf16 v[114:117], v[156:159], v[206:209], v[114:117]
	v_mfma_f32_16x16x32_bf16 v[102:105], v[148:151], v[214:217], v[102:105]
	v_mfma_f32_16x16x32_bf16 v[98:101], v[156:159], v[214:217], v[98:101]
	v_mfma_f32_16x16x32_bf16 v[86:89], v[148:151], v[222:225], v[86:89]
	v_mfma_f32_16x16x32_bf16 v[82:85], v[156:159], v[222:225], v[82:85]
	v_mfma_f32_16x16x32_bf16 v[126:129], v[152:155], v[202:205], v[126:129]
	v_mfma_f32_16x16x32_bf16 v[122:125], v[160:163], v[202:205], v[122:125]
	v_mfma_f32_16x16x32_bf16 v[118:121], v[152:155], v[210:213], v[118:121]
	v_mfma_f32_16x16x32_bf16 v[114:117], v[160:163], v[210:213], v[114:117]
	v_mfma_f32_16x16x32_bf16 v[102:105], v[152:155], v[218:221], v[102:105]
	v_mfma_f32_16x16x32_bf16 v[98:101], v[160:163], v[218:221], v[98:101]
	v_mfma_f32_16x16x32_bf16 v[86:89], v[152:155], v[226:229], v[86:89]
	v_mfma_f32_16x16x32_bf16 v[82:85], v[160:163], v[226:229], v[82:85]
	v_mfma_f32_16x16x32_bf16 v[110:113], v[164:167], v[180:183], v[110:113]
	v_mfma_f32_16x16x32_bf16 v[106:109], v[172:175], v[180:183], v[106:109]
	v_mfma_f32_16x16x32_bf16 v[94:97], v[164:167], v[206:209], v[94:97]
	v_mfma_f32_16x16x32_bf16 v[90:93], v[172:175], v[206:209], v[90:93]
	v_mfma_f32_16x16x32_bf16 v[78:81], v[164:167], v[214:217], v[78:81]
	v_mfma_f32_16x16x32_bf16 v[74:77], v[172:175], v[214:217], v[74:77]
	v_mfma_f32_16x16x32_bf16 v[70:73], v[164:167], v[222:225], v[70:73]
	v_mfma_f32_16x16x32_bf16 v[66:69], v[172:175], v[222:225], v[66:69]
	v_mfma_f32_16x16x32_bf16 v[110:113], v[168:171], v[202:205], v[110:113]
	v_mfma_f32_16x16x32_bf16 v[106:109], v[176:179], v[202:205], v[106:109]
	v_mfma_f32_16x16x32_bf16 v[94:97], v[168:171], v[210:213], v[94:97]
	v_mfma_f32_16x16x32_bf16 v[90:93], v[176:179], v[210:213], v[90:93]
	v_mfma_f32_16x16x32_bf16 v[78:81], v[168:171], v[218:221], v[78:81]
	v_mfma_f32_16x16x32_bf16 v[74:77], v[176:179], v[218:221], v[74:77]
	v_mfma_f32_16x16x32_bf16 v[70:73], v[168:171], v[226:229], v[70:73]
	v_mfma_f32_16x16x32_bf16 v[66:69], v[176:179], v[226:229], v[66:69]
	s_setprio 0
	s_barrier
	s_add_i32 s40, s40, s26
	v_lshl_add_u64 v[142:143], s[20:21], 0, v[0:1]
	s_mov_b32 m0, s40
	ds_read_b128 v[180:183], v147 offset:16384
	ds_read_b128 v[202:205], v147 offset:17408
	ds_read_b128 v[206:209], v147 offset:18432
	ds_read_b128 v[210:213], v147 offset:19456
	ds_read_b128 v[214:217], v147 offset:20480
	ds_read_b128 v[218:221], v147 offset:21504
	ds_read_b128 v[222:225], v147 offset:22528
	ds_read_b128 v[226:229], v147 offset:23552
	global_load_lds_dwordx4 v[142:143], off
	s_add_i32 m0, s40, 0x2000
	s_add_u32 s40, s20, 0x40000
	v_lshl_add_u64 v[184:185], s[20:21], 0, v[134:135]
	s_addc_u32 s41, s21, 0
	s_add_i32 s42, s42, s26
	global_load_lds_dwordx4 v[184:185], off
	v_lshl_add_u64 v[230:231], s[40:41], 0, v[0:1]
	s_mov_b32 m0, s42
	v_lshl_add_u64 v[232:233], s[22:23], 0, v[132:133]
	global_load_lds_dwordx4 v[230:231], off
	v_lshl_add_u64 v[230:231], s[40:41], 0, v[134:135]
	s_add_i32 m0, s42, 0x2000
	s_nop 0
	global_load_lds_dwordx4 v[230:231], off
	v_lshl_add_u64 v[230:231], s[22:23], 0, v[130:131]
	s_mov_b32 m0, s27
	s_nop 0
	global_load_lds_dwordx4 v[230:231], off
	s_mov_b32 m0, s28
	s_nop 0
	global_load_lds_dwordx4 v[232:233], off
	s_waitcnt vmcnt(8)
	s_waitcnt lgkmcnt(0)
	s_barrier
; #define PG8_STAGE(bufoff, gbase, voff) do { _Pragma("unroll") for (int _i = 0; _i < 2; ++_i) \
;         __builtin_amdgcn_global_load_lds((const unsigned*)((const char*)(gbase) + (voff)[_i]), (LAS unsigned*)(lds + (bufoff) + ldsw + _i * 8192), 16, 0, 0); } while (0)
; #define PG8_LDA(dst, b, h) do { _Pragma("unroll") for (int m = 0; m < 4; ++m) _Pragma("unroll") for (int k = 0; k < 2; ++k) dst[m][k] = *(const LAS bf16x8*)(lds + PG8_SA(b, h) + aoff + m * 2048 + k * 1024); } while (0)
; #define PG8_LDB(dst, b, h) do { _Pragma("unroll") for (int n = 0; n < 2; ++n) _Pragma("unroll") for (int k = 0; k < 2; ++k) dst[n][k] = *(const LAS bf16x8*)(lds + PG8_SB(b, h) + boff + n * 2048 + k * 1024); } while (0)
; #define PG8_MMA(ai, bj, At, Bt_) do { __builtin_amdgcn_s_setprio(1); _Pragma("unroll") for (int m = 0; m < 4; ++m) _Pragma("unroll") for (int n = 0; n < 2; ++n) _Pragma("unroll") for (int k = 0; k < 2; ++k) \
;         acc[ai][bj][m][n] = __builtin_amdgcn_mfma_f32_16x16x32_bf16(Bt_[n][k], At[m][k], acc[ai][bj][m][n], 0, 0, 0); __builtin_amdgcn_s_setprio(0); } while (0)
; #define PG8_WAIT_V(n) asm volatile("s_waitcnt vmcnt(" #n ")" ::: "memory")
; #define PG8_WAIT_L(n) asm volatile("s_waitcnt lgkmcnt(" #n ")" ::: "memory")
; #define PG8_BAR __builtin_amdgcn_s_barrier()
; #define PG8_SCHED __builtin_amdgcn_sched_barrier(0)
; __device__ __forceinline__ void gemm_phase(LAS unsigned char* lds, const bf16_t* A, const bf16_t* Bt, int M, int N, int K, const Epi& E) {
;     ...
;             PG8_WAIT_V(8); PG8_WAIT_L(0); PG8_BAR; PG8_MMA(1, 0, At, B0); PG8_MMA(1, 1, At, B1); PG8_BAR; PG8_SCHED;
;             PG8_LDB(B0, 1, 0); PG8_LDB(B1, 1, 1); PG8_SCHED; PG8_LDA(At, 1, 0); PG8_STAGE(PG8_SA(0, 1), a2 + hstep, voffA);
;             PG8_WAIT_V(8); PG8_WAIT_L(0); PG8_BAR; PG8_MMA(0, 0, At, B0); PG8_MMA(0, 1, At, B1); PG8_BAR; PG8_SCHED;
	s_setprio 1
	s_waitcnt lgkmcnt(0)
	v_mfma_f32_16x16x32_bf16 v[62:65], v[148:151], v[180:183], v[62:65]
	v_mfma_f32_16x16x32_bf16 v[58:61], v[156:159], v[180:183], v[58:61]
	v_mfma_f32_16x16x32_bf16 v[54:57], v[148:151], v[206:209], v[54:57]
	v_mfma_f32_16x16x32_bf16 v[50:53], v[156:159], v[206:209], v[50:53]
	v_mfma_f32_16x16x32_bf16 v[38:41], v[148:151], v[214:217], v[38:41]
	v_mfma_f32_16x16x32_bf16 v[34:37], v[156:159], v[214:217], v[34:37]
	v_mfma_f32_16x16x32_bf16 v[22:25], v[148:151], v[222:225], v[22:25]
	v_mfma_f32_16x16x32_bf16 v[18:21], v[156:159], v[222:225], v[18:21]
	v_mfma_f32_16x16x32_bf16 v[62:65], v[152:155], v[202:205], v[62:65]
	v_mfma_f32_16x16x32_bf16 v[58:61], v[160:163], v[202:205], v[58:61]
	v_mfma_f32_16x16x32_bf16 v[54:57], v[152:155], v[210:213], v[54:57]
	v_mfma_f32_16x16x32_bf16 v[50:53], v[160:163], v[210:213], v[50:53]
	v_mfma_f32_16x16x32_bf16 v[38:41], v[152:155], v[218:221], v[38:41]
	v_mfma_f32_16x16x32_bf16 v[34:37], v[160:163], v[218:221], v[34:37]
	v_mfma_f32_16x16x32_bf16 v[22:25], v[152:155], v[226:229], v[22:25]
	v_mfma_f32_16x16x32_bf16 v[18:21], v[160:163], v[226:229], v[18:21]
	v_mfma_f32_16x16x32_bf16 v[46:49], v[164:167], v[180:183], v[46:49]
	v_mfma_f32_16x16x32_bf16 v[42:45], v[172:175], v[180:183], v[42:45]
	v_mfma_f32_16x16x32_bf16 v[30:33], v[164:167], v[206:209], v[30:33]
	v_mfma_f32_16x16x32_bf16 v[26:29], v[172:175], v[206:209], v[26:29]
	v_mfma_f32_16x16x32_bf16 v[14:17], v[164:167], v[214:217], v[14:17]
	v_mfma_f32_16x16x32_bf16 v[10:13], v[172:175], v[214:217], v[10:13]
	v_mfma_f32_16x16x32_bf16 v[6:9], v[164:167], v[222:225], v[6:9]
	v_mfma_f32_16x16x32_bf16 v[2:5], v[172:175], v[222:225], v[2:5]
	v_mfma_f32_16x16x32_bf16 v[46:49], v[168:171], v[202:205], v[46:49]
	v_mfma_f32_16x16x32_bf16 v[42:45], v[176:179], v[202:205], v[42:45]
	v_mfma_f32_16x16x32_bf16 v[30:33], v[168:171], v[210:213], v[30:33]
	v_mfma_f32_16x16x32_bf16 v[26:29], v[176:179], v[210:213], v[26:29]
	v_mfma_f32_16x16x32_bf16 v[14:17], v[168:171], v[218:221], v[14:17]
	v_mfma_f32_16x16x32_bf16 v[10:13], v[176:179], v[218:221], v[10:13]
	v_mfma_f32_16x16x32_bf16 v[6:9], v[168:171], v[226:229], v[6:9]
	v_mfma_f32_16x16x32_bf16 v[2:5], v[176:179], v[226:229], v[2:5]
	s_setprio 0
	s_barrier
	s_add_i32 s40, 0, 0x18000
	s_add_i32 s41, 0, 0x1c000
	v_add_u32_e32 v160, s40, v145
	v_add_u32_e32 v176, s41, v145
	ds_read_b128 v[148:151], v160
	ds_read_b128 v[152:155], v160 offset:1024
	ds_read_b128 v[156:159], v160 offset:2048
	ds_read_b128 v[160:163], v160 offset:3072
	ds_read_b128 v[164:167], v176
	ds_read_b128 v[168:171], v176 offset:1024
	ds_read_b128 v[172:175], v176 offset:2048
	ds_read_b128 v[176:179], v176 offset:3072
	s_add_u32 s22, s22, 0x40000
	s_addc_u32 s23, s23, 0
	s_mov_b32 m0, s29
	v_lshl_add_u64 v[240:241], s[22:23], 0, v[130:131]
	ds_read_b128 v[180:183], v147 offset:32768
	ds_read_b128 v[202:205], v147 offset:33792
	ds_read_b128 v[206:209], v147 offset:34816
	ds_read_b128 v[210:213], v147 offset:35840
	ds_read_b128 v[214:217], v147 offset:36864
	ds_read_b128 v[218:221], v147 offset:37888
	ds_read_b128 v[222:225], v147 offset:38912
	ds_read_b128 v[226:229], v147 offset:39936
	global_load_lds_dwordx4 v[240:241], off
	v_lshl_add_u64 v[240:241], s[22:23], 0, v[132:133]
	s_mov_b32 m0, s30
	s_nop 0
	global_load_lds_dwordx4 v[240:241], off
	s_waitcnt vmcnt(8)
	s_waitcnt lgkmcnt(0)
	s_barrier
	s_setprio 1
	s_waitcnt lgkmcnt(0)
	v_mfma_f32_16x16x32_bf16 v[126:129], v[148:151], v[180:183], v[126:129]
	v_mfma_f32_16x16x32_bf16 v[122:125], v[156:159], v[180:183], v[122:125]
	v_mfma_f32_16x16x32_bf16 v[118:121], v[148:151], v[206:209], v[118:121]
	v_mfma_f32_16x16x32_bf16 v[114:117], v[156:159], v[206:209], v[114:117]
	v_mfma_f32_16x16x32_bf16 v[102:105], v[148:151], v[214:217], v[102:105]
	v_mfma_f32_16x16x32_bf16 v[98:101], v[156:159], v[214:217], v[98:101]
	v_mfma_f32_16x16x32_bf16 v[86:89], v[148:151], v[222:225], v[86:89]
	v_mfma_f32_16x16x32_bf16 v[82:85], v[156:159], v[222:225], v[82:85]
	v_mfma_f32_16x16x32_bf16 v[126:129], v[152:155], v[202:205], v[126:129]
	v_mfma_f32_16x16x32_bf16 v[122:125], v[160:163], v[202:205], v[122:125]
	v_mfma_f32_16x16x32_bf16 v[118:121], v[152:155], v[210:213], v[118:121]
	v_mfma_f32_16x16x32_bf16 v[114:117], v[160:163], v[210:213], v[114:117]
	v_mfma_f32_16x16x32_bf16 v[102:105], v[152:155], v[218:221], v[102:105]
	v_mfma_f32_16x16x32_bf16 v[98:101], v[160:163], v[218:221], v[98:101]
	v_mfma_f32_16x16x32_bf16 v[86:89], v[152:155], v[226:229], v[86:89]
	v_mfma_f32_16x16x32_bf16 v[82:85], v[160:163], v[226:229], v[82:85]
	v_mfma_f32_16x16x32_bf16 v[110:113], v[164:167], v[180:183], v[110:113]
	v_mfma_f32_16x16x32_bf16 v[106:109], v[172:175], v[180:183], v[106:109]
	v_mfma_f32_16x16x32_bf16 v[94:97], v[164:167], v[206:209], v[94:97]
	v_mfma_f32_16x16x32_bf16 v[90:93], v[172:175], v[206:209], v[90:93]
	v_mfma_f32_16x16x32_bf16 v[78:81], v[164:167], v[214:217], v[78:81]
	v_mfma_f32_16x16x32_bf16 v[74:77], v[172:175], v[214:217], v[74:77]
	v_mfma_f32_16x16x32_bf16 v[70:73], v[164:167], v[222:225], v[70:73]
	v_mfma_f32_16x16x32_bf16 v[66:69], v[172:175], v[222:225], v[66:69]
	v_mfma_f32_16x16x32_bf16 v[110:113], v[168:171], v[202:205], v[110:113]
	v_mfma_f32_16x16x32_bf16 v[106:109], v[176:179], v[202:205], v[106:109]
	v_mfma_f32_16x16x32_bf16 v[94:97], v[168:171], v[210:213], v[94:97]
	v_mfma_f32_16x16x32_bf16 v[90:93], v[176:179], v[210:213], v[90:93]
	v_mfma_f32_16x16x32_bf16 v[78:81], v[168:171], v[218:221], v[78:81]
	v_mfma_f32_16x16x32_bf16 v[74:77], v[176:179], v[218:221], v[74:77]
	v_mfma_f32_16x16x32_bf16 v[70:73], v[168:171], v[226:229], v[70:73]
	v_mfma_f32_16x16x32_bf16 v[66:69], v[176:179], v[226:229], v[66:69]
	s_setprio 0
	s_barrier
; #define PG8_STAGE(bufoff, gbase, voff) do { _Pragma("unroll") for (int _i = 0; _i < 2; ++_i) \
;         __builtin_amdgcn_global_load_lds((const unsigned*)((const char*)(gbase) + (voff)[_i]), (LAS unsigned*)(lds + (bufoff) + ldsw + _i * 8192), 16, 0, 0); } while (0)
; #define PG8_LDA(dst, b, h) do { _Pragma("unroll") for (int m = 0; m < 4; ++m) _Pragma("unroll") for (int k = 0; k < 2; ++k) dst[m][k] = *(const LAS bf16x8*)(lds + PG8_SA(b, h) + aoff + m * 2048 + k * 1024); } while (0)
; #define PG8_MMA(ai, bj, At, Bt_) do { __builtin_amdgcn_s_setprio(1); _Pragma("unroll") for (int m = 0; m < 4; ++m) _Pragma("unroll") for (int n = 0; n < 2; ++n) _Pragma("unroll") for (int k = 0; k < 2; ++k) \
;         acc[ai][bj][m][n] = __builtin_amdgcn_mfma_f32_16x16x32_bf16(Bt_[n][k], At[m][k], acc[ai][bj][m][n], 0, 0, 0); __builtin_amdgcn_s_setprio(0); } while (0)
; #define PG8_WAIT_V(n) asm volatile("s_waitcnt vmcnt(" #n ")" ::: "memory")
; #define PG8_WAIT_L(n) asm volatile("s_waitcnt lgkmcnt(" #n ")" ::: "memory")
; #define PG8_BAR __builtin_amdgcn_s_barrier()
; #define PG8_SCHED __builtin_amdgcn_sched_barrier(0)
; __device__ __forceinline__ void gemm_phase(LAS unsigned char* lds, const bf16_t* A, const bf16_t* Bt, int M, int N, int K, const Epi& E) {
;     ...
;             PG8_LDA(At, 1, 1); PG8_STAGE(PG8_SB(1, 0), b3, voffB); PG8_STAGE(PG8_SB(1, 1), b3 + hstep, voffB); PG8_STAGE(PG8_SA(1, 0), a3, voffA);
;             PG8_WAIT_V(8); PG8_WAIT_L(0); PG8_BAR; PG8_MMA(1, 0, At, B0); PG8_MMA(1, 1, At, B1); PG8_BAR; PG8_SCHED;
;         }
;         if (wr == 0) PG8_BAR;
	s_add_i32 s22, s40, s26
	v_lshl_add_u64 v[142:143], v[142:143], 0, s[44:45]
	s_mov_b32 m0, s22
	ds_read_b128 v[180:183], v147 offset:49152
	ds_read_b128 v[202:205], v147 offset:50176
	ds_read_b128 v[206:209], v147 offset:51200
	ds_read_b128 v[210:213], v147 offset:52224
	ds_read_b128 v[214:217], v147 offset:53248
	ds_read_b128 v[218:221], v147 offset:54272
	ds_read_b128 v[222:225], v147 offset:55296
	ds_read_b128 v[226:229], v147 offset:56320
	global_load_lds_dwordx4 v[142:143], off
	s_add_i32 m0, s22, 0x2000
	s_add_u32 s20, s20, 0x40080
	v_lshl_add_u64 v[142:143], v[184:185], 0, s[44:45]
	s_addc_u32 s21, s21, 0
	s_add_i32 s22, s41, s26
	global_load_lds_dwordx4 v[142:143], off
	v_lshl_add_u64 v[142:143], s[20:21], 0, v[0:1]
	s_mov_b32 m0, s22
	s_nop 0
	global_load_lds_dwordx4 v[142:143], off
	v_lshl_add_u64 v[142:143], s[20:21], 0, v[134:135]
	s_add_i32 m0, s22, 0x2000
	s_nop 0
	global_load_lds_dwordx4 v[142:143], off
	v_lshl_add_u64 v[142:143], v[230:231], 0, s[44:45]
	s_mov_b32 m0, s31
	s_nop 0
	global_load_lds_dwordx4 v[142:143], off
	v_lshl_add_u64 v[142:143], v[232:233], 0, s[44:45]
	s_mov_b32 m0, s33
	s_nop 0
	global_load_lds_dwordx4 v[142:143], off
	s_waitcnt vmcnt(8)
	s_waitcnt lgkmcnt(0)
	s_barrier
	s_setprio 1
	s_waitcnt lgkmcnt(0)
	v_mfma_f32_16x16x32_bf16 v[62:65], v[148:151], v[180:183], v[62:65]
	v_mfma_f32_16x16x32_bf16 v[58:61], v[156:159], v[180:183], v[58:61]
	v_mfma_f32_16x16x32_bf16 v[54:57], v[148:151], v[206:209], v[54:57]
	v_mfma_f32_16x16x32_bf16 v[50:53], v[156:159], v[206:209], v[50:53]
	v_mfma_f32_16x16x32_bf16 v[38:41], v[148:151], v[214:217], v[38:41]
	v_mfma_f32_16x16x32_bf16 v[34:37], v[156:159], v[214:217], v[34:37]
	v_mfma_f32_16x16x32_bf16 v[22:25], v[148:151], v[222:225], v[22:25]
	v_mfma_f32_16x16x32_bf16 v[18:21], v[156:159], v[222:225], v[18:21]
	v_mfma_f32_16x16x32_bf16 v[62:65], v[152:155], v[202:205], v[62:65]
	v_mfma_f32_16x16x32_bf16 v[58:61], v[160:163], v[202:205], v[58:61]
	v_mfma_f32_16x16x32_bf16 v[54:57], v[152:155], v[210:213], v[54:57]
	v_mfma_f32_16x16x32_bf16 v[50:53], v[160:163], v[210:213], v[50:53]
	v_mfma_f32_16x16x32_bf16 v[38:41], v[152:155], v[218:221], v[38:41]
	v_mfma_f32_16x16x32_bf16 v[34:37], v[160:163], v[218:221], v[34:37]
	v_mfma_f32_16x16x32_bf16 v[22:25], v[152:155], v[226:229], v[22:25]
	v_mfma_f32_16x16x32_bf16 v[18:21], v[160:163], v[226:229], v[18:21]
	v_mfma_f32_16x16x32_bf16 v[46:49], v[164:167], v[180:183], v[46:49]
	v_mfma_f32_16x16x32_bf16 v[42:45], v[172:175], v[180:183], v[42:45]
	v_mfma_f32_16x16x32_bf16 v[30:33], v[164:167], v[206:209], v[30:33]
	v_mfma_f32_16x16x32_bf16 v[26:29], v[172:175], v[206:209], v[26:29]
	v_mfma_f32_16x16x32_bf16 v[14:17], v[164:167], v[214:217], v[14:17]
	v_mfma_f32_16x16x32_bf16 v[10:13], v[172:175], v[214:217], v[10:13]
	v_mfma_f32_16x16x32_bf16 v[6:9], v[164:167], v[222:225], v[6:9]
	v_mfma_f32_16x16x32_bf16 v[2:5], v[172:175], v[222:225], v[2:5]
	v_mfma_f32_16x16x32_bf16 v[46:49], v[168:171], v[202:205], v[46:49]
	v_mfma_f32_16x16x32_bf16 v[42:45], v[176:179], v[202:205], v[42:45]
	v_mfma_f32_16x16x32_bf16 v[30:33], v[168:171], v[210:213], v[30:33]
	v_mfma_f32_16x16x32_bf16 v[26:29], v[176:179], v[210:213], v[26:29]
	v_mfma_f32_16x16x32_bf16 v[14:17], v[168:171], v[218:221], v[14:17]
	v_mfma_f32_16x16x32_bf16 v[10:13], v[176:179], v[218:221], v[10:13]
	v_mfma_f32_16x16x32_bf16 v[6:9], v[168:171], v[226:229], v[6:9]
	v_mfma_f32_16x16x32_bf16 v[2:5], v[176:179], v[226:229], v[2:5]
	s_setprio 0
	s_barrier
	s_add_i32 s39, s39, 2
	s_add_u32 s18, s18, 0x100
	s_addc_u32 s19, s19, 0
	s_add_u32 s37, s37, 0x100
	s_addc_u32 s38, s38, 0
	s_cmp_gt_u32 s39, 13
	s_cbranch_scc0 .LBB0_735
	s_and_b64 vcc, exec, s[4:5]
	s_cbranch_vccz .LBB0_738
	s_barrier

; #define PG8_STAGE(bufoff, gbase, voff) do { _Pragma("unroll") for (int _i = 0; _i < 2; ++_i) \
;         __builtin_amdgcn_global_load_lds((const unsigned*)((const char*)(gbase) + (voff)[_i]), (LAS unsigned*)(lds + (bufoff) + ldsw + _i * 8192), 16, 0, 0); } while (0)
; #define PG8_LDA(dst, b, h) do { _Pragma("unroll") for (int m = 0; m < 4; ++m) _Pragma("unroll") for (int k = 0; k < 2; ++k) dst[m][k] = *(const LAS bf16x8*)(lds + PG8_SA(b, h) + aoff + m * 2048 + k * 1024); } while (0)
; #define PG8_LDB(dst, b, h) do { _Pragma("unroll") for (int n = 0; n < 2; ++n) _Pragma("unroll") for (int k = 0; k < 2; ++k) dst[n][k] = *(const LAS bf16x8*)(lds + PG8_SB(b, h) + boff + n * 2048 + k * 1024); } while (0)
; #define PG8_MMA(ai, bj, At, Bt_) do { __builtin_amdgcn_s_setprio(1); _Pragma("unroll") for (int m = 0; m < 4; ++m) _Pragma("unroll") for (int n = 0; n < 2; ++n) _Pragma("unroll") for (int k = 0; k < 2; ++k) \
;         acc[ai][bj][m][n] = __builtin_amdgcn_mfma_f32_16x16x32_bf16(Bt_[n][k], At[m][k], acc[ai][bj][m][n], 0, 0, 0); __builtin_amdgcn_s_setprio(0); } while (0)
; #define PG8_WAIT_V(n) asm volatile("s_waitcnt vmcnt(" #n ")" ::: "memory")
; #define PG8_WAIT_L(n) asm volatile("s_waitcnt lgkmcnt(" #n ")" ::: "memory")
; #define PG8_BAR __builtin_amdgcn_s_barrier()
; #define PG8_SCHED __builtin_amdgcn_sched_barrier(0)
; __device__ __forceinline__ void gemm_phase(LAS unsigned char* lds, const bf16_t* A, const bf16_t* Bt, int M, int N, int K, const Epi& E) {
;     ...
;             PG8_LDB(B0, 0, 0); PG8_LDB(B1, 0, 1); PG8_SCHED; PG8_LDA(At, 0, 0); PG8_STAGE(PG8_SA(1, 1), a1 + hstep, voffA);
;             PG8_WAIT_V(8); PG8_WAIT_L(0); PG8_BAR; PG8_MMA(0, 0, At, B0); PG8_MMA(0, 1, At, B1); PG8_BAR; PG8_SCHED;
;             PG8_LDA(At, 0, 1); PG8_STAGE(PG8_SB(0, 0), b2, voffB); PG8_STAGE(PG8_SB(0, 1), b2 + hstep, voffB); PG8_STAGE(PG8_SA(0, 0), a2, voffA);
;             PG8_WAIT_V(8); PG8_WAIT_L(0); PG8_BAR; PG8_MMA(1, 0, At, B0); PG8_MMA(1, 1, At, B1); PG8_BAR; PG8_SCHED;
.LBB0_950:
	s_add_u32 s20, s18, 0xfffc0080
	s_addc_u32 s21, s19, -1
	s_add_i32 s41, 0, 0x10000
	s_cmp_eq_u32 s40, 12
	s_cselect_b32 s23, s1, s21
	s_cselect_b32 s22, s3, s20
	s_cselect_b32 s21, s11, s39
	s_cselect_b32 s20, s13, s38
	s_add_i32 s44, 0, 0x14000
	s_waitcnt vmcnt(0)
	v_add_u32_e32 v118, s41, v249
	v_add_u32_e32 v158, s44, v249
	ds_read_b128 v[102:105], v118
	ds_read_b128 v[110:113], v118 offset:1024
	ds_read_b128 v[114:117], v118 offset:2048
	ds_read_b128 v[118:121], v118 offset:3072
	ds_read_b128 v[146:149], v158
	ds_read_b128 v[150:153], v158 offset:1024
	ds_read_b128 v[154:157], v158 offset:2048
	ds_read_b128 v[158:161], v158 offset:3072
	v_lshl_add_u64 v[220:221], s[18:19], 0, v[208:209]
	s_add_i32 m0, s27, 0xc000
	ds_read_b128 v[162:165], v240
	ds_read_b128 v[166:169], v240 offset:1024
	ds_read_b128 v[170:173], v240 offset:2048
	ds_read_b128 v[174:177], v240 offset:3072
	ds_read_b128 v[178:181], v240 offset:4096
	ds_read_b128 v[182:185], v240 offset:5120
	ds_read_b128 v[212:215], v240 offset:6144
	ds_read_b128 v[216:219], v240 offset:7168
	global_load_lds_dwordx4 v[220:221], off
	v_lshl_add_u64 v[220:221], s[18:19], 0, v[210:211]
	s_add_i32 m0, s27, 0xe000
	s_nop 0
	global_load_lds_dwordx4 v[220:221], off
	s_waitcnt vmcnt(8)
	s_waitcnt lgkmcnt(0)
	s_barrier
	s_setprio 1
	s_waitcnt lgkmcnt(0)
	v_mfma_f32_16x16x32_bf16 v[142:145], v[102:105], v[162:165], v[142:145]
	v_mfma_f32_16x16x32_bf16 v[138:141], v[114:117], v[162:165], v[138:141]
	v_mfma_f32_16x16x32_bf16 v[126:129], v[102:105], v[170:173], v[126:129]
	v_mfma_f32_16x16x32_bf16 v[122:125], v[114:117], v[170:173], v[122:125]
	v_mfma_f32_16x16x32_bf16 v[94:97], v[102:105], v[178:181], v[94:97]
	v_mfma_f32_16x16x32_bf16 v[90:93], v[114:117], v[178:181], v[90:93]
	v_mfma_f32_16x16x32_bf16 v[78:81], v[102:105], v[212:215], v[78:81]
	v_mfma_f32_16x16x32_bf16 v[74:77], v[114:117], v[212:215], v[74:77]
	v_mfma_f32_16x16x32_bf16 v[142:145], v[110:113], v[166:169], v[142:145]
	v_mfma_f32_16x16x32_bf16 v[138:141], v[118:121], v[166:169], v[138:141]
	v_mfma_f32_16x16x32_bf16 v[126:129], v[110:113], v[174:177], v[126:129]
	v_mfma_f32_16x16x32_bf16 v[122:125], v[118:121], v[174:177], v[122:125]
	v_mfma_f32_16x16x32_bf16 v[94:97], v[110:113], v[182:185], v[94:97]
	v_mfma_f32_16x16x32_bf16 v[90:93], v[118:121], v[182:185], v[90:93]
	v_mfma_f32_16x16x32_bf16 v[78:81], v[110:113], v[216:219], v[78:81]
	v_mfma_f32_16x16x32_bf16 v[74:77], v[118:121], v[216:219], v[74:77]
	v_mfma_f32_16x16x32_bf16 v[134:137], v[146:149], v[162:165], v[134:137]
	v_mfma_f32_16x16x32_bf16 v[130:133], v[154:157], v[162:165], v[130:133]
	v_mfma_f32_16x16x32_bf16 v[106:109], v[146:149], v[170:173], v[106:109]
	v_mfma_f32_16x16x32_bf16 v[98:101], v[154:157], v[170:173], v[98:101]
	v_mfma_f32_16x16x32_bf16 v[86:89], v[146:149], v[178:181], v[86:89]
	v_mfma_f32_16x16x32_bf16 v[82:85], v[154:157], v[178:181], v[82:85]
	v_mfma_f32_16x16x32_bf16 v[70:73], v[146:149], v[212:215], v[70:73]
	v_mfma_f32_16x16x32_bf16 v[66:69], v[154:157], v[212:215], v[66:69]
	v_mfma_f32_16x16x32_bf16 v[134:137], v[150:153], v[166:169], v[134:137]
	v_mfma_f32_16x16x32_bf16 v[130:133], v[158:161], v[166:169], v[130:133]
	v_mfma_f32_16x16x32_bf16 v[106:109], v[150:153], v[174:177], v[106:109]
	v_mfma_f32_16x16x32_bf16 v[98:101], v[158:161], v[174:177], v[98:101]
	v_mfma_f32_16x16x32_bf16 v[86:89], v[150:153], v[182:185], v[86:89]
	v_mfma_f32_16x16x32_bf16 v[82:85], v[158:161], v[182:185], v[82:85]
	v_mfma_f32_16x16x32_bf16 v[70:73], v[150:153], v[216:219], v[70:73]
	v_mfma_f32_16x16x32_bf16 v[66:69], v[158:161], v[216:219], v[66:69]
	s_setprio 0
	s_barrier
	s_add_i32 s41, s41, s26
	v_lshl_add_u64 v[220:221], s[20:21], 0, v[0:1]
	s_mov_b32 m0, s41
	ds_read_b128 v[162:165], v240 offset:16384
	ds_read_b128 v[166:169], v240 offset:17408
	ds_read_b128 v[170:173], v240 offset:18432
	ds_read_b128 v[174:177], v240 offset:19456
	ds_read_b128 v[178:181], v240 offset:20480
	ds_read_b128 v[182:185], v240 offset:21504
	ds_read_b128 v[212:215], v240 offset:22528
	ds_read_b128 v[216:219], v240 offset:23552
	global_load_lds_dwordx4 v[220:221], off
	s_add_i32 m0, s41, 0x2000
	s_add_u32 s42, s20, 0x40000
	v_lshl_add_u64 v[222:223], s[20:21], 0, v[206:207]
	s_addc_u32 s43, s21, 0
	s_add_i32 s41, s44, s26
	global_load_lds_dwordx4 v[222:223], off
	v_lshl_add_u64 v[224:225], s[42:43], 0, v[0:1]
	s_mov_b32 m0, s41
	v_lshl_add_u64 v[226:227], s[22:23], 0, v[204:205]
	global_load_lds_dwordx4 v[224:225], off
	v_lshl_add_u64 v[224:225], s[42:43], 0, v[206:207]
	s_add_i32 m0, s41, 0x2000
	s_nop 0
	global_load_lds_dwordx4 v[224:225], off
	v_lshl_add_u64 v[224:225], s[22:23], 0, v[202:203]
	s_mov_b32 m0, s27
	s_nop 0
	global_load_lds_dwordx4 v[224:225], off
	s_mov_b32 m0, s28
	s_nop 0
	global_load_lds_dwordx4 v[226:227], off
	s_waitcnt vmcnt(8)
	s_waitcnt lgkmcnt(0)
	s_barrier
; #define PG8_STAGE(bufoff, gbase, voff) do { _Pragma("unroll") for (int _i = 0; _i < 2; ++_i) \
;         __builtin_amdgcn_global_load_lds((const unsigned*)((const char*)(gbase) + (voff)[_i]), (LAS unsigned*)(lds + (bufoff) + ldsw + _i * 8192), 16, 0, 0); } while (0)
; #define PG8_LDA(dst, b, h) do { _Pragma("unroll") for (int m = 0; m < 4; ++m) _Pragma("unroll") for (int k = 0; k < 2; ++k) dst[m][k] = *(const LAS bf16x8*)(lds + PG8_SA(b, h) + aoff + m * 2048 + k * 1024); } while (0)
; #define PG8_LDB(dst, b, h) do { _Pragma("unroll") for (int n = 0; n < 2; ++n) _Pragma("unroll") for (int k = 0; k < 2; ++k) dst[n][k] = *(const LAS bf16x8*)(lds + PG8_SB(b, h) + boff + n * 2048 + k * 1024); } while (0)
; #define PG8_MMA(ai, bj, At, Bt_) do { __builtin_amdgcn_s_setprio(1); _Pragma("unroll") for (int m = 0; m < 4; ++m) _Pragma("unroll") for (int n = 0; n < 2; ++n) _Pragma("unroll") for (int k = 0; k < 2; ++k) \
;         acc[ai][bj][m][n] = __builtin_amdgcn_mfma_f32_16x16x32_bf16(Bt_[n][k], At[m][k], acc[ai][bj][m][n], 0, 0, 0); __builtin_amdgcn_s_setprio(0); } while (0)
; #define PG8_WAIT_V(n) asm volatile("s_waitcnt vmcnt(" #n ")" ::: "memory")
; #define PG8_WAIT_L(n) asm volatile("s_waitcnt lgkmcnt(" #n ")" ::: "memory")
; #define PG8_BAR __builtin_amdgcn_s_barrier()
; #define PG8_SCHED __builtin_amdgcn_sched_barrier(0)
; __device__ __forceinline__ void gemm_phase(LAS unsigned char* lds, const bf16_t* A, const bf16_t* Bt, int M, int N, int K, const Epi& E) {
;     ...
;             PG8_WAIT_V(8); PG8_WAIT_L(0); PG8_BAR; PG8_MMA(1, 0, At, B0); PG8_MMA(1, 1, At, B1); PG8_BAR; PG8_SCHED;
;             PG8_LDB(B0, 1, 0); PG8_LDB(B1, 1, 1); PG8_SCHED; PG8_LDA(At, 1, 0); PG8_STAGE(PG8_SA(0, 1), a2 + hstep, voffA);
;             PG8_WAIT_V(8); PG8_WAIT_L(0); PG8_BAR; PG8_MMA(0, 0, At, B0); PG8_MMA(0, 1, At, B1); PG8_BAR; PG8_SCHED;
	s_setprio 1
	s_waitcnt lgkmcnt(0)
	v_mfma_f32_16x16x32_bf16 v[62:65], v[102:105], v[162:165], v[62:65]
	v_mfma_f32_16x16x32_bf16 v[58:61], v[114:117], v[162:165], v[58:61]
	v_mfma_f32_16x16x32_bf16 v[46:49], v[102:105], v[170:173], v[46:49]
	v_mfma_f32_16x16x32_bf16 v[42:45], v[114:117], v[170:173], v[42:45]
	v_mfma_f32_16x16x32_bf16 v[30:33], v[102:105], v[178:181], v[30:33]
	v_mfma_f32_16x16x32_bf16 v[26:29], v[114:117], v[178:181], v[26:29]
	v_mfma_f32_16x16x32_bf16 v[14:17], v[102:105], v[212:215], v[14:17]
	v_mfma_f32_16x16x32_bf16 v[10:13], v[114:117], v[212:215], v[10:13]
	v_mfma_f32_16x16x32_bf16 v[62:65], v[110:113], v[166:169], v[62:65]
	v_mfma_f32_16x16x32_bf16 v[58:61], v[118:121], v[166:169], v[58:61]
	v_mfma_f32_16x16x32_bf16 v[46:49], v[110:113], v[174:177], v[46:49]
	v_mfma_f32_16x16x32_bf16 v[42:45], v[118:121], v[174:177], v[42:45]
	v_mfma_f32_16x16x32_bf16 v[30:33], v[110:113], v[182:185], v[30:33]
	v_mfma_f32_16x16x32_bf16 v[26:29], v[118:121], v[182:185], v[26:29]
	v_mfma_f32_16x16x32_bf16 v[14:17], v[110:113], v[216:219], v[14:17]
	v_mfma_f32_16x16x32_bf16 v[10:13], v[118:121], v[216:219], v[10:13]
	v_mfma_f32_16x16x32_bf16 v[54:57], v[146:149], v[162:165], v[54:57]
	v_mfma_f32_16x16x32_bf16 v[50:53], v[154:157], v[162:165], v[50:53]
	v_mfma_f32_16x16x32_bf16 v[38:41], v[146:149], v[170:173], v[38:41]
	v_mfma_f32_16x16x32_bf16 v[34:37], v[154:157], v[170:173], v[34:37]
	v_mfma_f32_16x16x32_bf16 v[22:25], v[146:149], v[178:181], v[22:25]
	v_mfma_f32_16x16x32_bf16 v[18:21], v[154:157], v[178:181], v[18:21]
	v_mfma_f32_16x16x32_bf16 v[6:9], v[146:149], v[212:215], v[6:9]
	v_mfma_f32_16x16x32_bf16 v[2:5], v[154:157], v[212:215], v[2:5]
	v_mfma_f32_16x16x32_bf16 v[54:57], v[150:153], v[166:169], v[54:57]
	v_mfma_f32_16x16x32_bf16 v[50:53], v[158:161], v[166:169], v[50:53]
	v_mfma_f32_16x16x32_bf16 v[38:41], v[150:153], v[174:177], v[38:41]
	v_mfma_f32_16x16x32_bf16 v[34:37], v[158:161], v[174:177], v[34:37]
	v_mfma_f32_16x16x32_bf16 v[22:25], v[150:153], v[182:185], v[22:25]
	v_mfma_f32_16x16x32_bf16 v[18:21], v[158:161], v[182:185], v[18:21]
	v_mfma_f32_16x16x32_bf16 v[6:9], v[150:153], v[216:219], v[6:9]
	v_mfma_f32_16x16x32_bf16 v[2:5], v[158:161], v[216:219], v[2:5]
	s_setprio 0
	s_barrier
	s_add_i32 s41, 0, 0x18000
	s_add_i32 s42, 0, 0x1c000
	v_add_u32_e32 v118, s41, v249
	v_add_u32_e32 v158, s42, v249
	ds_read_b128 v[102:105], v118
	ds_read_b128 v[110:113], v118 offset:1024
	ds_read_b128 v[114:117], v118 offset:2048
	ds_read_b128 v[118:121], v118 offset:3072
	ds_read_b128 v[146:149], v158
	ds_read_b128 v[150:153], v158 offset:1024
	ds_read_b128 v[154:157], v158 offset:2048
	ds_read_b128 v[158:161], v158 offset:3072
	s_add_u32 s22, s22, 0x40000
	s_addc_u32 s23, s23, 0
	s_mov_b32 m0, s29
	v_lshl_add_u64 v[228:229], s[22:23], 0, v[202:203]
	ds_read_b128 v[162:165], v240 offset:32768
	ds_read_b128 v[166:169], v240 offset:33792
	ds_read_b128 v[170:173], v240 offset:34816
	ds_read_b128 v[174:177], v240 offset:35840
	ds_read_b128 v[178:181], v240 offset:36864
	ds_read_b128 v[182:185], v240 offset:37888
	ds_read_b128 v[212:215], v240 offset:38912
	ds_read_b128 v[216:219], v240 offset:39936
	global_load_lds_dwordx4 v[228:229], off
	v_lshl_add_u64 v[228:229], s[22:23], 0, v[204:205]
	s_mov_b32 m0, s30
	s_nop 0
	global_load_lds_dwordx4 v[228:229], off
	s_waitcnt vmcnt(8)
	s_waitcnt lgkmcnt(0)
	s_barrier
	s_setprio 1
	s_waitcnt lgkmcnt(0)
	v_mfma_f32_16x16x32_bf16 v[142:145], v[102:105], v[162:165], v[142:145]
	v_mfma_f32_16x16x32_bf16 v[138:141], v[114:117], v[162:165], v[138:141]
	v_mfma_f32_16x16x32_bf16 v[126:129], v[102:105], v[170:173], v[126:129]
	v_mfma_f32_16x16x32_bf16 v[122:125], v[114:117], v[170:173], v[122:125]
	v_mfma_f32_16x16x32_bf16 v[94:97], v[102:105], v[178:181], v[94:97]
	v_mfma_f32_16x16x32_bf16 v[90:93], v[114:117], v[178:181], v[90:93]
	v_mfma_f32_16x16x32_bf16 v[78:81], v[102:105], v[212:215], v[78:81]
	v_mfma_f32_16x16x32_bf16 v[74:77], v[114:117], v[212:215], v[74:77]
	v_mfma_f32_16x16x32_bf16 v[142:145], v[110:113], v[166:169], v[142:145]
	v_mfma_f32_16x16x32_bf16 v[138:141], v[118:121], v[166:169], v[138:141]
	v_mfma_f32_16x16x32_bf16 v[126:129], v[110:113], v[174:177], v[126:129]
	v_mfma_f32_16x16x32_bf16 v[122:125], v[118:121], v[174:177], v[122:125]
	v_mfma_f32_16x16x32_bf16 v[94:97], v[110:113], v[182:185], v[94:97]
	v_mfma_f32_16x16x32_bf16 v[90:93], v[118:121], v[182:185], v[90:93]
	v_mfma_f32_16x16x32_bf16 v[78:81], v[110:113], v[216:219], v[78:81]
	v_mfma_f32_16x16x32_bf16 v[74:77], v[118:121], v[216:219], v[74:77]
	v_mfma_f32_16x16x32_bf16 v[134:137], v[146:149], v[162:165], v[134:137]
	v_mfma_f32_16x16x32_bf16 v[130:133], v[154:157], v[162:165], v[130:133]
	v_mfma_f32_16x16x32_bf16 v[106:109], v[146:149], v[170:173], v[106:109]
	v_mfma_f32_16x16x32_bf16 v[98:101], v[154:157], v[170:173], v[98:101]
	v_mfma_f32_16x16x32_bf16 v[86:89], v[146:149], v[178:181], v[86:89]
	v_mfma_f32_16x16x32_bf16 v[82:85], v[154:157], v[178:181], v[82:85]
	v_mfma_f32_16x16x32_bf16 v[70:73], v[146:149], v[212:215], v[70:73]
	v_mfma_f32_16x16x32_bf16 v[66:69], v[154:157], v[212:215], v[66:69]
	v_mfma_f32_16x16x32_bf16 v[134:137], v[150:153], v[166:169], v[134:137]
	v_mfma_f32_16x16x32_bf16 v[130:133], v[158:161], v[166:169], v[130:133]
	v_mfma_f32_16x16x32_bf16 v[106:109], v[150:153], v[174:177], v[106:109]
	v_mfma_f32_16x16x32_bf16 v[98:101], v[158:161], v[174:177], v[98:101]
	v_mfma_f32_16x16x32_bf16 v[86:89], v[150:153], v[182:185], v[86:89]
	v_mfma_f32_16x16x32_bf16 v[82:85], v[158:161], v[182:185], v[82:85]
	v_mfma_f32_16x16x32_bf16 v[70:73], v[150:153], v[216:219], v[70:73]
	v_mfma_f32_16x16x32_bf16 v[66:69], v[158:161], v[216:219], v[66:69]
	s_setprio 0
	s_barrier
; #define PG8_STAGE(bufoff, gbase, voff) do { _Pragma("unroll") for (int _i = 0; _i < 2; ++_i) \
;         __builtin_amdgcn_global_load_lds((const unsigned*)((const char*)(gbase) + (voff)[_i]), (LAS unsigned*)(lds + (bufoff) + ldsw + _i * 8192), 16, 0, 0); } while (0)
; #define PG8_LDA(dst, b, h) do { _Pragma("unroll") for (int m = 0; m < 4; ++m) _Pragma("unroll") for (int k = 0; k < 2; ++k) dst[m][k] = *(const LAS bf16x8*)(lds + PG8_SA(b, h) + aoff + m * 2048 + k * 1024); } while (0)
; #define PG8_MMA(ai, bj, At, Bt_) do { __builtin_amdgcn_s_setprio(1); _Pragma("unroll") for (int m = 0; m < 4; ++m) _Pragma("unroll") for (int n = 0; n < 2; ++n) _Pragma("unroll") for (int k = 0; k < 2; ++k) \
;         acc[ai][bj][m][n] = __builtin_amdgcn_mfma_f32_16x16x32_bf16(Bt_[n][k], At[m][k], acc[ai][bj][m][n], 0, 0, 0); __builtin_amdgcn_s_setprio(0); } while (0)
; #define PG8_WAIT_V(n) asm volatile("s_waitcnt vmcnt(" #n ")" ::: "memory")
; #define PG8_WAIT_L(n) asm volatile("s_waitcnt lgkmcnt(" #n ")" ::: "memory")
; #define PG8_BAR __builtin_amdgcn_s_barrier()
; #define PG8_SCHED __builtin_amdgcn_sched_barrier(0)
; __device__ __forceinline__ void gemm_phase(LAS unsigned char* lds, const bf16_t* A, const bf16_t* Bt, int M, int N, int K, const Epi& E) {
;     ...
;             PG8_LDA(At, 1, 1); PG8_STAGE(PG8_SB(1, 0), b3, voffB); PG8_STAGE(PG8_SB(1, 1), b3 + hstep, voffB); PG8_STAGE(PG8_SA(1, 0), a3, voffA);
;             PG8_WAIT_V(8); PG8_WAIT_L(0); PG8_BAR; PG8_MMA(1, 0, At, B0); PG8_MMA(1, 1, At, B1); PG8_BAR; PG8_SCHED;
;         }
;         if (wr == 0) PG8_BAR;
	s_add_i32 s22, s41, s26
	v_lshl_add_u64 v[220:221], v[220:221], 0, s[46:47]
	s_mov_b32 m0, s22
	ds_read_b128 v[162:165], v240 offset:49152
	ds_read_b128 v[166:169], v240 offset:50176
	ds_read_b128 v[170:173], v240 offset:51200
	ds_read_b128 v[174:177], v240 offset:52224
	ds_read_b128 v[178:181], v240 offset:53248
	ds_read_b128 v[182:185], v240 offset:54272
	ds_read_b128 v[212:215], v240 offset:55296
	ds_read_b128 v[216:219], v240 offset:56320
	global_load_lds_dwordx4 v[220:221], off
	s_add_i32 m0, s22, 0x2000
	s_add_u32 s20, s20, 0x40080
	v_lshl_add_u64 v[220:221], v[222:223], 0, s[46:47]
	s_addc_u32 s21, s21, 0
	s_add_i32 s22, s42, s26
	global_load_lds_dwordx4 v[220:221], off
	v_lshl_add_u64 v[220:221], s[20:21], 0, v[0:1]
	s_mov_b32 m0, s22
	s_nop 0
	global_load_lds_dwordx4 v[220:221], off
	v_lshl_add_u64 v[220:221], s[20:21], 0, v[206:207]
	s_add_i32 m0, s22, 0x2000
	s_nop 0
	global_load_lds_dwordx4 v[220:221], off
	v_lshl_add_u64 v[220:221], v[224:225], 0, s[46:47]
	s_mov_b32 m0, s33
	s_nop 0
	global_load_lds_dwordx4 v[220:221], off
	v_lshl_add_u64 v[220:221], v[226:227], 0, s[46:47]
	s_mov_b32 m0, s34
	s_nop 0
	global_load_lds_dwordx4 v[220:221], off
	s_waitcnt vmcnt(8)
	s_waitcnt lgkmcnt(0)
	s_barrier
	s_setprio 1
	s_waitcnt lgkmcnt(0)
	v_mfma_f32_16x16x32_bf16 v[62:65], v[102:105], v[162:165], v[62:65]
	v_mfma_f32_16x16x32_bf16 v[58:61], v[114:117], v[162:165], v[58:61]
	v_mfma_f32_16x16x32_bf16 v[46:49], v[102:105], v[170:173], v[46:49]
	v_mfma_f32_16x16x32_bf16 v[42:45], v[114:117], v[170:173], v[42:45]
	v_mfma_f32_16x16x32_bf16 v[30:33], v[102:105], v[178:181], v[30:33]
	v_mfma_f32_16x16x32_bf16 v[26:29], v[114:117], v[178:181], v[26:29]
	v_mfma_f32_16x16x32_bf16 v[14:17], v[102:105], v[212:215], v[14:17]
	v_mfma_f32_16x16x32_bf16 v[10:13], v[114:117], v[212:215], v[10:13]
	v_mfma_f32_16x16x32_bf16 v[62:65], v[110:113], v[166:169], v[62:65]
	v_mfma_f32_16x16x32_bf16 v[58:61], v[118:121], v[166:169], v[58:61]
	v_mfma_f32_16x16x32_bf16 v[46:49], v[110:113], v[174:177], v[46:49]
	v_mfma_f32_16x16x32_bf16 v[42:45], v[118:121], v[174:177], v[42:45]
	v_mfma_f32_16x16x32_bf16 v[30:33], v[110:113], v[182:185], v[30:33]
	v_mfma_f32_16x16x32_bf16 v[26:29], v[118:121], v[182:185], v[26:29]
	v_mfma_f32_16x16x32_bf16 v[14:17], v[110:113], v[216:219], v[14:17]
	v_mfma_f32_16x16x32_bf16 v[10:13], v[118:121], v[216:219], v[10:13]
	v_mfma_f32_16x16x32_bf16 v[54:57], v[146:149], v[162:165], v[54:57]
	v_mfma_f32_16x16x32_bf16 v[50:53], v[154:157], v[162:165], v[50:53]
	v_mfma_f32_16x16x32_bf16 v[38:41], v[146:149], v[170:173], v[38:41]
	v_mfma_f32_16x16x32_bf16 v[34:37], v[154:157], v[170:173], v[34:37]
	v_mfma_f32_16x16x32_bf16 v[22:25], v[146:149], v[178:181], v[22:25]
	v_mfma_f32_16x16x32_bf16 v[18:21], v[154:157], v[178:181], v[18:21]
	v_mfma_f32_16x16x32_bf16 v[6:9], v[146:149], v[212:215], v[6:9]
	v_mfma_f32_16x16x32_bf16 v[2:5], v[154:157], v[212:215], v[2:5]
	v_mfma_f32_16x16x32_bf16 v[54:57], v[150:153], v[166:169], v[54:57]
	v_mfma_f32_16x16x32_bf16 v[50:53], v[158:161], v[166:169], v[50:53]
	v_mfma_f32_16x16x32_bf16 v[38:41], v[150:153], v[174:177], v[38:41]
	v_mfma_f32_16x16x32_bf16 v[34:37], v[158:161], v[174:177], v[34:37]
	v_mfma_f32_16x16x32_bf16 v[22:25], v[150:153], v[182:185], v[22:25]
	v_mfma_f32_16x16x32_bf16 v[18:21], v[158:161], v[182:185], v[18:21]
	v_mfma_f32_16x16x32_bf16 v[6:9], v[150:153], v[216:219], v[6:9]
	v_mfma_f32_16x16x32_bf16 v[2:5], v[158:161], v[216:219], v[2:5]
	s_setprio 0
	s_barrier
	s_add_i32 s40, s40, 2
	s_add_u32 s18, s18, 0x100
	s_addc_u32 s19, s19, 0
	s_add_u32 s38, s38, 0x100
	s_addc_u32 s39, s39, 0
	s_cmp_gt_u32 s40, 13
	s_cbranch_scc0 .LBB0_950
	s_and_b64 vcc, exec, s[6:7]
	s_cbranch_vccz .LBB0_953
	s_barrier

; #define PG8_STAGE(bufoff, gbase, voff) do { _Pragma("unroll") for (int _i = 0; _i < 2; ++_i) \
;         __builtin_amdgcn_global_load_lds((const unsigned*)((const char*)(gbase) + (voff)[_i]), (LAS unsigned*)(lds + (bufoff) + ldsw + _i * 8192), 16, 0, 0); } while (0)
; #define PG8_LDA(dst, b, h) do { _Pragma("unroll") for (int m = 0; m < 4; ++m) _Pragma("unroll") for (int k = 0; k < 2; ++k) dst[m][k] = *(const LAS bf16x8*)(lds + PG8_SA(b, h) + aoff + m * 2048 + k * 1024); } while (0)
; #define PG8_LDB(dst, b, h) do { _Pragma("unroll") for (int n = 0; n < 2; ++n) _Pragma("unroll") for (int k = 0; k < 2; ++k) dst[n][k] = *(const LAS bf16x8*)(lds + PG8_SB(b, h) + boff + n * 2048 + k * 1024); } while (0)
; #define PG8_MMA(ai, bj, At, Bt_) do { __builtin_amdgcn_s_setprio(1); _Pragma("unroll") for (int m = 0; m < 4; ++m) _Pragma("unroll") for (int n = 0; n < 2; ++n) _Pragma("unroll") for (int k = 0; k < 2; ++k) \
;         acc[ai][bj][m][n] = __builtin_amdgcn_mfma_f32_16x16x32_bf16(Bt_[n][k], At[m][k], acc[ai][bj][m][n], 0, 0, 0); __builtin_amdgcn_s_setprio(0); } while (0)
; #define PG8_WAIT_V(n) asm volatile("s_waitcnt vmcnt(" #n ")" ::: "memory")
; #define PG8_WAIT_L(n) asm volatile("s_waitcnt lgkmcnt(" #n ")" ::: "memory")
; __device__ __forceinline__ void gemm_phase(LAS unsigned char* lds, const bf16_t* A, const bf16_t* Bt, int M, int N, int K, const Epi& E) {
;     ...
;         for (int t = 0; t < nt; t += 2) {
;             const bool last = (t == nt - 2);
;             const char* a1 = cA + (size_t)(t + 1) * kstep;
;             const char* a2 = last ? nA : cA + (size_t)(t + 2) * kstep; const char* b2 = last ? nB : cB + (size_t)(t + 2) * kstep;
;             const char* a3 = a2 + kstep; const char* b3 = b2 + kstep;
;             PG8_LDB(B0, 0, 0); PG8_LDB(B1, 0, 1); PG8_SCHED; PG8_LDA(At, 0, 0); PG8_STAGE(PG8_SA(1, 1), a1 + hstep, voffA);
;             PG8_WAIT_V(8); PG8_WAIT_L(0); PG8_BAR; PG8_MMA(0, 0, At, B0); PG8_MMA(0, 1, At, B1); PG8_BAR; PG8_SCHED;
;             PG8_LDA(At, 0, 1); PG8_STAGE(PG8_SB(0, 0), b2, voffB); PG8_STAGE(PG8_SB(0, 1), b2 + hstep, voffB); PG8_STAGE(PG8_SA(0, 0), a2, voffA);
;             PG8_WAIT_V(8); PG8_WAIT_L(0); PG8_BAR; PG8_MMA(1, 0, At, B0); PG8_MMA(1, 1, At, B1); PG8_BAR; PG8_SCHED;
;             PG8_LDB(B0, 1, 0); PG8_LDB(B1, 1, 1); PG8_SCHED; PG8_LDA(At, 1, 0); PG8_STAGE(PG8_SA(0, 1), a2 + hstep, voffA);
.LBB0_1111:
	s_add_u32 s20, s18, 0xfffc0080
	s_addc_u32 s21, s19, -1
	s_add_i32 s42, 0, 0x10000
	s_cmp_eq_u32 s41, 12
	s_cselect_b32 s23, s11, s21
	s_cselect_b32 s22, s15, s20
	v_add_u32_e32 v142, s42, v145
	s_cselect_b32 s21, s9, s40
	s_cselect_b32 s20, s38, s39
	s_add_i32 s44, 0, 0x14000
	ds_read_b128 v[148:151], v142
	ds_read_b128 v[152:155], v142 offset:1024
	ds_read_b128 v[156:159], v142 offset:2048
	ds_read_b128 v[160:163], v142 offset:3072
	v_add_u32_e32 v142, s44, v145
	ds_read_b128 v[164:167], v142
	ds_read_b128 v[168:171], v142 offset:1024
	ds_read_b128 v[172:175], v142 offset:2048
	ds_read_b128 v[176:179], v142 offset:3072
	v_lshl_add_u64 v[142:143], s[18:19], 0, v[138:139]
	s_add_i32 m0, s29, 0xc000
	ds_read_b128 v[180:183], v147
	ds_read_b128 v[202:205], v147 offset:1024
	ds_read_b128 v[206:209], v147 offset:2048
	ds_read_b128 v[210:213], v147 offset:3072
	ds_read_b128 v[214:217], v147 offset:4096
	ds_read_b128 v[218:221], v147 offset:5120
	ds_read_b128 v[222:225], v147 offset:6144
	ds_read_b128 v[226:229], v147 offset:7168
	global_load_lds_dwordx4 v[142:143], off
	v_lshl_add_u64 v[142:143], s[18:19], 0, v[140:141]
	s_add_i32 m0, s29, 0xe000
	s_nop 0
	global_load_lds_dwordx4 v[142:143], off
	s_waitcnt vmcnt(8)
	s_waitcnt lgkmcnt(0)
	s_barrier
	s_setprio 1
	s_waitcnt lgkmcnt(0)
	v_mfma_f32_16x16x32_bf16 v[126:129], v[148:151], v[180:183], v[126:129]
	v_mfma_f32_16x16x32_bf16 v[122:125], v[156:159], v[180:183], v[122:125]
	v_mfma_f32_16x16x32_bf16 v[118:121], v[148:151], v[206:209], v[118:121]
	v_mfma_f32_16x16x32_bf16 v[114:117], v[156:159], v[206:209], v[114:117]
	v_mfma_f32_16x16x32_bf16 v[102:105], v[148:151], v[214:217], v[102:105]
	v_mfma_f32_16x16x32_bf16 v[98:101], v[156:159], v[214:217], v[98:101]
	v_mfma_f32_16x16x32_bf16 v[86:89], v[148:151], v[222:225], v[86:89]
	v_mfma_f32_16x16x32_bf16 v[82:85], v[156:159], v[222:225], v[82:85]
	v_mfma_f32_16x16x32_bf16 v[126:129], v[152:155], v[202:205], v[126:129]
	v_mfma_f32_16x16x32_bf16 v[122:125], v[160:163], v[202:205], v[122:125]
	v_mfma_f32_16x16x32_bf16 v[118:121], v[152:155], v[210:213], v[118:121]
	v_mfma_f32_16x16x32_bf16 v[114:117], v[160:163], v[210:213], v[114:117]
	v_mfma_f32_16x16x32_bf16 v[102:105], v[152:155], v[218:221], v[102:105]
	v_mfma_f32_16x16x32_bf16 v[98:101], v[160:163], v[218:221], v[98:101]
	v_mfma_f32_16x16x32_bf16 v[86:89], v[152:155], v[226:229], v[86:89]
	v_mfma_f32_16x16x32_bf16 v[82:85], v[160:163], v[226:229], v[82:85]
	v_mfma_f32_16x16x32_bf16 v[110:113], v[164:167], v[180:183], v[110:113]
	v_mfma_f32_16x16x32_bf16 v[106:109], v[172:175], v[180:183], v[106:109]
	v_mfma_f32_16x16x32_bf16 v[94:97], v[164:167], v[206:209], v[94:97]
	v_mfma_f32_16x16x32_bf16 v[90:93], v[172:175], v[206:209], v[90:93]
	v_mfma_f32_16x16x32_bf16 v[78:81], v[164:167], v[214:217], v[78:81]
	v_mfma_f32_16x16x32_bf16 v[74:77], v[172:175], v[214:217], v[74:77]
	v_mfma_f32_16x16x32_bf16 v[70:73], v[164:167], v[222:225], v[70:73]
	v_mfma_f32_16x16x32_bf16 v[66:69], v[172:175], v[222:225], v[66:69]
	v_mfma_f32_16x16x32_bf16 v[110:113], v[168:171], v[202:205], v[110:113]
	v_mfma_f32_16x16x32_bf16 v[106:109], v[176:179], v[202:205], v[106:109]
	v_mfma_f32_16x16x32_bf16 v[94:97], v[168:171], v[210:213], v[94:97]
	v_mfma_f32_16x16x32_bf16 v[90:93], v[176:179], v[210:213], v[90:93]
	v_mfma_f32_16x16x32_bf16 v[78:81], v[168:171], v[218:221], v[78:81]
	v_mfma_f32_16x16x32_bf16 v[74:77], v[176:179], v[218:221], v[74:77]
	v_mfma_f32_16x16x32_bf16 v[70:73], v[168:171], v[226:229], v[70:73]
	v_mfma_f32_16x16x32_bf16 v[66:69], v[176:179], v[226:229], v[66:69]
	s_setprio 0
	s_barrier
	s_add_i32 s42, s42, s28
	v_lshl_add_u64 v[142:143], s[20:21], 0, v[0:1]
	s_mov_b32 m0, s42
	ds_read_b128 v[180:183], v147 offset:16384
	ds_read_b128 v[202:205], v147 offset:17408
	ds_read_b128 v[206:209], v147 offset:18432
	ds_read_b128 v[210:213], v147 offset:19456
	ds_read_b128 v[214:217], v147 offset:20480
	ds_read_b128 v[218:221], v147 offset:21504
	ds_read_b128 v[222:225], v147 offset:22528
	ds_read_b128 v[226:229], v147 offset:23552
	global_load_lds_dwordx4 v[142:143], off
	s_add_i32 m0, s42, 0x2000
	s_add_u32 s42, s20, 0x40000
	v_lshl_add_u64 v[184:185], s[20:21], 0, v[134:135]
	s_addc_u32 s43, s21, 0
	s_add_i32 s44, s44, s28
	global_load_lds_dwordx4 v[184:185], off
	v_lshl_add_u64 v[230:231], s[42:43], 0, v[0:1]
	s_mov_b32 m0, s44
	v_lshl_add_u64 v[232:233], s[22:23], 0, v[132:133]
	global_load_lds_dwordx4 v[230:231], off
	v_lshl_add_u64 v[230:231], s[42:43], 0, v[134:135]
	s_add_i32 m0, s44, 0x2000
	s_nop 0
	global_load_lds_dwordx4 v[230:231], off
	v_lshl_add_u64 v[230:231], s[22:23], 0, v[130:131]
	s_mov_b32 m0, s29
	s_nop 0
	global_load_lds_dwordx4 v[230:231], off
	s_mov_b32 m0, s30
	s_nop 0
	global_load_lds_dwordx4 v[232:233], off
	s_waitcnt vmcnt(8)
	s_waitcnt lgkmcnt(0)
	s_barrier
; #define PG8_STAGE(bufoff, gbase, voff) do { _Pragma("unroll") for (int _i = 0; _i < 2; ++_i) \
;         __builtin_amdgcn_global_load_lds((const unsigned*)((const char*)(gbase) + (voff)[_i]), (LAS unsigned*)(lds + (bufoff) + ldsw + _i * 8192), 16, 0, 0); } while (0)
; #define PG8_LDA(dst, b, h) do { _Pragma("unroll") for (int m = 0; m < 4; ++m) _Pragma("unroll") for (int k = 0; k < 2; ++k) dst[m][k] = *(const LAS bf16x8*)(lds + PG8_SA(b, h) + aoff + m * 2048 + k * 1024); } while (0)
; #define PG8_LDB(dst, b, h) do { _Pragma("unroll") for (int n = 0; n < 2; ++n) _Pragma("unroll") for (int k = 0; k < 2; ++k) dst[n][k] = *(const LAS bf16x8*)(lds + PG8_SB(b, h) + boff + n * 2048 + k * 1024); } while (0)
; #define PG8_MMA(ai, bj, At, Bt_) do { __builtin_amdgcn_s_setprio(1); _Pragma("unroll") for (int m = 0; m < 4; ++m) _Pragma("unroll") for (int n = 0; n < 2; ++n) _Pragma("unroll") for (int k = 0; k < 2; ++k) \
;         acc[ai][bj][m][n] = __builtin_amdgcn_mfma_f32_16x16x32_bf16(Bt_[n][k], At[m][k], acc[ai][bj][m][n], 0, 0, 0); __builtin_amdgcn_s_setprio(0); } while (0)
; #define PG8_WAIT_V(n) asm volatile("s_waitcnt vmcnt(" #n ")" ::: "memory")
; #define PG8_WAIT_L(n) asm volatile("s_waitcnt lgkmcnt(" #n ")" ::: "memory")
; #define PG8_BAR __builtin_amdgcn_s_barrier()
; #define PG8_SCHED __builtin_amdgcn_sched_barrier(0)
; __device__ __forceinline__ void gemm_phase(LAS unsigned char* lds, const bf16_t* A, const bf16_t* Bt, int M, int N, int K, const Epi& E) {
;     ...
;             PG8_WAIT_V(8); PG8_WAIT_L(0); PG8_BAR; PG8_MMA(1, 0, At, B0); PG8_MMA(1, 1, At, B1); PG8_BAR; PG8_SCHED;
;             PG8_LDB(B0, 1, 0); PG8_LDB(B1, 1, 1); PG8_SCHED; PG8_LDA(At, 1, 0); PG8_STAGE(PG8_SA(0, 1), a2 + hstep, voffA);
;             PG8_WAIT_V(8); PG8_WAIT_L(0); PG8_BAR; PG8_MMA(0, 0, At, B0); PG8_MMA(0, 1, At, B1); PG8_BAR; PG8_SCHED;
	s_setprio 1
	s_waitcnt lgkmcnt(0)
	v_mfma_f32_16x16x32_bf16 v[62:65], v[148:151], v[180:183], v[62:65]
	v_mfma_f32_16x16x32_bf16 v[58:61], v[156:159], v[180:183], v[58:61]
	v_mfma_f32_16x16x32_bf16 v[54:57], v[148:151], v[206:209], v[54:57]
	v_mfma_f32_16x16x32_bf16 v[50:53], v[156:159], v[206:209], v[50:53]
	v_mfma_f32_16x16x32_bf16 v[38:41], v[148:151], v[214:217], v[38:41]
	v_mfma_f32_16x16x32_bf16 v[34:37], v[156:159], v[214:217], v[34:37]
	v_mfma_f32_16x16x32_bf16 v[22:25], v[148:151], v[222:225], v[22:25]
	v_mfma_f32_16x16x32_bf16 v[18:21], v[156:159], v[222:225], v[18:21]
	v_mfma_f32_16x16x32_bf16 v[62:65], v[152:155], v[202:205], v[62:65]
	v_mfma_f32_16x16x32_bf16 v[58:61], v[160:163], v[202:205], v[58:61]
	v_mfma_f32_16x16x32_bf16 v[54:57], v[152:155], v[210:213], v[54:57]
	v_mfma_f32_16x16x32_bf16 v[50:53], v[160:163], v[210:213], v[50:53]
	v_mfma_f32_16x16x32_bf16 v[38:41], v[152:155], v[218:221], v[38:41]
	v_mfma_f32_16x16x32_bf16 v[34:37], v[160:163], v[218:221], v[34:37]
	v_mfma_f32_16x16x32_bf16 v[22:25], v[152:155], v[226:229], v[22:25]
	v_mfma_f32_16x16x32_bf16 v[18:21], v[160:163], v[226:229], v[18:21]
	v_mfma_f32_16x16x32_bf16 v[46:49], v[164:167], v[180:183], v[46:49]
	v_mfma_f32_16x16x32_bf16 v[42:45], v[172:175], v[180:183], v[42:45]
	v_mfma_f32_16x16x32_bf16 v[30:33], v[164:167], v[206:209], v[30:33]
	v_mfma_f32_16x16x32_bf16 v[26:29], v[172:175], v[206:209], v[26:29]
	v_mfma_f32_16x16x32_bf16 v[14:17], v[164:167], v[214:217], v[14:17]
	v_mfma_f32_16x16x32_bf16 v[10:13], v[172:175], v[214:217], v[10:13]
	v_mfma_f32_16x16x32_bf16 v[6:9], v[164:167], v[222:225], v[6:9]
	v_mfma_f32_16x16x32_bf16 v[2:5], v[172:175], v[222:225], v[2:5]
	v_mfma_f32_16x16x32_bf16 v[46:49], v[168:171], v[202:205], v[46:49]
	v_mfma_f32_16x16x32_bf16 v[42:45], v[176:179], v[202:205], v[42:45]
	v_mfma_f32_16x16x32_bf16 v[30:33], v[168:171], v[210:213], v[30:33]
	v_mfma_f32_16x16x32_bf16 v[26:29], v[176:179], v[210:213], v[26:29]
	v_mfma_f32_16x16x32_bf16 v[14:17], v[168:171], v[218:221], v[14:17]
	v_mfma_f32_16x16x32_bf16 v[10:13], v[176:179], v[218:221], v[10:13]
	v_mfma_f32_16x16x32_bf16 v[6:9], v[168:171], v[226:229], v[6:9]
	v_mfma_f32_16x16x32_bf16 v[2:5], v[176:179], v[226:229], v[2:5]
	s_setprio 0
	s_barrier
	s_add_i32 s42, 0, 0x18000
	s_add_i32 s43, 0, 0x1c000
	v_add_u32_e32 v160, s42, v145
	v_add_u32_e32 v176, s43, v145
	ds_read_b128 v[148:151], v160
	ds_read_b128 v[152:155], v160 offset:1024
	ds_read_b128 v[156:159], v160 offset:2048
	ds_read_b128 v[160:163], v160 offset:3072
	ds_read_b128 v[164:167], v176
	ds_read_b128 v[168:171], v176 offset:1024
	ds_read_b128 v[172:175], v176 offset:2048
	ds_read_b128 v[176:179], v176 offset:3072
	s_add_u32 s22, s22, 0x40000
	s_addc_u32 s23, s23, 0
	s_mov_b32 m0, s31
	v_lshl_add_u64 v[240:241], s[22:23], 0, v[130:131]
	ds_read_b128 v[180:183], v147 offset:32768
	ds_read_b128 v[202:205], v147 offset:33792
	ds_read_b128 v[206:209], v147 offset:34816
	ds_read_b128 v[210:213], v147 offset:35840
	ds_read_b128 v[214:217], v147 offset:36864
	ds_read_b128 v[218:221], v147 offset:37888
	ds_read_b128 v[222:225], v147 offset:38912
	ds_read_b128 v[226:229], v147 offset:39936
	global_load_lds_dwordx4 v[240:241], off
	v_lshl_add_u64 v[240:241], s[22:23], 0, v[132:133]
	s_mov_b32 m0, s33
	s_nop 0
	global_load_lds_dwordx4 v[240:241], off
	s_waitcnt vmcnt(8)
	s_waitcnt lgkmcnt(0)
	s_barrier
	s_setprio 1
	s_waitcnt lgkmcnt(0)
	v_mfma_f32_16x16x32_bf16 v[126:129], v[148:151], v[180:183], v[126:129]
	v_mfma_f32_16x16x32_bf16 v[122:125], v[156:159], v[180:183], v[122:125]
	v_mfma_f32_16x16x32_bf16 v[118:121], v[148:151], v[206:209], v[118:121]
	v_mfma_f32_16x16x32_bf16 v[114:117], v[156:159], v[206:209], v[114:117]
	v_mfma_f32_16x16x32_bf16 v[102:105], v[148:151], v[214:217], v[102:105]
	v_mfma_f32_16x16x32_bf16 v[98:101], v[156:159], v[214:217], v[98:101]
	v_mfma_f32_16x16x32_bf16 v[86:89], v[148:151], v[222:225], v[86:89]
	v_mfma_f32_16x16x32_bf16 v[82:85], v[156:159], v[222:225], v[82:85]
	v_mfma_f32_16x16x32_bf16 v[126:129], v[152:155], v[202:205], v[126:129]
	v_mfma_f32_16x16x32_bf16 v[122:125], v[160:163], v[202:205], v[122:125]
	v_mfma_f32_16x16x32_bf16 v[118:121], v[152:155], v[210:213], v[118:121]
	v_mfma_f32_16x16x32_bf16 v[114:117], v[160:163], v[210:213], v[114:117]
	v_mfma_f32_16x16x32_bf16 v[102:105], v[152:155], v[218:221], v[102:105]
	v_mfma_f32_16x16x32_bf16 v[98:101], v[160:163], v[218:221], v[98:101]
	v_mfma_f32_16x16x32_bf16 v[86:89], v[152:155], v[226:229], v[86:89]
	v_mfma_f32_16x16x32_bf16 v[82:85], v[160:163], v[226:229], v[82:85]
	v_mfma_f32_16x16x32_bf16 v[110:113], v[164:167], v[180:183], v[110:113]
	v_mfma_f32_16x16x32_bf16 v[106:109], v[172:175], v[180:183], v[106:109]
	v_mfma_f32_16x16x32_bf16 v[94:97], v[164:167], v[206:209], v[94:97]
	v_mfma_f32_16x16x32_bf16 v[90:93], v[172:175], v[206:209], v[90:93]
	v_mfma_f32_16x16x32_bf16 v[78:81], v[164:167], v[214:217], v[78:81]
	v_mfma_f32_16x16x32_bf16 v[74:77], v[172:175], v[214:217], v[74:77]
	v_mfma_f32_16x16x32_bf16 v[70:73], v[164:167], v[222:225], v[70:73]
	v_mfma_f32_16x16x32_bf16 v[66:69], v[172:175], v[222:225], v[66:69]
	v_mfma_f32_16x16x32_bf16 v[110:113], v[168:171], v[202:205], v[110:113]
	v_mfma_f32_16x16x32_bf16 v[106:109], v[176:179], v[202:205], v[106:109]
	v_mfma_f32_16x16x32_bf16 v[94:97], v[168:171], v[210:213], v[94:97]
	v_mfma_f32_16x16x32_bf16 v[90:93], v[176:179], v[210:213], v[90:93]
	v_mfma_f32_16x16x32_bf16 v[78:81], v[168:171], v[218:221], v[78:81]
	v_mfma_f32_16x16x32_bf16 v[74:77], v[176:179], v[218:221], v[74:77]
	v_mfma_f32_16x16x32_bf16 v[70:73], v[168:171], v[226:229], v[70:73]
	v_mfma_f32_16x16x32_bf16 v[66:69], v[176:179], v[226:229], v[66:69]
	s_setprio 0
	s_barrier
; #define PG8_STAGE(bufoff, gbase, voff) do { _Pragma("unroll") for (int _i = 0; _i < 2; ++_i) \
;         __builtin_amdgcn_global_load_lds((const unsigned*)((const char*)(gbase) + (voff)[_i]), (LAS unsigned*)(lds + (bufoff) + ldsw + _i * 8192), 16, 0, 0); } while (0)
; #define PG8_LDA(dst, b, h) do { _Pragma("unroll") for (int m = 0; m < 4; ++m) _Pragma("unroll") for (int k = 0; k < 2; ++k) dst[m][k] = *(const LAS bf16x8*)(lds + PG8_SA(b, h) + aoff + m * 2048 + k * 1024); } while (0)
; #define PG8_MMA(ai, bj, At, Bt_) do { __builtin_amdgcn_s_setprio(1); _Pragma("unroll") for (int m = 0; m < 4; ++m) _Pragma("unroll") for (int n = 0; n < 2; ++n) _Pragma("unroll") for (int k = 0; k < 2; ++k) \
;         acc[ai][bj][m][n] = __builtin_amdgcn_mfma_f32_16x16x32_bf16(Bt_[n][k], At[m][k], acc[ai][bj][m][n], 0, 0, 0); __builtin_amdgcn_s_setprio(0); } while (0)
; #define PG8_WAIT_V(n) asm volatile("s_waitcnt vmcnt(" #n ")" ::: "memory")
; #define PG8_WAIT_L(n) asm volatile("s_waitcnt lgkmcnt(" #n ")" ::: "memory")
; #define PG8_BAR __builtin_amdgcn_s_barrier()
; #define PG8_SCHED __builtin_amdgcn_sched_barrier(0)
; __device__ __forceinline__ void gemm_phase(LAS unsigned char* lds, const bf16_t* A, const bf16_t* Bt, int M, int N, int K, const Epi& E) {
;     ...
;             PG8_LDA(At, 1, 1); PG8_STAGE(PG8_SB(1, 0), b3, voffB); PG8_STAGE(PG8_SB(1, 1), b3 + hstep, voffB); PG8_STAGE(PG8_SA(1, 0), a3, voffA);
;             PG8_WAIT_V(8); PG8_WAIT_L(0); PG8_BAR; PG8_MMA(1, 0, At, B0); PG8_MMA(1, 1, At, B1); PG8_BAR; PG8_SCHED;
;         }
;         if (wr == 0) PG8_BAR;
	s_add_i32 s22, s42, s28
	v_lshl_add_u64 v[142:143], v[142:143], 0, s[46:47]
	s_mov_b32 m0, s22
	ds_read_b128 v[180:183], v147 offset:49152
	ds_read_b128 v[202:205], v147 offset:50176
	ds_read_b128 v[206:209], v147 offset:51200
	ds_read_b128 v[210:213], v147 offset:52224
	ds_read_b128 v[214:217], v147 offset:53248
	ds_read_b128 v[218:221], v147 offset:54272
	ds_read_b128 v[222:225], v147 offset:55296
	ds_read_b128 v[226:229], v147 offset:56320
	global_load_lds_dwordx4 v[142:143], off
	s_add_i32 m0, s22, 0x2000
	s_add_u32 s20, s20, 0x40080
	v_lshl_add_u64 v[142:143], v[184:185], 0, s[46:47]
	s_addc_u32 s21, s21, 0
	s_add_i32 s22, s43, s28
	global_load_lds_dwordx4 v[142:143], off
	v_lshl_add_u64 v[142:143], s[20:21], 0, v[0:1]
	s_mov_b32 m0, s22
	s_nop 0
	global_load_lds_dwordx4 v[142:143], off
	v_lshl_add_u64 v[142:143], s[20:21], 0, v[134:135]
	s_add_i32 m0, s22, 0x2000
	s_nop 0
	global_load_lds_dwordx4 v[142:143], off
	v_lshl_add_u64 v[142:143], v[230:231], 0, s[46:47]
	s_mov_b32 m0, s34
	s_nop 0
	global_load_lds_dwordx4 v[142:143], off
	v_lshl_add_u64 v[142:143], v[232:233], 0, s[46:47]
	s_mov_b32 m0, s35
	s_nop 0
	global_load_lds_dwordx4 v[142:143], off
	s_waitcnt vmcnt(8)
	s_waitcnt lgkmcnt(0)
	s_barrier
	s_setprio 1
	s_waitcnt lgkmcnt(0)
	v_mfma_f32_16x16x32_bf16 v[62:65], v[148:151], v[180:183], v[62:65]
	v_mfma_f32_16x16x32_bf16 v[58:61], v[156:159], v[180:183], v[58:61]
	v_mfma_f32_16x16x32_bf16 v[54:57], v[148:151], v[206:209], v[54:57]
	v_mfma_f32_16x16x32_bf16 v[50:53], v[156:159], v[206:209], v[50:53]
	v_mfma_f32_16x16x32_bf16 v[38:41], v[148:151], v[214:217], v[38:41]
	v_mfma_f32_16x16x32_bf16 v[34:37], v[156:159], v[214:217], v[34:37]
	v_mfma_f32_16x16x32_bf16 v[22:25], v[148:151], v[222:225], v[22:25]
	v_mfma_f32_16x16x32_bf16 v[18:21], v[156:159], v[222:225], v[18:21]
	v_mfma_f32_16x16x32_bf16 v[62:65], v[152:155], v[202:205], v[62:65]
	v_mfma_f32_16x16x32_bf16 v[58:61], v[160:163], v[202:205], v[58:61]
	v_mfma_f32_16x16x32_bf16 v[54:57], v[152:155], v[210:213], v[54:57]
	v_mfma_f32_16x16x32_bf16 v[50:53], v[160:163], v[210:213], v[50:53]
	v_mfma_f32_16x16x32_bf16 v[38:41], v[152:155], v[218:221], v[38:41]
	v_mfma_f32_16x16x32_bf16 v[34:37], v[160:163], v[218:221], v[34:37]
	v_mfma_f32_16x16x32_bf16 v[22:25], v[152:155], v[226:229], v[22:25]
	v_mfma_f32_16x16x32_bf16 v[18:21], v[160:163], v[226:229], v[18:21]
	v_mfma_f32_16x16x32_bf16 v[46:49], v[164:167], v[180:183], v[46:49]
	v_mfma_f32_16x16x32_bf16 v[42:45], v[172:175], v[180:183], v[42:45]
	v_mfma_f32_16x16x32_bf16 v[30:33], v[164:167], v[206:209], v[30:33]
	v_mfma_f32_16x16x32_bf16 v[26:29], v[172:175], v[206:209], v[26:29]
	v_mfma_f32_16x16x32_bf16 v[14:17], v[164:167], v[214:217], v[14:17]
	v_mfma_f32_16x16x32_bf16 v[10:13], v[172:175], v[214:217], v[10:13]
	v_mfma_f32_16x16x32_bf16 v[6:9], v[164:167], v[222:225], v[6:9]
	v_mfma_f32_16x16x32_bf16 v[2:5], v[172:175], v[222:225], v[2:5]
	v_mfma_f32_16x16x32_bf16 v[46:49], v[168:171], v[202:205], v[46:49]
	v_mfma_f32_16x16x32_bf16 v[42:45], v[176:179], v[202:205], v[42:45]
	v_mfma_f32_16x16x32_bf16 v[30:33], v[168:171], v[210:213], v[30:33]
	v_mfma_f32_16x16x32_bf16 v[26:29], v[176:179], v[210:213], v[26:29]
	v_mfma_f32_16x16x32_bf16 v[14:17], v[168:171], v[218:221], v[14:17]
	v_mfma_f32_16x16x32_bf16 v[10:13], v[176:179], v[218:221], v[10:13]
	v_mfma_f32_16x16x32_bf16 v[6:9], v[168:171], v[226:229], v[6:9]
	v_mfma_f32_16x16x32_bf16 v[2:5], v[176:179], v[226:229], v[2:5]
	s_setprio 0
	s_barrier
	s_add_i32 s41, s41, 2
	s_add_u32 s18, s18, 0x100
	s_addc_u32 s19, s19, 0
	s_add_u32 s39, s39, 0x100
	s_addc_u32 s40, s40, 0
	s_cmp_gt_u32 s41, 13
	s_cbranch_scc0 .LBB0_1111
	s_and_b64 vcc, exec, s[4:5]
	s_cbranch_vccz .LBB0_1114
	s_barrier

; #define PG8_STAGE(bufoff, gbase, voff) do { _Pragma("unroll") for (int _i = 0; _i < 2; ++_i) \
;         __builtin_amdgcn_global_load_lds((const unsigned*)((const char*)(gbase) + (voff)[_i]), (LAS unsigned*)(lds + (bufoff) + ldsw + _i * 8192), 16, 0, 0); } while (0)
; #define PG8_LDA(dst, b, h) do { _Pragma("unroll") for (int m = 0; m < 4; ++m) _Pragma("unroll") for (int k = 0; k < 2; ++k) dst[m][k] = *(const LAS bf16x8*)(lds + PG8_SA(b, h) + aoff + m * 2048 + k * 1024); } while (0)
; #define PG8_LDB(dst, b, h) do { _Pragma("unroll") for (int n = 0; n < 2; ++n) _Pragma("unroll") for (int k = 0; k < 2; ++k) dst[n][k] = *(const LAS bf16x8*)(lds + PG8_SB(b, h) + boff + n * 2048 + k * 1024); } while (0)
; #define PG8_MMA(ai, bj, At, Bt_) do { __builtin_amdgcn_s_setprio(1); _Pragma("unroll") for (int m = 0; m < 4; ++m) _Pragma("unroll") for (int n = 0; n < 2; ++n) _Pragma("unroll") for (int k = 0; k < 2; ++k) \
;         acc[ai][bj][m][n] = __builtin_amdgcn_mfma_f32_16x16x32_bf16(Bt_[n][k], At[m][k], acc[ai][bj][m][n], 0, 0, 0); __builtin_amdgcn_s_setprio(0); } while (0)
; #define PG8_WAIT_V(n) asm volatile("s_waitcnt vmcnt(" #n ")" ::: "memory")
; #define PG8_WAIT_L(n) asm volatile("s_waitcnt lgkmcnt(" #n ")" ::: "memory")
; __device__ __forceinline__ void gemm_phase(LAS unsigned char* lds, const bf16_t* A, const bf16_t* Bt, int M, int N, int K, const Epi& E) {
;     ...
;         for (int t = 0; t < nt; t += 2) {
;             const bool last = (t == nt - 2);
;             const char* a1 = cA + (size_t)(t + 1) * kstep;
;             const char* a2 = last ? nA : cA + (size_t)(t + 2) * kstep; const char* b2 = last ? nB : cB + (size_t)(t + 2) * kstep;
;             const char* a3 = a2 + kstep; const char* b3 = b2 + kstep;
;             PG8_LDB(B0, 0, 0); PG8_LDB(B1, 0, 1); PG8_SCHED; PG8_LDA(At, 0, 0); PG8_STAGE(PG8_SA(1, 1), a1 + hstep, voffA);
;             PG8_WAIT_V(8); PG8_WAIT_L(0); PG8_BAR; PG8_MMA(0, 0, At, B0); PG8_MMA(0, 1, At, B1); PG8_BAR; PG8_SCHED;
;             PG8_LDA(At, 0, 1); PG8_STAGE(PG8_SB(0, 0), b2, voffB); PG8_STAGE(PG8_SB(0, 1), b2 + hstep, voffB); PG8_STAGE(PG8_SA(0, 0), a2, voffA);
;             PG8_WAIT_V(8); PG8_WAIT_L(0); PG8_BAR; PG8_MMA(1, 0, At, B0); PG8_MMA(1, 1, At, B1); PG8_BAR; PG8_SCHED;
;             PG8_LDB(B0, 1, 0); PG8_LDB(B1, 1, 1); PG8_SCHED; PG8_LDA(At, 1, 0); PG8_STAGE(PG8_SA(0, 1), a2 + hstep, voffA);
.LBB0_2541:
	s_add_u32 s20, s18, 0xfffc0080
	s_addc_u32 s21, s19, -1
	s_add_i32 s43, 0, 0x10000
	s_cmp_eq_u32 s42, 12
	s_cselect_b32 s23, s1, s21
	s_cselect_b32 s22, s3, s20
	s_cselect_b32 s21, s11, s41
	s_cselect_b32 s20, s13, s40
	s_add_i32 s46, 0, 0x14000
	v_add_u32_e32 v118, s43, v249
	v_add_u32_e32 v158, s46, v249
	ds_read_b128 v[102:105], v118
	ds_read_b128 v[110:113], v118 offset:1024
	ds_read_b128 v[114:117], v118 offset:2048
	ds_read_b128 v[118:121], v118 offset:3072
	ds_read_b128 v[146:149], v158
	ds_read_b128 v[150:153], v158 offset:1024
	ds_read_b128 v[154:157], v158 offset:2048
	ds_read_b128 v[158:161], v158 offset:3072
	v_lshl_add_u64 v[220:221], s[18:19], 0, v[208:209]
	s_add_i32 m0, s29, 0xc000
	ds_read_b128 v[162:165], v240
	ds_read_b128 v[166:169], v240 offset:1024
	ds_read_b128 v[170:173], v240 offset:2048
	ds_read_b128 v[174:177], v240 offset:3072
	ds_read_b128 v[178:181], v240 offset:4096
	ds_read_b128 v[182:185], v240 offset:5120
	ds_read_b128 v[212:215], v240 offset:6144
	ds_read_b128 v[216:219], v240 offset:7168
	global_load_lds_dwordx4 v[220:221], off
	v_lshl_add_u64 v[220:221], s[18:19], 0, v[210:211]
	s_add_i32 m0, s29, 0xe000
	s_nop 0
	global_load_lds_dwordx4 v[220:221], off
	s_waitcnt vmcnt(8)
	s_waitcnt lgkmcnt(0)
	s_barrier
	s_setprio 1
	s_waitcnt lgkmcnt(0)
	v_mfma_f32_16x16x32_bf16 v[142:145], v[102:105], v[162:165], v[142:145]
	v_mfma_f32_16x16x32_bf16 v[138:141], v[114:117], v[162:165], v[138:141]
	v_mfma_f32_16x16x32_bf16 v[126:129], v[102:105], v[170:173], v[126:129]
	v_mfma_f32_16x16x32_bf16 v[122:125], v[114:117], v[170:173], v[122:125]
	v_mfma_f32_16x16x32_bf16 v[94:97], v[102:105], v[178:181], v[94:97]
	v_mfma_f32_16x16x32_bf16 v[90:93], v[114:117], v[178:181], v[90:93]
	v_mfma_f32_16x16x32_bf16 v[78:81], v[102:105], v[212:215], v[78:81]
	v_mfma_f32_16x16x32_bf16 v[74:77], v[114:117], v[212:215], v[74:77]
	v_mfma_f32_16x16x32_bf16 v[142:145], v[110:113], v[166:169], v[142:145]
	v_mfma_f32_16x16x32_bf16 v[138:141], v[118:121], v[166:169], v[138:141]
	v_mfma_f32_16x16x32_bf16 v[126:129], v[110:113], v[174:177], v[126:129]
	v_mfma_f32_16x16x32_bf16 v[122:125], v[118:121], v[174:177], v[122:125]
	v_mfma_f32_16x16x32_bf16 v[94:97], v[110:113], v[182:185], v[94:97]
	v_mfma_f32_16x16x32_bf16 v[90:93], v[118:121], v[182:185], v[90:93]
	v_mfma_f32_16x16x32_bf16 v[78:81], v[110:113], v[216:219], v[78:81]
	v_mfma_f32_16x16x32_bf16 v[74:77], v[118:121], v[216:219], v[74:77]
	v_mfma_f32_16x16x32_bf16 v[134:137], v[146:149], v[162:165], v[134:137]
	v_mfma_f32_16x16x32_bf16 v[130:133], v[154:157], v[162:165], v[130:133]
	v_mfma_f32_16x16x32_bf16 v[106:109], v[146:149], v[170:173], v[106:109]
	v_mfma_f32_16x16x32_bf16 v[98:101], v[154:157], v[170:173], v[98:101]
	v_mfma_f32_16x16x32_bf16 v[86:89], v[146:149], v[178:181], v[86:89]
	v_mfma_f32_16x16x32_bf16 v[82:85], v[154:157], v[178:181], v[82:85]
	v_mfma_f32_16x16x32_bf16 v[70:73], v[146:149], v[212:215], v[70:73]
	v_mfma_f32_16x16x32_bf16 v[66:69], v[154:157], v[212:215], v[66:69]
	v_mfma_f32_16x16x32_bf16 v[134:137], v[150:153], v[166:169], v[134:137]
	v_mfma_f32_16x16x32_bf16 v[130:133], v[158:161], v[166:169], v[130:133]
	v_mfma_f32_16x16x32_bf16 v[106:109], v[150:153], v[174:177], v[106:109]
	v_mfma_f32_16x16x32_bf16 v[98:101], v[158:161], v[174:177], v[98:101]
	v_mfma_f32_16x16x32_bf16 v[86:89], v[150:153], v[182:185], v[86:89]
	v_mfma_f32_16x16x32_bf16 v[82:85], v[158:161], v[182:185], v[82:85]
	v_mfma_f32_16x16x32_bf16 v[70:73], v[150:153], v[216:219], v[70:73]
	v_mfma_f32_16x16x32_bf16 v[66:69], v[158:161], v[216:219], v[66:69]
	s_setprio 0
	s_barrier
	s_add_i32 s43, s43, s28
	v_lshl_add_u64 v[220:221], s[20:21], 0, v[0:1]
	s_mov_b32 m0, s43
	ds_read_b128 v[162:165], v240 offset:16384
	ds_read_b128 v[166:169], v240 offset:17408
	ds_read_b128 v[170:173], v240 offset:18432
	ds_read_b128 v[174:177], v240 offset:19456
	ds_read_b128 v[178:181], v240 offset:20480
	ds_read_b128 v[182:185], v240 offset:21504
	ds_read_b128 v[212:215], v240 offset:22528
	ds_read_b128 v[216:219], v240 offset:23552
	global_load_lds_dwordx4 v[220:221], off
	s_add_i32 m0, s43, 0x2000
	s_add_u32 s44, s20, 0x40000
	v_lshl_add_u64 v[222:223], s[20:21], 0, v[206:207]
	s_addc_u32 s45, s21, 0
	s_add_i32 s43, s46, s28
	global_load_lds_dwordx4 v[222:223], off
	v_lshl_add_u64 v[224:225], s[44:45], 0, v[0:1]
	s_mov_b32 m0, s43
	v_lshl_add_u64 v[226:227], s[22:23], 0, v[204:205]
	global_load_lds_dwordx4 v[224:225], off
	v_lshl_add_u64 v[224:225], s[44:45], 0, v[206:207]
	s_add_i32 m0, s43, 0x2000
	s_nop 0
	global_load_lds_dwordx4 v[224:225], off
	v_lshl_add_u64 v[224:225], s[22:23], 0, v[202:203]
	s_mov_b32 m0, s29
	s_nop 0
	global_load_lds_dwordx4 v[224:225], off
	s_mov_b32 m0, s30
	s_nop 0
	global_load_lds_dwordx4 v[226:227], off
	s_waitcnt vmcnt(8)
	s_waitcnt lgkmcnt(0)
	s_barrier
; #define PG8_STAGE(bufoff, gbase, voff) do { _Pragma("unroll") for (int _i = 0; _i < 2; ++_i) \
;         __builtin_amdgcn_global_load_lds((const unsigned*)((const char*)(gbase) + (voff)[_i]), (LAS unsigned*)(lds + (bufoff) + ldsw + _i * 8192), 16, 0, 0); } while (0)
; #define PG8_LDA(dst, b, h) do { _Pragma("unroll") for (int m = 0; m < 4; ++m) _Pragma("unroll") for (int k = 0; k < 2; ++k) dst[m][k] = *(const LAS bf16x8*)(lds + PG8_SA(b, h) + aoff + m * 2048 + k * 1024); } while (0)
; #define PG8_LDB(dst, b, h) do { _Pragma("unroll") for (int n = 0; n < 2; ++n) _Pragma("unroll") for (int k = 0; k < 2; ++k) dst[n][k] = *(const LAS bf16x8*)(lds + PG8_SB(b, h) + boff + n * 2048 + k * 1024); } while (0)
; #define PG8_MMA(ai, bj, At, Bt_) do { __builtin_amdgcn_s_setprio(1); _Pragma("unroll") for (int m = 0; m < 4; ++m) _Pragma("unroll") for (int n = 0; n < 2; ++n) _Pragma("unroll") for (int k = 0; k < 2; ++k) \
;         acc[ai][bj][m][n] = __builtin_amdgcn_mfma_f32_16x16x32_bf16(Bt_[n][k], At[m][k], acc[ai][bj][m][n], 0, 0, 0); __builtin_amdgcn_s_setprio(0); } while (0)
; #define PG8_WAIT_V(n) asm volatile("s_waitcnt vmcnt(" #n ")" ::: "memory")
; #define PG8_WAIT_L(n) asm volatile("s_waitcnt lgkmcnt(" #n ")" ::: "memory")
; #define PG8_BAR __builtin_amdgcn_s_barrier()
; #define PG8_SCHED __builtin_amdgcn_sched_barrier(0)
; __device__ __forceinline__ void gemm_phase(LAS unsigned char* lds, const bf16_t* A, const bf16_t* Bt, int M, int N, int K, const Epi& E) {
;     ...
;             PG8_WAIT_V(8); PG8_WAIT_L(0); PG8_BAR; PG8_MMA(1, 0, At, B0); PG8_MMA(1, 1, At, B1); PG8_BAR; PG8_SCHED;
;             PG8_LDB(B0, 1, 0); PG8_LDB(B1, 1, 1); PG8_SCHED; PG8_LDA(At, 1, 0); PG8_STAGE(PG8_SA(0, 1), a2 + hstep, voffA);
;             PG8_WAIT_V(8); PG8_WAIT_L(0); PG8_BAR; PG8_MMA(0, 0, At, B0); PG8_MMA(0, 1, At, B1); PG8_BAR; PG8_SCHED;
	s_setprio 1
	s_waitcnt lgkmcnt(0)
	v_mfma_f32_16x16x32_bf16 v[62:65], v[102:105], v[162:165], v[62:65]
	v_mfma_f32_16x16x32_bf16 v[58:61], v[114:117], v[162:165], v[58:61]
	v_mfma_f32_16x16x32_bf16 v[46:49], v[102:105], v[170:173], v[46:49]
	v_mfma_f32_16x16x32_bf16 v[42:45], v[114:117], v[170:173], v[42:45]
	v_mfma_f32_16x16x32_bf16 v[30:33], v[102:105], v[178:181], v[30:33]
	v_mfma_f32_16x16x32_bf16 v[26:29], v[114:117], v[178:181], v[26:29]
	v_mfma_f32_16x16x32_bf16 v[14:17], v[102:105], v[212:215], v[14:17]
	v_mfma_f32_16x16x32_bf16 v[10:13], v[114:117], v[212:215], v[10:13]
	v_mfma_f32_16x16x32_bf16 v[62:65], v[110:113], v[166:169], v[62:65]
	v_mfma_f32_16x16x32_bf16 v[58:61], v[118:121], v[166:169], v[58:61]
	v_mfma_f32_16x16x32_bf16 v[46:49], v[110:113], v[174:177], v[46:49]
	v_mfma_f32_16x16x32_bf16 v[42:45], v[118:121], v[174:177], v[42:45]
	v_mfma_f32_16x16x32_bf16 v[30:33], v[110:113], v[182:185], v[30:33]
	v_mfma_f32_16x16x32_bf16 v[26:29], v[118:121], v[182:185], v[26:29]
	v_mfma_f32_16x16x32_bf16 v[14:17], v[110:113], v[216:219], v[14:17]
	v_mfma_f32_16x16x32_bf16 v[10:13], v[118:121], v[216:219], v[10:13]
	v_mfma_f32_16x16x32_bf16 v[54:57], v[146:149], v[162:165], v[54:57]
	v_mfma_f32_16x16x32_bf16 v[50:53], v[154:157], v[162:165], v[50:53]
	v_mfma_f32_16x16x32_bf16 v[38:41], v[146:149], v[170:173], v[38:41]
	v_mfma_f32_16x16x32_bf16 v[34:37], v[154:157], v[170:173], v[34:37]
	v_mfma_f32_16x16x32_bf16 v[22:25], v[146:149], v[178:181], v[22:25]
	v_mfma_f32_16x16x32_bf16 v[18:21], v[154:157], v[178:181], v[18:21]
	v_mfma_f32_16x16x32_bf16 v[6:9], v[146:149], v[212:215], v[6:9]
	v_mfma_f32_16x16x32_bf16 v[2:5], v[154:157], v[212:215], v[2:5]
	v_mfma_f32_16x16x32_bf16 v[54:57], v[150:153], v[166:169], v[54:57]
	v_mfma_f32_16x16x32_bf16 v[50:53], v[158:161], v[166:169], v[50:53]
	v_mfma_f32_16x16x32_bf16 v[38:41], v[150:153], v[174:177], v[38:41]
	v_mfma_f32_16x16x32_bf16 v[34:37], v[158:161], v[174:177], v[34:37]
	v_mfma_f32_16x16x32_bf16 v[22:25], v[150:153], v[182:185], v[22:25]
	v_mfma_f32_16x16x32_bf16 v[18:21], v[158:161], v[182:185], v[18:21]
	v_mfma_f32_16x16x32_bf16 v[6:9], v[150:153], v[216:219], v[6:9]
	v_mfma_f32_16x16x32_bf16 v[2:5], v[158:161], v[216:219], v[2:5]
	s_setprio 0
	s_barrier
	s_add_i32 s43, 0, 0x18000
	s_add_i32 s44, 0, 0x1c000
	v_add_u32_e32 v118, s43, v249
	v_add_u32_e32 v158, s44, v249
	ds_read_b128 v[102:105], v118
	ds_read_b128 v[110:113], v118 offset:1024
	ds_read_b128 v[114:117], v118 offset:2048
	ds_read_b128 v[118:121], v118 offset:3072
	ds_read_b128 v[146:149], v158
	ds_read_b128 v[150:153], v158 offset:1024
	ds_read_b128 v[154:157], v158 offset:2048
	ds_read_b128 v[158:161], v158 offset:3072
	s_add_u32 s22, s22, 0x40000
	s_addc_u32 s23, s23, 0
	s_mov_b32 m0, s31
	v_lshl_add_u64 v[228:229], s[22:23], 0, v[202:203]
	ds_read_b128 v[162:165], v240 offset:32768
	ds_read_b128 v[166:169], v240 offset:33792
	ds_read_b128 v[170:173], v240 offset:34816
	ds_read_b128 v[174:177], v240 offset:35840
	ds_read_b128 v[178:181], v240 offset:36864
	ds_read_b128 v[182:185], v240 offset:37888
	ds_read_b128 v[212:215], v240 offset:38912
	ds_read_b128 v[216:219], v240 offset:39936
	global_load_lds_dwordx4 v[228:229], off
	v_lshl_add_u64 v[228:229], s[22:23], 0, v[204:205]
	s_mov_b32 m0, s33
	s_nop 0
	global_load_lds_dwordx4 v[228:229], off
	s_waitcnt vmcnt(8)
	s_waitcnt lgkmcnt(0)
	s_barrier
	s_setprio 1
	s_waitcnt lgkmcnt(0)
	v_mfma_f32_16x16x32_bf16 v[142:145], v[102:105], v[162:165], v[142:145]
	v_mfma_f32_16x16x32_bf16 v[138:141], v[114:117], v[162:165], v[138:141]
	v_mfma_f32_16x16x32_bf16 v[126:129], v[102:105], v[170:173], v[126:129]
	v_mfma_f32_16x16x32_bf16 v[122:125], v[114:117], v[170:173], v[122:125]
	v_mfma_f32_16x16x32_bf16 v[94:97], v[102:105], v[178:181], v[94:97]
	v_mfma_f32_16x16x32_bf16 v[90:93], v[114:117], v[178:181], v[90:93]
	v_mfma_f32_16x16x32_bf16 v[78:81], v[102:105], v[212:215], v[78:81]
	v_mfma_f32_16x16x32_bf16 v[74:77], v[114:117], v[212:215], v[74:77]
	v_mfma_f32_16x16x32_bf16 v[142:145], v[110:113], v[166:169], v[142:145]
	v_mfma_f32_16x16x32_bf16 v[138:141], v[118:121], v[166:169], v[138:141]
	v_mfma_f32_16x16x32_bf16 v[126:129], v[110:113], v[174:177], v[126:129]
	v_mfma_f32_16x16x32_bf16 v[122:125], v[118:121], v[174:177], v[122:125]
	v_mfma_f32_16x16x32_bf16 v[94:97], v[110:113], v[182:185], v[94:97]
	v_mfma_f32_16x16x32_bf16 v[90:93], v[118:121], v[182:185], v[90:93]
	v_mfma_f32_16x16x32_bf16 v[78:81], v[110:113], v[216:219], v[78:81]
	v_mfma_f32_16x16x32_bf16 v[74:77], v[118:121], v[216:219], v[74:77]
	v_mfma_f32_16x16x32_bf16 v[134:137], v[146:149], v[162:165], v[134:137]
	v_mfma_f32_16x16x32_bf16 v[130:133], v[154:157], v[162:165], v[130:133]
	v_mfma_f32_16x16x32_bf16 v[106:109], v[146:149], v[170:173], v[106:109]
	v_mfma_f32_16x16x32_bf16 v[98:101], v[154:157], v[170:173], v[98:101]
	v_mfma_f32_16x16x32_bf16 v[86:89], v[146:149], v[178:181], v[86:89]
	v_mfma_f32_16x16x32_bf16 v[82:85], v[154:157], v[178:181], v[82:85]
	v_mfma_f32_16x16x32_bf16 v[70:73], v[146:149], v[212:215], v[70:73]
	v_mfma_f32_16x16x32_bf16 v[66:69], v[154:157], v[212:215], v[66:69]
	v_mfma_f32_16x16x32_bf16 v[134:137], v[150:153], v[166:169], v[134:137]
	v_mfma_f32_16x16x32_bf16 v[130:133], v[158:161], v[166:169], v[130:133]
	v_mfma_f32_16x16x32_bf16 v[106:109], v[150:153], v[174:177], v[106:109]
	v_mfma_f32_16x16x32_bf16 v[98:101], v[158:161], v[174:177], v[98:101]
	v_mfma_f32_16x16x32_bf16 v[86:89], v[150:153], v[182:185], v[86:89]
	v_mfma_f32_16x16x32_bf16 v[82:85], v[158:161], v[182:185], v[82:85]
	v_mfma_f32_16x16x32_bf16 v[70:73], v[150:153], v[216:219], v[70:73]
	v_mfma_f32_16x16x32_bf16 v[66:69], v[158:161], v[216:219], v[66:69]
	s_setprio 0
	s_barrier
; #define PG8_STAGE(bufoff, gbase, voff) do { _Pragma("unroll") for (int _i = 0; _i < 2; ++_i) \
;         __builtin_amdgcn_global_load_lds((const unsigned*)((const char*)(gbase) + (voff)[_i]), (LAS unsigned*)(lds + (bufoff) + ldsw + _i * 8192), 16, 0, 0); } while (0)
; #define PG8_LDA(dst, b, h) do { _Pragma("unroll") for (int m = 0; m < 4; ++m) _Pragma("unroll") for (int k = 0; k < 2; ++k) dst[m][k] = *(const LAS bf16x8*)(lds + PG8_SA(b, h) + aoff + m * 2048 + k * 1024); } while (0)
; #define PG8_MMA(ai, bj, At, Bt_) do { __builtin_amdgcn_s_setprio(1); _Pragma("unroll") for (int m = 0; m < 4; ++m) _Pragma("unroll") for (int n = 0; n < 2; ++n) _Pragma("unroll") for (int k = 0; k < 2; ++k) \
;         acc[ai][bj][m][n] = __builtin_amdgcn_mfma_f32_16x16x32_bf16(Bt_[n][k], At[m][k], acc[ai][bj][m][n], 0, 0, 0); __builtin_amdgcn_s_setprio(0); } while (0)
; #define PG8_WAIT_V(n) asm volatile("s_waitcnt vmcnt(" #n ")" ::: "memory")
; #define PG8_WAIT_L(n) asm volatile("s_waitcnt lgkmcnt(" #n ")" ::: "memory")
; #define PG8_BAR __builtin_amdgcn_s_barrier()
; #define PG8_SCHED __builtin_amdgcn_sched_barrier(0)
; __device__ __forceinline__ void gemm_phase(LAS unsigned char* lds, const bf16_t* A, const bf16_t* Bt, int M, int N, int K, const Epi& E) {
;     ...
;             PG8_LDA(At, 1, 1); PG8_STAGE(PG8_SB(1, 0), b3, voffB); PG8_STAGE(PG8_SB(1, 1), b3 + hstep, voffB); PG8_STAGE(PG8_SA(1, 0), a3, voffA);
;             PG8_WAIT_V(8); PG8_WAIT_L(0); PG8_BAR; PG8_MMA(1, 0, At, B0); PG8_MMA(1, 1, At, B1); PG8_BAR; PG8_SCHED;
;         }
;         if (wr == 0) PG8_BAR;
	s_add_i32 s22, s43, s28
	v_lshl_add_u64 v[220:221], v[220:221], 0, s[48:49]
	s_mov_b32 m0, s22
	ds_read_b128 v[162:165], v240 offset:49152
	ds_read_b128 v[166:169], v240 offset:50176
	ds_read_b128 v[170:173], v240 offset:51200
	ds_read_b128 v[174:177], v240 offset:52224
	ds_read_b128 v[178:181], v240 offset:53248
	ds_read_b128 v[182:185], v240 offset:54272
	ds_read_b128 v[212:215], v240 offset:55296
	ds_read_b128 v[216:219], v240 offset:56320
	global_load_lds_dwordx4 v[220:221], off
	s_add_i32 m0, s22, 0x2000
	s_add_u32 s20, s20, 0x40080
	v_lshl_add_u64 v[220:221], v[222:223], 0, s[48:49]
	s_addc_u32 s21, s21, 0
	s_add_i32 s22, s44, s28
	global_load_lds_dwordx4 v[220:221], off
	v_lshl_add_u64 v[220:221], s[20:21], 0, v[0:1]
	s_mov_b32 m0, s22
	s_nop 0
	global_load_lds_dwordx4 v[220:221], off
	v_lshl_add_u64 v[220:221], s[20:21], 0, v[206:207]
	s_add_i32 m0, s22, 0x2000
	s_nop 0
	global_load_lds_dwordx4 v[220:221], off
	v_lshl_add_u64 v[220:221], v[224:225], 0, s[48:49]
	s_mov_b32 m0, s35
	s_nop 0
	global_load_lds_dwordx4 v[220:221], off
	v_lshl_add_u64 v[220:221], v[226:227], 0, s[48:49]
	s_mov_b32 m0, s38
	s_nop 0
	global_load_lds_dwordx4 v[220:221], off
	s_waitcnt vmcnt(8)
	s_waitcnt lgkmcnt(0)
	s_barrier
	s_setprio 1
	s_waitcnt lgkmcnt(0)
	v_mfma_f32_16x16x32_bf16 v[62:65], v[102:105], v[162:165], v[62:65]
	v_mfma_f32_16x16x32_bf16 v[58:61], v[114:117], v[162:165], v[58:61]
	v_mfma_f32_16x16x32_bf16 v[46:49], v[102:105], v[170:173], v[46:49]
	v_mfma_f32_16x16x32_bf16 v[42:45], v[114:117], v[170:173], v[42:45]
	v_mfma_f32_16x16x32_bf16 v[30:33], v[102:105], v[178:181], v[30:33]
	v_mfma_f32_16x16x32_bf16 v[26:29], v[114:117], v[178:181], v[26:29]
	v_mfma_f32_16x16x32_bf16 v[14:17], v[102:105], v[212:215], v[14:17]
	v_mfma_f32_16x16x32_bf16 v[10:13], v[114:117], v[212:215], v[10:13]
	v_mfma_f32_16x16x32_bf16 v[62:65], v[110:113], v[166:169], v[62:65]
	v_mfma_f32_16x16x32_bf16 v[58:61], v[118:121], v[166:169], v[58:61]
	v_mfma_f32_16x16x32_bf16 v[46:49], v[110:113], v[174:177], v[46:49]
	v_mfma_f32_16x16x32_bf16 v[42:45], v[118:121], v[174:177], v[42:45]
	v_mfma_f32_16x16x32_bf16 v[30:33], v[110:113], v[182:185], v[30:33]
	v_mfma_f32_16x16x32_bf16 v[26:29], v[118:121], v[182:185], v[26:29]
	v_mfma_f32_16x16x32_bf16 v[14:17], v[110:113], v[216:219], v[14:17]
	v_mfma_f32_16x16x32_bf16 v[10:13], v[118:121], v[216:219], v[10:13]
	v_mfma_f32_16x16x32_bf16 v[54:57], v[146:149], v[162:165], v[54:57]
	v_mfma_f32_16x16x32_bf16 v[50:53], v[154:157], v[162:165], v[50:53]
	v_mfma_f32_16x16x32_bf16 v[38:41], v[146:149], v[170:173], v[38:41]
	v_mfma_f32_16x16x32_bf16 v[34:37], v[154:157], v[170:173], v[34:37]
	v_mfma_f32_16x16x32_bf16 v[22:25], v[146:149], v[178:181], v[22:25]
	v_mfma_f32_16x16x32_bf16 v[18:21], v[154:157], v[178:181], v[18:21]
	v_mfma_f32_16x16x32_bf16 v[6:9], v[146:149], v[212:215], v[6:9]
	v_mfma_f32_16x16x32_bf16 v[2:5], v[154:157], v[212:215], v[2:5]
	v_mfma_f32_16x16x32_bf16 v[54:57], v[150:153], v[166:169], v[54:57]
	v_mfma_f32_16x16x32_bf16 v[50:53], v[158:161], v[166:169], v[50:53]
	v_mfma_f32_16x16x32_bf16 v[38:41], v[150:153], v[174:177], v[38:41]
	v_mfma_f32_16x16x32_bf16 v[34:37], v[158:161], v[174:177], v[34:37]
	v_mfma_f32_16x16x32_bf16 v[22:25], v[150:153], v[182:185], v[22:25]
	v_mfma_f32_16x16x32_bf16 v[18:21], v[158:161], v[182:185], v[18:21]
	v_mfma_f32_16x16x32_bf16 v[6:9], v[150:153], v[216:219], v[6:9]
	v_mfma_f32_16x16x32_bf16 v[2:5], v[158:161], v[216:219], v[2:5]
	s_setprio 0
	s_barrier
	s_add_i32 s42, s42, 2
	s_add_u32 s18, s18, 0x100
	s_addc_u32 s19, s19, 0
	s_add_u32 s40, s40, 0x100
	s_addc_u32 s41, s41, 0
	s_cmp_gt_u32 s42, 13
	s_cbranch_scc0 .LBB0_2541
	s_and_b64 vcc, exec, s[6:7]
	s_cbranch_vccz .LBB0_2544
	s_barrier

; #define PG8_STAGE(bufoff, gbase, voff) do { _Pragma("unroll") for (int _i = 0; _i < 2; ++_i) \
;         __builtin_amdgcn_global_load_lds((const unsigned*)((const char*)(gbase) + (voff)[_i]), (LAS unsigned*)(lds + (bufoff) + ldsw + _i * 8192), 16, 0, 0); } while (0)
; #define PG8_LDA(dst, b, h) do { _Pragma("unroll") for (int m = 0; m < 4; ++m) _Pragma("unroll") for (int k = 0; k < 2; ++k) dst[m][k] = *(const LAS bf16x8*)(lds + PG8_SA(b, h) + aoff + m * 2048 + k * 1024); } while (0)
; #define PG8_LDB(dst, b, h) do { _Pragma("unroll") for (int n = 0; n < 2; ++n) _Pragma("unroll") for (int k = 0; k < 2; ++k) dst[n][k] = *(const LAS bf16x8*)(lds + PG8_SB(b, h) + boff + n * 2048 + k * 1024); } while (0)
; #define PG8_MMA(ai, bj, At, Bt_) do { __builtin_amdgcn_s_setprio(1); _Pragma("unroll") for (int m = 0; m < 4; ++m) _Pragma("unroll") for (int n = 0; n < 2; ++n) _Pragma("unroll") for (int k = 0; k < 2; ++k) \
;         acc[ai][bj][m][n] = __builtin_amdgcn_mfma_f32_16x16x32_bf16(Bt_[n][k], At[m][k], acc[ai][bj][m][n], 0, 0, 0); __builtin_amdgcn_s_setprio(0); } while (0)
; #define PG8_WAIT_V(n) asm volatile("s_waitcnt vmcnt(" #n ")" ::: "memory")
; #define PG8_WAIT_L(n) asm volatile("s_waitcnt lgkmcnt(" #n ")" ::: "memory")
; __device__ __forceinline__ void gemm_phase(LAS unsigned char* lds, const bf16_t* A, const bf16_t* Bt, int M, int N, int K, const Epi& E) {
;     ...
;         for (int t = 0; t < nt; t += 2) {
;             const bool last = (t == nt - 2);
;             const char* a1 = cA + (size_t)(t + 1) * kstep;
;             const char* a2 = last ? nA : cA + (size_t)(t + 2) * kstep; const char* b2 = last ? nB : cB + (size_t)(t + 2) * kstep;
;             const char* a3 = a2 + kstep; const char* b3 = b2 + kstep;
;             PG8_LDB(B0, 0, 0); PG8_LDB(B1, 0, 1); PG8_SCHED; PG8_LDA(At, 0, 0); PG8_STAGE(PG8_SA(1, 1), a1 + hstep, voffA);
;             PG8_WAIT_V(8); PG8_WAIT_L(0); PG8_BAR; PG8_MMA(0, 0, At, B0); PG8_MMA(0, 1, At, B1); PG8_BAR; PG8_SCHED;
;             PG8_LDA(At, 0, 1); PG8_STAGE(PG8_SB(0, 0), b2, voffB); PG8_STAGE(PG8_SB(0, 1), b2 + hstep, voffB); PG8_STAGE(PG8_SA(0, 0), a2, voffA);
;             PG8_WAIT_V(8); PG8_WAIT_L(0); PG8_BAR; PG8_MMA(1, 0, At, B0); PG8_MMA(1, 1, At, B1); PG8_BAR; PG8_SCHED;
;             PG8_LDB(B0, 1, 0); PG8_LDB(B1, 1, 1); PG8_SCHED; PG8_LDA(At, 1, 0); PG8_STAGE(PG8_SA(0, 1), a2 + hstep, voffA);
.LBB0_2823:
	s_add_u32 s22, s20, 0xfffc0080
	s_addc_u32 s23, s21, -1
	s_add_i32 s53, 0, 0x10000
	s_cmp_eq_u32 s52, 12
	s_cselect_b32 s25, s11, s23
	s_cselect_b32 s24, s17, s22
	s_cselect_b32 s23, s5, s51
	s_cselect_b32 s22, s49, s50
	s_add_i32 s56, 0, 0x14000
	v_add_u32_e32 v158, s53, v137
	v_add_u32_e32 v174, s56, v137
	ds_read_b128 v[146:149], v158
	ds_read_b128 v[150:153], v158 offset:1024
	ds_read_b128 v[154:157], v158 offset:2048
	ds_read_b128 v[158:161], v158 offset:3072
	ds_read_b128 v[162:165], v174
	ds_read_b128 v[166:169], v174 offset:1024
	ds_read_b128 v[170:173], v174 offset:2048
	ds_read_b128 v[174:177], v174 offset:3072
	v_lshl_add_u64 v[184:185], s[20:21], 0, v[142:143]
	s_add_i32 m0, s19, 0xc000
	ds_read_b128 v[178:181], v182
	ds_read_b128 v[202:205], v182 offset:1024
	ds_read_b128 v[206:209], v182 offset:2048
	ds_read_b128 v[210:213], v182 offset:3072
	ds_read_b128 v[214:217], v182 offset:4096
	ds_read_b128 v[218:221], v182 offset:5120
	ds_read_b128 v[222:225], v182 offset:6144
	ds_read_b128 v[226:229], v182 offset:7168
	global_load_lds_dwordx4 v[184:185], off
	v_lshl_add_u64 v[184:185], s[20:21], 0, v[144:145]
	s_add_i32 m0, s19, 0xe000
	s_nop 0
	global_load_lds_dwordx4 v[184:185], off
	s_waitcnt vmcnt(8)
	s_waitcnt lgkmcnt(0)
	s_barrier
	s_setprio 1
	s_waitcnt lgkmcnt(0)
	v_mfma_f32_16x16x32_bf16 v[126:129], v[146:149], v[178:181], v[126:129]
	v_mfma_f32_16x16x32_bf16 v[122:125], v[154:157], v[178:181], v[122:125]
	v_mfma_f32_16x16x32_bf16 v[102:105], v[146:149], v[206:209], v[102:105]
	v_mfma_f32_16x16x32_bf16 v[98:101], v[154:157], v[206:209], v[98:101]
	v_mfma_f32_16x16x32_bf16 v[94:97], v[146:149], v[214:217], v[94:97]
	v_mfma_f32_16x16x32_bf16 v[90:93], v[154:157], v[214:217], v[90:93]
	v_mfma_f32_16x16x32_bf16 v[70:73], v[146:149], v[222:225], v[70:73]
	v_mfma_f32_16x16x32_bf16 v[66:69], v[154:157], v[222:225], v[66:69]
	v_mfma_f32_16x16x32_bf16 v[126:129], v[150:153], v[202:205], v[126:129]
	v_mfma_f32_16x16x32_bf16 v[122:125], v[158:161], v[202:205], v[122:125]
	v_mfma_f32_16x16x32_bf16 v[102:105], v[150:153], v[210:213], v[102:105]
	v_mfma_f32_16x16x32_bf16 v[98:101], v[158:161], v[210:213], v[98:101]
	v_mfma_f32_16x16x32_bf16 v[94:97], v[150:153], v[218:221], v[94:97]
	v_mfma_f32_16x16x32_bf16 v[90:93], v[158:161], v[218:221], v[90:93]
	v_mfma_f32_16x16x32_bf16 v[70:73], v[150:153], v[226:229], v[70:73]
	v_mfma_f32_16x16x32_bf16 v[66:69], v[158:161], v[226:229], v[66:69]
	v_mfma_f32_16x16x32_bf16 v[118:121], v[162:165], v[178:181], v[118:121]
	v_mfma_f32_16x16x32_bf16 v[114:117], v[170:173], v[178:181], v[114:117]
	v_mfma_f32_16x16x32_bf16 v[110:113], v[162:165], v[206:209], v[110:113]
	v_mfma_f32_16x16x32_bf16 v[106:109], v[170:173], v[206:209], v[106:109]
	v_mfma_f32_16x16x32_bf16 v[86:89], v[162:165], v[214:217], v[86:89]
	v_mfma_f32_16x16x32_bf16 v[82:85], v[170:173], v[214:217], v[82:85]
	v_mfma_f32_16x16x32_bf16 v[78:81], v[162:165], v[222:225], v[78:81]
	v_mfma_f32_16x16x32_bf16 v[74:77], v[170:173], v[222:225], v[74:77]
	v_mfma_f32_16x16x32_bf16 v[118:121], v[166:169], v[202:205], v[118:121]
	v_mfma_f32_16x16x32_bf16 v[114:117], v[174:177], v[202:205], v[114:117]
	v_mfma_f32_16x16x32_bf16 v[110:113], v[166:169], v[210:213], v[110:113]
	v_mfma_f32_16x16x32_bf16 v[106:109], v[174:177], v[210:213], v[106:109]
	v_mfma_f32_16x16x32_bf16 v[86:89], v[166:169], v[218:221], v[86:89]
	v_mfma_f32_16x16x32_bf16 v[82:85], v[174:177], v[218:221], v[82:85]
	v_mfma_f32_16x16x32_bf16 v[78:81], v[166:169], v[226:229], v[78:81]
	v_mfma_f32_16x16x32_bf16 v[74:77], v[174:177], v[226:229], v[74:77]
	s_setprio 0
	s_barrier
	s_add_i32 s53, s53, s27
	v_lshl_add_u64 v[184:185], s[22:23], 0, v[0:1]
	s_mov_b32 m0, s53
	ds_read_b128 v[178:181], v182 offset:16384
	ds_read_b128 v[202:205], v182 offset:17408
	ds_read_b128 v[206:209], v182 offset:18432
	ds_read_b128 v[210:213], v182 offset:19456
	ds_read_b128 v[214:217], v182 offset:20480
	ds_read_b128 v[218:221], v182 offset:21504
	ds_read_b128 v[222:225], v182 offset:22528
	ds_read_b128 v[226:229], v182 offset:23552
	global_load_lds_dwordx4 v[184:185], off
	s_add_i32 m0, s53, 0x2000
	s_add_u32 s54, s22, 0x40000
	v_lshl_add_u64 v[230:231], s[22:23], 0, v[134:135]
	s_addc_u32 s55, s23, 0
	s_add_i32 s53, s56, s27
	global_load_lds_dwordx4 v[230:231], off
	v_lshl_add_u64 v[232:233], s[54:55], 0, v[0:1]
	s_mov_b32 m0, s53
	v_lshl_add_u64 v[240:241], s[24:25], 0, v[132:133]
	global_load_lds_dwordx4 v[232:233], off
	v_lshl_add_u64 v[232:233], s[54:55], 0, v[134:135]
	s_add_i32 m0, s53, 0x2000
	s_nop 0
	global_load_lds_dwordx4 v[232:233], off
	v_lshl_add_u64 v[232:233], s[24:25], 0, v[130:131]
	s_mov_b32 m0, s19
	s_nop 0
	global_load_lds_dwordx4 v[232:233], off
	s_mov_b32 m0, s30
	s_nop 0
	global_load_lds_dwordx4 v[240:241], off
	s_waitcnt vmcnt(8)
	s_waitcnt lgkmcnt(0)
	s_barrier
; #define PG8_STAGE(bufoff, gbase, voff) do { _Pragma("unroll") for (int _i = 0; _i < 2; ++_i) \
;         __builtin_amdgcn_global_load_lds((const unsigned*)((const char*)(gbase) + (voff)[_i]), (LAS unsigned*)(lds + (bufoff) + ldsw + _i * 8192), 16, 0, 0); } while (0)
; #define PG8_LDA(dst, b, h) do { _Pragma("unroll") for (int m = 0; m < 4; ++m) _Pragma("unroll") for (int k = 0; k < 2; ++k) dst[m][k] = *(const LAS bf16x8*)(lds + PG8_SA(b, h) + aoff + m * 2048 + k * 1024); } while (0)
; #define PG8_LDB(dst, b, h) do { _Pragma("unroll") for (int n = 0; n < 2; ++n) _Pragma("unroll") for (int k = 0; k < 2; ++k) dst[n][k] = *(const LAS bf16x8*)(lds + PG8_SB(b, h) + boff + n * 2048 + k * 1024); } while (0)
; #define PG8_MMA(ai, bj, At, Bt_) do { __builtin_amdgcn_s_setprio(1); _Pragma("unroll") for (int m = 0; m < 4; ++m) _Pragma("unroll") for (int n = 0; n < 2; ++n) _Pragma("unroll") for (int k = 0; k < 2; ++k) \
;         acc[ai][bj][m][n] = __builtin_amdgcn_mfma_f32_16x16x32_bf16(Bt_[n][k], At[m][k], acc[ai][bj][m][n], 0, 0, 0); __builtin_amdgcn_s_setprio(0); } while (0)
; #define PG8_WAIT_V(n) asm volatile("s_waitcnt vmcnt(" #n ")" ::: "memory")
; #define PG8_WAIT_L(n) asm volatile("s_waitcnt lgkmcnt(" #n ")" ::: "memory")
; #define PG8_BAR __builtin_amdgcn_s_barrier()
; #define PG8_SCHED __builtin_amdgcn_sched_barrier(0)
; __device__ __forceinline__ void gemm_phase(LAS unsigned char* lds, const bf16_t* A, const bf16_t* Bt, int M, int N, int K, const Epi& E) {
;     ...
;             PG8_WAIT_V(8); PG8_WAIT_L(0); PG8_BAR; PG8_MMA(1, 0, At, B0); PG8_MMA(1, 1, At, B1); PG8_BAR; PG8_SCHED;
;             PG8_LDB(B0, 1, 0); PG8_LDB(B1, 1, 1); PG8_SCHED; PG8_LDA(At, 1, 0); PG8_STAGE(PG8_SA(0, 1), a2 + hstep, voffA);
;             PG8_WAIT_V(8); PG8_WAIT_L(0); PG8_BAR; PG8_MMA(0, 0, At, B0); PG8_MMA(0, 1, At, B1); PG8_BAR; PG8_SCHED;
	s_setprio 1
	s_waitcnt lgkmcnt(0)
	v_mfma_f32_16x16x32_bf16 v[62:65], v[146:149], v[178:181], v[62:65]
	v_mfma_f32_16x16x32_bf16 v[58:61], v[154:157], v[178:181], v[58:61]
	v_mfma_f32_16x16x32_bf16 v[38:41], v[146:149], v[206:209], v[38:41]
	v_mfma_f32_16x16x32_bf16 v[34:37], v[154:157], v[206:209], v[34:37]
	v_mfma_f32_16x16x32_bf16 v[30:33], v[146:149], v[214:217], v[30:33]
	v_mfma_f32_16x16x32_bf16 v[26:29], v[154:157], v[214:217], v[26:29]
	v_mfma_f32_16x16x32_bf16 v[10:13], v[146:149], v[222:225], v[10:13]
	v_mfma_f32_16x16x32_bf16 v[2:5], v[154:157], v[222:225], v[2:5]
	v_mfma_f32_16x16x32_bf16 v[62:65], v[150:153], v[202:205], v[62:65]
	v_mfma_f32_16x16x32_bf16 v[58:61], v[158:161], v[202:205], v[58:61]
	v_mfma_f32_16x16x32_bf16 v[38:41], v[150:153], v[210:213], v[38:41]
	v_mfma_f32_16x16x32_bf16 v[34:37], v[158:161], v[210:213], v[34:37]
	v_mfma_f32_16x16x32_bf16 v[30:33], v[150:153], v[218:221], v[30:33]
	v_mfma_f32_16x16x32_bf16 v[26:29], v[158:161], v[218:221], v[26:29]
	v_mfma_f32_16x16x32_bf16 v[10:13], v[150:153], v[226:229], v[10:13]
	v_mfma_f32_16x16x32_bf16 v[2:5], v[158:161], v[226:229], v[2:5]
	v_mfma_f32_16x16x32_bf16 v[54:57], v[162:165], v[178:181], v[54:57]
	v_mfma_f32_16x16x32_bf16 v[50:53], v[170:173], v[178:181], v[50:53]
	v_mfma_f32_16x16x32_bf16 v[46:49], v[162:165], v[206:209], v[46:49]
	v_mfma_f32_16x16x32_bf16 v[42:45], v[170:173], v[206:209], v[42:45]
	v_mfma_f32_16x16x32_bf16 v[22:25], v[162:165], v[214:217], v[22:25]
	v_mfma_f32_16x16x32_bf16 v[18:21], v[170:173], v[214:217], v[18:21]
	v_mfma_f32_16x16x32_bf16 v[14:17], v[162:165], v[222:225], v[14:17]
	v_mfma_f32_16x16x32_bf16 v[6:9], v[170:173], v[222:225], v[6:9]
	v_mfma_f32_16x16x32_bf16 v[54:57], v[166:169], v[202:205], v[54:57]
	v_mfma_f32_16x16x32_bf16 v[50:53], v[174:177], v[202:205], v[50:53]
	v_mfma_f32_16x16x32_bf16 v[46:49], v[166:169], v[210:213], v[46:49]
	v_mfma_f32_16x16x32_bf16 v[42:45], v[174:177], v[210:213], v[42:45]
	v_mfma_f32_16x16x32_bf16 v[22:25], v[166:169], v[218:221], v[22:25]
	v_mfma_f32_16x16x32_bf16 v[18:21], v[174:177], v[218:221], v[18:21]
	v_mfma_f32_16x16x32_bf16 v[14:17], v[166:169], v[226:229], v[14:17]
	v_mfma_f32_16x16x32_bf16 v[6:9], v[174:177], v[226:229], v[6:9]
	s_setprio 0
	s_barrier
	s_add_i32 s53, 0, 0x18000
	s_add_i32 s54, 0, 0x1c000
	v_add_u32_e32 v158, s53, v137
	v_add_u32_e32 v174, s54, v137
	ds_read_b128 v[146:149], v158
	ds_read_b128 v[150:153], v158 offset:1024
	ds_read_b128 v[154:157], v158 offset:2048
	ds_read_b128 v[158:161], v158 offset:3072
	ds_read_b128 v[162:165], v174
	ds_read_b128 v[166:169], v174 offset:1024
	ds_read_b128 v[170:173], v174 offset:2048
	ds_read_b128 v[174:177], v174 offset:3072
	s_add_u32 s24, s24, 0x40000
	s_addc_u32 s25, s25, 0
	s_mov_b32 m0, s31
	v_lshl_add_u64 v[246:247], s[24:25], 0, v[130:131]
	ds_read_b128 v[178:181], v182 offset:32768
	ds_read_b128 v[202:205], v182 offset:33792
	ds_read_b128 v[206:209], v182 offset:34816
	ds_read_b128 v[210:213], v182 offset:35840
	ds_read_b128 v[214:217], v182 offset:36864
	ds_read_b128 v[218:221], v182 offset:37888
	ds_read_b128 v[222:225], v182 offset:38912
	ds_read_b128 v[226:229], v182 offset:39936
	global_load_lds_dwordx4 v[246:247], off
	v_lshl_add_u64 v[246:247], s[24:25], 0, v[132:133]
	s_mov_b32 m0, s33
	s_nop 0
	global_load_lds_dwordx4 v[246:247], off
	s_waitcnt vmcnt(8)
	s_waitcnt lgkmcnt(0)
	s_barrier
	s_setprio 1
	s_waitcnt lgkmcnt(0)
	v_mfma_f32_16x16x32_bf16 v[126:129], v[146:149], v[178:181], v[126:129]
	v_mfma_f32_16x16x32_bf16 v[122:125], v[154:157], v[178:181], v[122:125]
	v_mfma_f32_16x16x32_bf16 v[102:105], v[146:149], v[206:209], v[102:105]
	v_mfma_f32_16x16x32_bf16 v[98:101], v[154:157], v[206:209], v[98:101]
	v_mfma_f32_16x16x32_bf16 v[94:97], v[146:149], v[214:217], v[94:97]
	v_mfma_f32_16x16x32_bf16 v[90:93], v[154:157], v[214:217], v[90:93]
	v_mfma_f32_16x16x32_bf16 v[70:73], v[146:149], v[222:225], v[70:73]
	v_mfma_f32_16x16x32_bf16 v[66:69], v[154:157], v[222:225], v[66:69]
	v_mfma_f32_16x16x32_bf16 v[126:129], v[150:153], v[202:205], v[126:129]
	v_mfma_f32_16x16x32_bf16 v[122:125], v[158:161], v[202:205], v[122:125]
	v_mfma_f32_16x16x32_bf16 v[102:105], v[150:153], v[210:213], v[102:105]
	v_mfma_f32_16x16x32_bf16 v[98:101], v[158:161], v[210:213], v[98:101]
	v_mfma_f32_16x16x32_bf16 v[94:97], v[150:153], v[218:221], v[94:97]
	v_mfma_f32_16x16x32_bf16 v[90:93], v[158:161], v[218:221], v[90:93]
	v_mfma_f32_16x16x32_bf16 v[70:73], v[150:153], v[226:229], v[70:73]
	v_mfma_f32_16x16x32_bf16 v[66:69], v[158:161], v[226:229], v[66:69]
	v_mfma_f32_16x16x32_bf16 v[118:121], v[162:165], v[178:181], v[118:121]
	v_mfma_f32_16x16x32_bf16 v[114:117], v[170:173], v[178:181], v[114:117]
	v_mfma_f32_16x16x32_bf16 v[110:113], v[162:165], v[206:209], v[110:113]
	v_mfma_f32_16x16x32_bf16 v[106:109], v[170:173], v[206:209], v[106:109]
	v_mfma_f32_16x16x32_bf16 v[86:89], v[162:165], v[214:217], v[86:89]
	v_mfma_f32_16x16x32_bf16 v[82:85], v[170:173], v[214:217], v[82:85]
	v_mfma_f32_16x16x32_bf16 v[78:81], v[162:165], v[222:225], v[78:81]
	v_mfma_f32_16x16x32_bf16 v[74:77], v[170:173], v[222:225], v[74:77]
	v_mfma_f32_16x16x32_bf16 v[118:121], v[166:169], v[202:205], v[118:121]
	v_mfma_f32_16x16x32_bf16 v[114:117], v[174:177], v[202:205], v[114:117]
	v_mfma_f32_16x16x32_bf16 v[110:113], v[166:169], v[210:213], v[110:113]
	v_mfma_f32_16x16x32_bf16 v[106:109], v[174:177], v[210:213], v[106:109]
	v_mfma_f32_16x16x32_bf16 v[86:89], v[166:169], v[218:221], v[86:89]
	v_mfma_f32_16x16x32_bf16 v[82:85], v[174:177], v[218:221], v[82:85]
	v_mfma_f32_16x16x32_bf16 v[78:81], v[166:169], v[226:229], v[78:81]
	v_mfma_f32_16x16x32_bf16 v[74:77], v[174:177], v[226:229], v[74:77]
	s_setprio 0
	s_barrier
; #define PG8_STAGE(bufoff, gbase, voff) do { _Pragma("unroll") for (int _i = 0; _i < 2; ++_i) \
;         __builtin_amdgcn_global_load_lds((const unsigned*)((const char*)(gbase) + (voff)[_i]), (LAS unsigned*)(lds + (bufoff) + ldsw + _i * 8192), 16, 0, 0); } while (0)
; #define PG8_LDA(dst, b, h) do { _Pragma("unroll") for (int m = 0; m < 4; ++m) _Pragma("unroll") for (int k = 0; k < 2; ++k) dst[m][k] = *(const LAS bf16x8*)(lds + PG8_SA(b, h) + aoff + m * 2048 + k * 1024); } while (0)
; #define PG8_MMA(ai, bj, At, Bt_) do { __builtin_amdgcn_s_setprio(1); _Pragma("unroll") for (int m = 0; m < 4; ++m) _Pragma("unroll") for (int n = 0; n < 2; ++n) _Pragma("unroll") for (int k = 0; k < 2; ++k) \
;         acc[ai][bj][m][n] = __builtin_amdgcn_mfma_f32_16x16x32_bf16(Bt_[n][k], At[m][k], acc[ai][bj][m][n], 0, 0, 0); __builtin_amdgcn_s_setprio(0); } while (0)
; #define PG8_WAIT_V(n) asm volatile("s_waitcnt vmcnt(" #n ")" ::: "memory")
; #define PG8_WAIT_L(n) asm volatile("s_waitcnt lgkmcnt(" #n ")" ::: "memory")
; #define PG8_BAR __builtin_amdgcn_s_barrier()
; #define PG8_SCHED __builtin_amdgcn_sched_barrier(0)
; __device__ __forceinline__ void gemm_phase(LAS unsigned char* lds, const bf16_t* A, const bf16_t* Bt, int M, int N, int K, const Epi& E) {
;     ...
;             PG8_LDA(At, 1, 1); PG8_STAGE(PG8_SB(1, 0), b3, voffB); PG8_STAGE(PG8_SB(1, 1), b3 + hstep, voffB); PG8_STAGE(PG8_SA(1, 0), a3, voffA);
;             PG8_WAIT_V(8); PG8_WAIT_L(0); PG8_BAR; PG8_MMA(1, 0, At, B0); PG8_MMA(1, 1, At, B1); PG8_BAR; PG8_SCHED;
;         }
;         if (wr == 0) PG8_BAR;
	s_add_i32 s24, s53, s27
	v_lshl_add_u64 v[184:185], v[184:185], 0, s[60:61]
	s_mov_b32 m0, s24
	ds_read_b128 v[178:181], v182 offset:49152
	ds_read_b128 v[202:205], v182 offset:50176
	ds_read_b128 v[206:209], v182 offset:51200
	ds_read_b128 v[210:213], v182 offset:52224
	ds_read_b128 v[214:217], v182 offset:53248
	ds_read_b128 v[218:221], v182 offset:54272
	ds_read_b128 v[222:225], v182 offset:55296
	ds_read_b128 v[226:229], v182 offset:56320
	global_load_lds_dwordx4 v[184:185], off
	s_add_i32 m0, s24, 0x2000
	s_add_u32 s22, s22, 0x40080
	v_lshl_add_u64 v[184:185], v[230:231], 0, s[60:61]
	s_addc_u32 s23, s23, 0
	s_add_i32 s24, s54, s27
	global_load_lds_dwordx4 v[184:185], off
	v_lshl_add_u64 v[184:185], s[22:23], 0, v[0:1]
	s_mov_b32 m0, s24
	s_nop 0
	global_load_lds_dwordx4 v[184:185], off
	v_lshl_add_u64 v[184:185], s[22:23], 0, v[134:135]
	s_add_i32 m0, s24, 0x2000
	s_nop 0
	global_load_lds_dwordx4 v[184:185], off
	v_lshl_add_u64 v[184:185], v[232:233], 0, s[60:61]
	s_mov_b32 m0, s46
	s_nop 0
	global_load_lds_dwordx4 v[184:185], off
	v_lshl_add_u64 v[184:185], v[240:241], 0, s[60:61]
	s_mov_b32 m0, s47
	s_nop 0
	global_load_lds_dwordx4 v[184:185], off
	s_waitcnt vmcnt(8)
	s_waitcnt lgkmcnt(0)
	s_barrier
	s_setprio 1
	s_waitcnt lgkmcnt(0)
	v_mfma_f32_16x16x32_bf16 v[62:65], v[146:149], v[178:181], v[62:65]
	v_mfma_f32_16x16x32_bf16 v[58:61], v[154:157], v[178:181], v[58:61]
	v_mfma_f32_16x16x32_bf16 v[38:41], v[146:149], v[206:209], v[38:41]
	v_mfma_f32_16x16x32_bf16 v[34:37], v[154:157], v[206:209], v[34:37]
	v_mfma_f32_16x16x32_bf16 v[30:33], v[146:149], v[214:217], v[30:33]
	v_mfma_f32_16x16x32_bf16 v[26:29], v[154:157], v[214:217], v[26:29]
	v_mfma_f32_16x16x32_bf16 v[10:13], v[146:149], v[222:225], v[10:13]
	v_mfma_f32_16x16x32_bf16 v[2:5], v[154:157], v[222:225], v[2:5]
	v_mfma_f32_16x16x32_bf16 v[62:65], v[150:153], v[202:205], v[62:65]
	v_mfma_f32_16x16x32_bf16 v[58:61], v[158:161], v[202:205], v[58:61]
	v_mfma_f32_16x16x32_bf16 v[38:41], v[150:153], v[210:213], v[38:41]
	v_mfma_f32_16x16x32_bf16 v[34:37], v[158:161], v[210:213], v[34:37]
	v_mfma_f32_16x16x32_bf16 v[30:33], v[150:153], v[218:221], v[30:33]
	v_mfma_f32_16x16x32_bf16 v[26:29], v[158:161], v[218:221], v[26:29]
	v_mfma_f32_16x16x32_bf16 v[10:13], v[150:153], v[226:229], v[10:13]
	v_mfma_f32_16x16x32_bf16 v[2:5], v[158:161], v[226:229], v[2:5]
	v_mfma_f32_16x16x32_bf16 v[54:57], v[162:165], v[178:181], v[54:57]
	v_mfma_f32_16x16x32_bf16 v[50:53], v[170:173], v[178:181], v[50:53]
	v_mfma_f32_16x16x32_bf16 v[46:49], v[162:165], v[206:209], v[46:49]
	v_mfma_f32_16x16x32_bf16 v[42:45], v[170:173], v[206:209], v[42:45]
	v_mfma_f32_16x16x32_bf16 v[22:25], v[162:165], v[214:217], v[22:25]
	v_mfma_f32_16x16x32_bf16 v[18:21], v[170:173], v[214:217], v[18:21]
	v_mfma_f32_16x16x32_bf16 v[14:17], v[162:165], v[222:225], v[14:17]
	v_mfma_f32_16x16x32_bf16 v[6:9], v[170:173], v[222:225], v[6:9]
	v_mfma_f32_16x16x32_bf16 v[54:57], v[166:169], v[202:205], v[54:57]
	v_mfma_f32_16x16x32_bf16 v[50:53], v[174:177], v[202:205], v[50:53]
	v_mfma_f32_16x16x32_bf16 v[46:49], v[166:169], v[210:213], v[46:49]
	v_mfma_f32_16x16x32_bf16 v[42:45], v[174:177], v[210:213], v[42:45]
	v_mfma_f32_16x16x32_bf16 v[22:25], v[166:169], v[218:221], v[22:25]
	v_mfma_f32_16x16x32_bf16 v[18:21], v[174:177], v[218:221], v[18:21]
	v_mfma_f32_16x16x32_bf16 v[14:17], v[166:169], v[226:229], v[14:17]
	v_mfma_f32_16x16x32_bf16 v[6:9], v[174:177], v[226:229], v[6:9]
	s_setprio 0
	s_barrier
	s_add_i32 s52, s52, 2
	s_add_u32 s20, s20, 0x100
	s_addc_u32 s21, s21, 0
	s_add_u32 s50, s50, 0x100
	s_addc_u32 s51, s51, 0
	s_cmp_gt_u32 s52, 13
	s_cbranch_scc0 .LBB0_2823
	s_and_b64 vcc, exec, s[2:3]
	s_cbranch_vccz .LBB0_2826
	s_barrier

; #define PG8_STAGE(bufoff, gbase, voff) do { _Pragma("unroll") for (int _i = 0; _i < 2; ++_i) \
;         __builtin_amdgcn_global_load_lds((const unsigned*)((const char*)(gbase) + (voff)[_i]), (LAS unsigned*)(lds + (bufoff) + ldsw + _i * 8192), 16, 0, 0); } while (0)
; #define PG8_LDA(dst, b, h) do { _Pragma("unroll") for (int m = 0; m < 4; ++m) _Pragma("unroll") for (int k = 0; k < 2; ++k) dst[m][k] = *(const LAS bf16x8*)(lds + PG8_SA(b, h) + aoff + m * 2048 + k * 1024); } while (0)
; #define PG8_LDB(dst, b, h) do { _Pragma("unroll") for (int n = 0; n < 2; ++n) _Pragma("unroll") for (int k = 0; k < 2; ++k) dst[n][k] = *(const LAS bf16x8*)(lds + PG8_SB(b, h) + boff + n * 2048 + k * 1024); } while (0)
; #define PG8_MMA(ai, bj, At, Bt_) do { __builtin_amdgcn_s_setprio(1); _Pragma("unroll") for (int m = 0; m < 4; ++m) _Pragma("unroll") for (int n = 0; n < 2; ++n) _Pragma("unroll") for (int k = 0; k < 2; ++k) \
;         acc[ai][bj][m][n] = __builtin_amdgcn_mfma_f32_16x16x32_bf16(Bt_[n][k], At[m][k], acc[ai][bj][m][n], 0, 0, 0); __builtin_amdgcn_s_setprio(0); } while (0)
; #define PG8_WAIT_V(n) asm volatile("s_waitcnt vmcnt(" #n ")" ::: "memory")
; #define PG8_WAIT_L(n) asm volatile("s_waitcnt lgkmcnt(" #n ")" ::: "memory")
; __device__ __forceinline__ void gemm_phase(LAS unsigned char* lds, const bf16_t* A, const bf16_t* Bt, int M, int N, int K, const Epi& E) {
;     ...
;         for (int t = 0; t < nt; t += 2) {
;             const bool last = (t == nt - 2);
;             const char* a1 = cA + (size_t)(t + 1) * kstep;
;             const char* a2 = last ? nA : cA + (size_t)(t + 2) * kstep; const char* b2 = last ? nB : cB + (size_t)(t + 2) * kstep;
;             const char* a3 = a2 + kstep; const char* b3 = b2 + kstep;
;             PG8_LDB(B0, 0, 0); PG8_LDB(B1, 0, 1); PG8_SCHED; PG8_LDA(At, 0, 0); PG8_STAGE(PG8_SA(1, 1), a1 + hstep, voffA);
;             PG8_WAIT_V(8); PG8_WAIT_L(0); PG8_BAR; PG8_MMA(0, 0, At, B0); PG8_MMA(0, 1, At, B1); PG8_BAR; PG8_SCHED;
;             PG8_LDA(At, 0, 1); PG8_STAGE(PG8_SB(0, 0), b2, voffB); PG8_STAGE(PG8_SB(0, 1), b2 + hstep, voffB); PG8_STAGE(PG8_SA(0, 0), a2, voffA);
;             PG8_WAIT_V(8); PG8_WAIT_L(0); PG8_BAR; PG8_MMA(1, 0, At, B0); PG8_MMA(1, 1, At, B1); PG8_BAR; PG8_SCHED;
;             PG8_LDB(B0, 1, 0); PG8_LDB(B1, 1, 1); PG8_SCHED; PG8_LDA(At, 1, 0); PG8_STAGE(PG8_SA(0, 1), a2 + hstep, voffA);
.LBB0_3077:
	s_add_u32 s2, s14, 0x100
	s_addc_u32 s3, s15, 0
	s_add_i32 s41, 0, 0x10000
	s_cmp_eq_u32 s40, 40
	s_cselect_b32 s19, s11, s3
	s_cselect_b32 s18, s10, s2
	s_cselect_b32 s17, s13, s39
	s_cselect_b32 s16, s12, s38
	s_add_i32 s42, 0, 0x14000
	v_add_u32_e32 v118, s41, v239
	v_add_u32_e32 v158, s42, v239
	ds_read_b128 v[102:105], v118
	ds_read_b128 v[110:113], v118 offset:1024
	ds_read_b128 v[114:117], v118 offset:2048
	ds_read_b128 v[118:121], v118 offset:3072
	ds_read_b128 v[146:149], v158
	ds_read_b128 v[150:153], v158 offset:1024
	ds_read_b128 v[154:157], v158 offset:2048
	ds_read_b128 v[158:161], v158 offset:3072
	v_lshl_add_u64 v[220:221], s[14:15], 0, v[208:209]
	s_add_i32 m0, s25, 0xc000
	ds_read_b128 v[162:165], v249
	ds_read_b128 v[166:169], v249 offset:1024
	ds_read_b128 v[170:173], v249 offset:2048
	ds_read_b128 v[174:177], v249 offset:3072
	ds_read_b128 v[178:181], v249 offset:4096
	ds_read_b128 v[182:185], v249 offset:5120
	ds_read_b128 v[212:215], v249 offset:6144
	ds_read_b128 v[216:219], v249 offset:7168
	global_load_lds_dwordx4 v[220:221], off
	v_lshl_add_u64 v[220:221], s[14:15], 0, v[210:211]
	s_add_i32 m0, s25, 0xe000
	s_nop 0
	global_load_lds_dwordx4 v[220:221], off
	s_waitcnt vmcnt(8)
	s_waitcnt lgkmcnt(0)
	s_barrier
	s_setprio 1
	s_waitcnt lgkmcnt(0)
	v_mfma_f32_16x16x32_bf16 v[142:145], v[102:105], v[162:165], v[142:145]
	v_mfma_f32_16x16x32_bf16 v[138:141], v[114:117], v[162:165], v[138:141]
	v_mfma_f32_16x16x32_bf16 v[126:129], v[102:105], v[170:173], v[126:129]
	v_mfma_f32_16x16x32_bf16 v[122:125], v[114:117], v[170:173], v[122:125]
	v_mfma_f32_16x16x32_bf16 v[94:97], v[102:105], v[178:181], v[94:97]
	v_mfma_f32_16x16x32_bf16 v[90:93], v[114:117], v[178:181], v[90:93]
	v_mfma_f32_16x16x32_bf16 v[78:81], v[102:105], v[212:215], v[78:81]
	v_mfma_f32_16x16x32_bf16 v[74:77], v[114:117], v[212:215], v[74:77]
	v_mfma_f32_16x16x32_bf16 v[142:145], v[110:113], v[166:169], v[142:145]
	v_mfma_f32_16x16x32_bf16 v[138:141], v[118:121], v[166:169], v[138:141]
	v_mfma_f32_16x16x32_bf16 v[126:129], v[110:113], v[174:177], v[126:129]
	v_mfma_f32_16x16x32_bf16 v[122:125], v[118:121], v[174:177], v[122:125]
	v_mfma_f32_16x16x32_bf16 v[94:97], v[110:113], v[182:185], v[94:97]
	v_mfma_f32_16x16x32_bf16 v[90:93], v[118:121], v[182:185], v[90:93]
	v_mfma_f32_16x16x32_bf16 v[78:81], v[110:113], v[216:219], v[78:81]
	v_mfma_f32_16x16x32_bf16 v[74:77], v[118:121], v[216:219], v[74:77]
	v_mfma_f32_16x16x32_bf16 v[134:137], v[146:149], v[162:165], v[134:137]
	v_mfma_f32_16x16x32_bf16 v[130:133], v[154:157], v[162:165], v[130:133]
	v_mfma_f32_16x16x32_bf16 v[106:109], v[146:149], v[170:173], v[106:109]
	v_mfma_f32_16x16x32_bf16 v[98:101], v[154:157], v[170:173], v[98:101]
	v_mfma_f32_16x16x32_bf16 v[86:89], v[146:149], v[178:181], v[86:89]
	v_mfma_f32_16x16x32_bf16 v[82:85], v[154:157], v[178:181], v[82:85]
	v_mfma_f32_16x16x32_bf16 v[70:73], v[146:149], v[212:215], v[70:73]
	v_mfma_f32_16x16x32_bf16 v[66:69], v[154:157], v[212:215], v[66:69]
	v_mfma_f32_16x16x32_bf16 v[134:137], v[150:153], v[166:169], v[134:137]
	v_mfma_f32_16x16x32_bf16 v[130:133], v[158:161], v[166:169], v[130:133]
	v_mfma_f32_16x16x32_bf16 v[106:109], v[150:153], v[174:177], v[106:109]
	v_mfma_f32_16x16x32_bf16 v[98:101], v[158:161], v[174:177], v[98:101]
	v_mfma_f32_16x16x32_bf16 v[86:89], v[150:153], v[182:185], v[86:89]
	v_mfma_f32_16x16x32_bf16 v[82:85], v[158:161], v[182:185], v[82:85]
	v_mfma_f32_16x16x32_bf16 v[70:73], v[150:153], v[216:219], v[70:73]
	v_mfma_f32_16x16x32_bf16 v[66:69], v[158:161], v[216:219], v[66:69]
	s_setprio 0
	s_barrier
	s_add_i32 s14, s41, s24
	v_lshl_add_u64 v[220:221], s[16:17], 0, v[0:1]
	s_mov_b32 m0, s14
	ds_read_b128 v[162:165], v249 offset:16384
	ds_read_b128 v[166:169], v249 offset:17408
	ds_read_b128 v[170:173], v249 offset:18432
	ds_read_b128 v[174:177], v249 offset:19456
	ds_read_b128 v[178:181], v249 offset:20480
	ds_read_b128 v[182:185], v249 offset:21504
	ds_read_b128 v[212:215], v249 offset:22528
	ds_read_b128 v[216:219], v249 offset:23552
	global_load_lds_dwordx4 v[220:221], off
	s_add_i32 m0, s14, 0x2000
	s_add_u32 s14, s16, 0xb0000
	v_lshl_add_u64 v[222:223], s[16:17], 0, v[206:207]
	s_addc_u32 s15, s17, 0
	s_add_i32 s41, s42, s24
	global_load_lds_dwordx4 v[222:223], off
	v_lshl_add_u64 v[224:225], s[14:15], 0, v[0:1]
	s_mov_b32 m0, s41
	v_lshl_add_u64 v[226:227], s[18:19], 0, v[204:205]
	global_load_lds_dwordx4 v[224:225], off
	v_lshl_add_u64 v[224:225], s[14:15], 0, v[206:207]
	s_add_i32 m0, s41, 0x2000
	s_nop 0
	global_load_lds_dwordx4 v[224:225], off
	v_lshl_add_u64 v[224:225], s[18:19], 0, v[202:203]
	s_mov_b32 m0, s25
	s_nop 0
	global_load_lds_dwordx4 v[224:225], off
	s_mov_b32 m0, s26
	s_nop 0
	global_load_lds_dwordx4 v[226:227], off
	s_waitcnt vmcnt(8)
	s_waitcnt lgkmcnt(0)
	s_barrier
; #define PG8_STAGE(bufoff, gbase, voff) do { _Pragma("unroll") for (int _i = 0; _i < 2; ++_i) \
;         __builtin_amdgcn_global_load_lds((const unsigned*)((const char*)(gbase) + (voff)[_i]), (LAS unsigned*)(lds + (bufoff) + ldsw + _i * 8192), 16, 0, 0); } while (0)
; #define PG8_LDA(dst, b, h) do { _Pragma("unroll") for (int m = 0; m < 4; ++m) _Pragma("unroll") for (int k = 0; k < 2; ++k) dst[m][k] = *(const LAS bf16x8*)(lds + PG8_SA(b, h) + aoff + m * 2048 + k * 1024); } while (0)
; #define PG8_LDB(dst, b, h) do { _Pragma("unroll") for (int n = 0; n < 2; ++n) _Pragma("unroll") for (int k = 0; k < 2; ++k) dst[n][k] = *(const LAS bf16x8*)(lds + PG8_SB(b, h) + boff + n * 2048 + k * 1024); } while (0)
; #define PG8_MMA(ai, bj, At, Bt_) do { __builtin_amdgcn_s_setprio(1); _Pragma("unroll") for (int m = 0; m < 4; ++m) _Pragma("unroll") for (int n = 0; n < 2; ++n) _Pragma("unroll") for (int k = 0; k < 2; ++k) \
;         acc[ai][bj][m][n] = __builtin_amdgcn_mfma_f32_16x16x32_bf16(Bt_[n][k], At[m][k], acc[ai][bj][m][n], 0, 0, 0); __builtin_amdgcn_s_setprio(0); } while (0)
; #define PG8_WAIT_V(n) asm volatile("s_waitcnt vmcnt(" #n ")" ::: "memory")
; #define PG8_WAIT_L(n) asm volatile("s_waitcnt lgkmcnt(" #n ")" ::: "memory")
; #define PG8_BAR __builtin_amdgcn_s_barrier()
; #define PG8_SCHED __builtin_amdgcn_sched_barrier(0)
; __device__ __forceinline__ void gemm_phase(LAS unsigned char* lds, const bf16_t* A, const bf16_t* Bt, int M, int N, int K, const Epi& E) {
;     ...
;             PG8_WAIT_V(8); PG8_WAIT_L(0); PG8_BAR; PG8_MMA(1, 0, At, B0); PG8_MMA(1, 1, At, B1); PG8_BAR; PG8_SCHED;
;             PG8_LDB(B0, 1, 0); PG8_LDB(B1, 1, 1); PG8_SCHED; PG8_LDA(At, 1, 0); PG8_STAGE(PG8_SA(0, 1), a2 + hstep, voffA);
;             PG8_WAIT_V(8); PG8_WAIT_L(0); PG8_BAR; PG8_MMA(0, 0, At, B0); PG8_MMA(0, 1, At, B1); PG8_BAR; PG8_SCHED;
	s_setprio 1
	s_waitcnt lgkmcnt(0)
	v_mfma_f32_16x16x32_bf16 v[62:65], v[102:105], v[162:165], v[62:65]
	v_mfma_f32_16x16x32_bf16 v[58:61], v[114:117], v[162:165], v[58:61]
	v_mfma_f32_16x16x32_bf16 v[46:49], v[102:105], v[170:173], v[46:49]
	v_mfma_f32_16x16x32_bf16 v[42:45], v[114:117], v[170:173], v[42:45]
	v_mfma_f32_16x16x32_bf16 v[30:33], v[102:105], v[178:181], v[30:33]
	v_mfma_f32_16x16x32_bf16 v[26:29], v[114:117], v[178:181], v[26:29]
	v_mfma_f32_16x16x32_bf16 v[14:17], v[102:105], v[212:215], v[14:17]
	v_mfma_f32_16x16x32_bf16 v[10:13], v[114:117], v[212:215], v[10:13]
	v_mfma_f32_16x16x32_bf16 v[62:65], v[110:113], v[166:169], v[62:65]
	v_mfma_f32_16x16x32_bf16 v[58:61], v[118:121], v[166:169], v[58:61]
	v_mfma_f32_16x16x32_bf16 v[46:49], v[110:113], v[174:177], v[46:49]
	v_mfma_f32_16x16x32_bf16 v[42:45], v[118:121], v[174:177], v[42:45]
	v_mfma_f32_16x16x32_bf16 v[30:33], v[110:113], v[182:185], v[30:33]
	v_mfma_f32_16x16x32_bf16 v[26:29], v[118:121], v[182:185], v[26:29]
	v_mfma_f32_16x16x32_bf16 v[14:17], v[110:113], v[216:219], v[14:17]
	v_mfma_f32_16x16x32_bf16 v[10:13], v[118:121], v[216:219], v[10:13]
	v_mfma_f32_16x16x32_bf16 v[54:57], v[146:149], v[162:165], v[54:57]
	v_mfma_f32_16x16x32_bf16 v[50:53], v[154:157], v[162:165], v[50:53]
	v_mfma_f32_16x16x32_bf16 v[38:41], v[146:149], v[170:173], v[38:41]
	v_mfma_f32_16x16x32_bf16 v[34:37], v[154:157], v[170:173], v[34:37]
	v_mfma_f32_16x16x32_bf16 v[22:25], v[146:149], v[178:181], v[22:25]
	v_mfma_f32_16x16x32_bf16 v[18:21], v[154:157], v[178:181], v[18:21]
	v_mfma_f32_16x16x32_bf16 v[6:9], v[146:149], v[212:215], v[6:9]
	v_mfma_f32_16x16x32_bf16 v[2:5], v[154:157], v[212:215], v[2:5]
	v_mfma_f32_16x16x32_bf16 v[54:57], v[150:153], v[166:169], v[54:57]
	v_mfma_f32_16x16x32_bf16 v[50:53], v[158:161], v[166:169], v[50:53]
	v_mfma_f32_16x16x32_bf16 v[38:41], v[150:153], v[174:177], v[38:41]
	v_mfma_f32_16x16x32_bf16 v[34:37], v[158:161], v[174:177], v[34:37]
	v_mfma_f32_16x16x32_bf16 v[22:25], v[150:153], v[182:185], v[22:25]
	v_mfma_f32_16x16x32_bf16 v[18:21], v[158:161], v[182:185], v[18:21]
	v_mfma_f32_16x16x32_bf16 v[6:9], v[150:153], v[216:219], v[6:9]
	v_mfma_f32_16x16x32_bf16 v[2:5], v[158:161], v[216:219], v[2:5]
	s_setprio 0
	s_barrier
	s_add_i32 s41, 0, 0x18000
	s_add_i32 s42, 0, 0x1c000
	v_add_u32_e32 v118, s41, v239
	v_add_u32_e32 v158, s42, v239
	ds_read_b128 v[102:105], v118
	ds_read_b128 v[110:113], v118 offset:1024
	ds_read_b128 v[114:117], v118 offset:2048
	ds_read_b128 v[118:121], v118 offset:3072
	ds_read_b128 v[146:149], v158
	ds_read_b128 v[150:153], v158 offset:1024
	ds_read_b128 v[154:157], v158 offset:2048
	ds_read_b128 v[158:161], v158 offset:3072
	s_add_u32 s14, s18, 0xb0000
	s_addc_u32 s15, s19, 0
	s_mov_b32 m0, s27
	v_lshl_add_u64 v[228:229], s[14:15], 0, v[202:203]
	ds_read_b128 v[162:165], v249 offset:32768
	ds_read_b128 v[166:169], v249 offset:33792
	ds_read_b128 v[170:173], v249 offset:34816
	ds_read_b128 v[174:177], v249 offset:35840
	ds_read_b128 v[178:181], v249 offset:36864
	ds_read_b128 v[182:185], v249 offset:37888
	ds_read_b128 v[212:215], v249 offset:38912
	ds_read_b128 v[216:219], v249 offset:39936
	global_load_lds_dwordx4 v[228:229], off
	v_lshl_add_u64 v[228:229], s[14:15], 0, v[204:205]
	s_mov_b32 m0, s28
	s_nop 0
	global_load_lds_dwordx4 v[228:229], off
	s_waitcnt vmcnt(8)
	s_waitcnt lgkmcnt(0)
	s_barrier
	s_setprio 1
	s_waitcnt lgkmcnt(0)
	v_mfma_f32_16x16x32_bf16 v[142:145], v[102:105], v[162:165], v[142:145]
	v_mfma_f32_16x16x32_bf16 v[138:141], v[114:117], v[162:165], v[138:141]
	v_mfma_f32_16x16x32_bf16 v[126:129], v[102:105], v[170:173], v[126:129]
	v_mfma_f32_16x16x32_bf16 v[122:125], v[114:117], v[170:173], v[122:125]
	v_mfma_f32_16x16x32_bf16 v[94:97], v[102:105], v[178:181], v[94:97]
	v_mfma_f32_16x16x32_bf16 v[90:93], v[114:117], v[178:181], v[90:93]
	v_mfma_f32_16x16x32_bf16 v[78:81], v[102:105], v[212:215], v[78:81]
	v_mfma_f32_16x16x32_bf16 v[74:77], v[114:117], v[212:215], v[74:77]
	v_mfma_f32_16x16x32_bf16 v[142:145], v[110:113], v[166:169], v[142:145]
	v_mfma_f32_16x16x32_bf16 v[138:141], v[118:121], v[166:169], v[138:141]
	v_mfma_f32_16x16x32_bf16 v[126:129], v[110:113], v[174:177], v[126:129]
	v_mfma_f32_16x16x32_bf16 v[122:125], v[118:121], v[174:177], v[122:125]
	v_mfma_f32_16x16x32_bf16 v[94:97], v[110:113], v[182:185], v[94:97]
	v_mfma_f32_16x16x32_bf16 v[90:93], v[118:121], v[182:185], v[90:93]
	v_mfma_f32_16x16x32_bf16 v[78:81], v[110:113], v[216:219], v[78:81]
	v_mfma_f32_16x16x32_bf16 v[74:77], v[118:121], v[216:219], v[74:77]
	v_mfma_f32_16x16x32_bf16 v[134:137], v[146:149], v[162:165], v[134:137]
	v_mfma_f32_16x16x32_bf16 v[130:133], v[154:157], v[162:165], v[130:133]
	v_mfma_f32_16x16x32_bf16 v[106:109], v[146:149], v[170:173], v[106:109]
	v_mfma_f32_16x16x32_bf16 v[98:101], v[154:157], v[170:173], v[98:101]
	v_mfma_f32_16x16x32_bf16 v[86:89], v[146:149], v[178:181], v[86:89]
	v_mfma_f32_16x16x32_bf16 v[82:85], v[154:157], v[178:181], v[82:85]
	v_mfma_f32_16x16x32_bf16 v[70:73], v[146:149], v[212:215], v[70:73]
	v_mfma_f32_16x16x32_bf16 v[66:69], v[154:157], v[212:215], v[66:69]
	v_mfma_f32_16x16x32_bf16 v[134:137], v[150:153], v[166:169], v[134:137]
	v_mfma_f32_16x16x32_bf16 v[130:133], v[158:161], v[166:169], v[130:133]
	v_mfma_f32_16x16x32_bf16 v[106:109], v[150:153], v[174:177], v[106:109]
	v_mfma_f32_16x16x32_bf16 v[98:101], v[158:161], v[174:177], v[98:101]
	v_mfma_f32_16x16x32_bf16 v[86:89], v[150:153], v[182:185], v[86:89]
	v_mfma_f32_16x16x32_bf16 v[82:85], v[158:161], v[182:185], v[82:85]
	v_mfma_f32_16x16x32_bf16 v[70:73], v[150:153], v[216:219], v[70:73]
	v_mfma_f32_16x16x32_bf16 v[66:69], v[158:161], v[216:219], v[66:69]
	s_setprio 0
	s_barrier
; #define PG8_STAGE(bufoff, gbase, voff) do { _Pragma("unroll") for (int _i = 0; _i < 2; ++_i) \
;         __builtin_amdgcn_global_load_lds((const unsigned*)((const char*)(gbase) + (voff)[_i]), (LAS unsigned*)(lds + (bufoff) + ldsw + _i * 8192), 16, 0, 0); } while (0)
; #define PG8_LDA(dst, b, h) do { _Pragma("unroll") for (int m = 0; m < 4; ++m) _Pragma("unroll") for (int k = 0; k < 2; ++k) dst[m][k] = *(const LAS bf16x8*)(lds + PG8_SA(b, h) + aoff + m * 2048 + k * 1024); } while (0)
; #define PG8_MMA(ai, bj, At, Bt_) do { __builtin_amdgcn_s_setprio(1); _Pragma("unroll") for (int m = 0; m < 4; ++m) _Pragma("unroll") for (int n = 0; n < 2; ++n) _Pragma("unroll") for (int k = 0; k < 2; ++k) \
;         acc[ai][bj][m][n] = __builtin_amdgcn_mfma_f32_16x16x32_bf16(Bt_[n][k], At[m][k], acc[ai][bj][m][n], 0, 0, 0); __builtin_amdgcn_s_setprio(0); } while (0)
; #define PG8_WAIT_V(n) asm volatile("s_waitcnt vmcnt(" #n ")" ::: "memory")
; #define PG8_WAIT_L(n) asm volatile("s_waitcnt lgkmcnt(" #n ")" ::: "memory")
; #define PG8_BAR __builtin_amdgcn_s_barrier()
; #define PG8_SCHED __builtin_amdgcn_sched_barrier(0)
; __device__ __forceinline__ void gemm_phase(LAS unsigned char* lds, const bf16_t* A, const bf16_t* Bt, int M, int N, int K, const Epi& E) {
;     ...
;             PG8_LDA(At, 1, 1); PG8_STAGE(PG8_SB(1, 0), b3, voffB); PG8_STAGE(PG8_SB(1, 1), b3 + hstep, voffB); PG8_STAGE(PG8_SA(1, 0), a3, voffA);
;             PG8_WAIT_V(8); PG8_WAIT_L(0); PG8_BAR; PG8_MMA(1, 0, At, B0); PG8_MMA(1, 1, At, B1); PG8_BAR; PG8_SCHED;
;         }
;         if (wr == 0) PG8_BAR;
	s_add_i32 s14, s41, s24
	v_lshl_add_u64 v[220:221], v[220:221], 0, s[44:45]
	s_mov_b32 m0, s14
	ds_read_b128 v[162:165], v249 offset:49152
	ds_read_b128 v[166:169], v249 offset:50176
	ds_read_b128 v[170:173], v249 offset:51200
	ds_read_b128 v[174:177], v249 offset:52224
	ds_read_b128 v[178:181], v249 offset:53248
	ds_read_b128 v[182:185], v249 offset:54272
	ds_read_b128 v[212:215], v249 offset:55296
	ds_read_b128 v[216:219], v249 offset:56320
	global_load_lds_dwordx4 v[220:221], off
	s_add_i32 m0, s14, 0x2000
	s_add_u32 s14, s16, 0xb0080
	v_lshl_add_u64 v[220:221], v[222:223], 0, s[44:45]
	s_addc_u32 s15, s17, 0
	s_add_i32 s16, s42, s24
	global_load_lds_dwordx4 v[220:221], off
	v_lshl_add_u64 v[220:221], s[14:15], 0, v[0:1]
	s_mov_b32 m0, s16
	s_nop 0
	global_load_lds_dwordx4 v[220:221], off
	v_lshl_add_u64 v[220:221], s[14:15], 0, v[206:207]
	s_add_i32 m0, s16, 0x2000
	s_nop 0
	global_load_lds_dwordx4 v[220:221], off
	v_lshl_add_u64 v[220:221], v[224:225], 0, s[44:45]
	s_mov_b32 m0, s30
	s_nop 0
	global_load_lds_dwordx4 v[220:221], off
	v_lshl_add_u64 v[220:221], v[226:227], 0, s[44:45]
	s_mov_b32 m0, s31
	s_nop 0
	global_load_lds_dwordx4 v[220:221], off
	s_waitcnt vmcnt(8)
	s_waitcnt lgkmcnt(0)
	s_barrier
	s_setprio 1
	s_waitcnt lgkmcnt(0)
	v_mfma_f32_16x16x32_bf16 v[62:65], v[102:105], v[162:165], v[62:65]
	v_mfma_f32_16x16x32_bf16 v[58:61], v[114:117], v[162:165], v[58:61]
	v_mfma_f32_16x16x32_bf16 v[46:49], v[102:105], v[170:173], v[46:49]
	v_mfma_f32_16x16x32_bf16 v[42:45], v[114:117], v[170:173], v[42:45]
	v_mfma_f32_16x16x32_bf16 v[30:33], v[102:105], v[178:181], v[30:33]
	v_mfma_f32_16x16x32_bf16 v[26:29], v[114:117], v[178:181], v[26:29]
	v_mfma_f32_16x16x32_bf16 v[14:17], v[102:105], v[212:215], v[14:17]
	v_mfma_f32_16x16x32_bf16 v[10:13], v[114:117], v[212:215], v[10:13]
	v_mfma_f32_16x16x32_bf16 v[62:65], v[110:113], v[166:169], v[62:65]
	v_mfma_f32_16x16x32_bf16 v[58:61], v[118:121], v[166:169], v[58:61]
	v_mfma_f32_16x16x32_bf16 v[46:49], v[110:113], v[174:177], v[46:49]
	v_mfma_f32_16x16x32_bf16 v[42:45], v[118:121], v[174:177], v[42:45]
	v_mfma_f32_16x16x32_bf16 v[30:33], v[110:113], v[182:185], v[30:33]
	v_mfma_f32_16x16x32_bf16 v[26:29], v[118:121], v[182:185], v[26:29]
	v_mfma_f32_16x16x32_bf16 v[14:17], v[110:113], v[216:219], v[14:17]
	v_mfma_f32_16x16x32_bf16 v[10:13], v[118:121], v[216:219], v[10:13]
	v_mfma_f32_16x16x32_bf16 v[54:57], v[146:149], v[162:165], v[54:57]
	v_mfma_f32_16x16x32_bf16 v[50:53], v[154:157], v[162:165], v[50:53]
	v_mfma_f32_16x16x32_bf16 v[38:41], v[146:149], v[170:173], v[38:41]
	v_mfma_f32_16x16x32_bf16 v[34:37], v[154:157], v[170:173], v[34:37]
	v_mfma_f32_16x16x32_bf16 v[22:25], v[146:149], v[178:181], v[22:25]
	v_mfma_f32_16x16x32_bf16 v[18:21], v[154:157], v[178:181], v[18:21]
	v_mfma_f32_16x16x32_bf16 v[6:9], v[146:149], v[212:215], v[6:9]
	v_mfma_f32_16x16x32_bf16 v[2:5], v[154:157], v[212:215], v[2:5]
	v_mfma_f32_16x16x32_bf16 v[54:57], v[150:153], v[166:169], v[54:57]
	v_mfma_f32_16x16x32_bf16 v[50:53], v[158:161], v[166:169], v[50:53]
	v_mfma_f32_16x16x32_bf16 v[38:41], v[150:153], v[174:177], v[38:41]
	v_mfma_f32_16x16x32_bf16 v[34:37], v[158:161], v[174:177], v[34:37]
	v_mfma_f32_16x16x32_bf16 v[22:25], v[150:153], v[182:185], v[22:25]
	v_mfma_f32_16x16x32_bf16 v[18:21], v[158:161], v[182:185], v[18:21]
	v_mfma_f32_16x16x32_bf16 v[6:9], v[150:153], v[216:219], v[6:9]
	v_mfma_f32_16x16x32_bf16 v[2:5], v[158:161], v[216:219], v[2:5]
	s_setprio 0
	s_barrier
	s_add_i32 s40, s40, 2
	s_add_u32 s38, s38, 0x100
	s_addc_u32 s39, s39, 0
	s_cmp_gt_u32 s40, 41
	s_mov_b64 s[14:15], s[2:3]
	s_cbranch_scc0 .LBB0_3077
	s_and_b64 vcc, exec, s[8:9]
	s_cbranch_vccz .LBB0_3080
	s_barrier
